# gated-merge loop software-pipelined (2 register sets, counted vmcnt) on top of wait fixes
# baseline (speedup 1.0000x reference)
.LBB0_581:
	v_add_co_u32_e32 v48, vcc, 0xf8000000, v26
	v_lshl_add_u64 v[50:51], v[26:27], 0, s[12:13]
	v_lshl_add_u64 v[54:55], v[26:27], 0, s[14:15]
	v_addc_co_u32_e32 v49, vcc, -1, v27, vcc
	global_load_dwordx4 v[20:23], v[26:27], off
	global_load_dwordx4 v[16:19], v[26:27], off offset:-16
	v_lshl_add_u64 v[52:53], v[26:27], 0, s[16:17]
	v_lshl_add_u64 v[56:57], v[26:27], 0, s[18:19]
	global_load_dwordx4 v[60:63], v[54:55], off offset:16
	global_load_dwordx4 v[64:67], v[50:51], off offset:16
	global_load_dwordx4 v[68:71], v[56:57], off offset:16
	global_load_dwordx4 v[72:75], v[52:53], off offset:16
	v_add_co_u32_e32 v50, vcc, 0xfc000000, v26
	v_lshl_add_u64 v[46:47], v[26:27], 0, s[20:21]
	s_nop 0
	v_addc_co_u32_e32 v51, vcc, -1, v27, vcc
	v_add_co_u32_e32 v52, vcc, 0xdfc00000, v26
	global_load_dwordx4 v[92:95], v[48:49], off offset:-16
	global_load_dwordx4 v[96:99], v[46:47], off offset:16
	v_addc_co_u32_e32 v53, vcc, -1, v27, vcc
	v_add_co_u32_e32 v48, vcc, s3, v26
	global_load_dwordx4 v[100:103], v[50:51], off offset:-16
	global_load_dwordx4 v[104:107], v[52:53], off offset:-16
	v_addc_co_u32_e32 v49, vcc, -1, v27, vcc
	v_add_co_u32_e32 v50, vcc, s23, v26
	v_add_u32_e32 v86, s8, v86
	s_nop 0
	v_addc_co_u32_e32 v51, vcc, -1, v27, vcc
	global_load_dwordx4 v[108:111], v[48:49], off offset:-16
	global_load_dwordx4 v[112:115], v[50:51], off offset:-16
	v_add_co_u32_e32 v252, vcc, 0xc7c00000, v26
	v_cmp_lt_i32_e64 s[0:1], s28, v86
	s_nop 0
	v_addc_co_u32_e32 v253, vcc, -1, v27, vcc
	s_or_b64 s[10:11], s[0:1], s[10:11]
	v_lshl_add_u64 v[26:27], v[26:27], 0, s[24:25]
	s_cmp_lg_u64 s[10:11], 0
	s_cbranch_scc1 .Lmp0_finalA
	v_add_co_u32_e32 v48, vcc, 0xf8000000, v26
	v_lshl_add_u64 v[50:51], v[26:27], 0, s[12:13]
	v_lshl_add_u64 v[54:55], v[26:27], 0, s[14:15]
	v_addc_co_u32_e32 v49, vcc, -1, v27, vcc
	global_load_dwordx4 v[184:187], v[26:27], off
	global_load_dwordx4 v[180:183], v[26:27], off offset:-16
	v_lshl_add_u64 v[52:53], v[26:27], 0, s[16:17]
	v_lshl_add_u64 v[56:57], v[26:27], 0, s[18:19]
	global_load_dwordx4 v[188:191], v[54:55], off offset:16
	global_load_dwordx4 v[192:195], v[50:51], off offset:16
	global_load_dwordx4 v[196:199], v[56:57], off offset:16
	global_load_dwordx4 v[220:223], v[52:53], off offset:16
	v_add_co_u32_e32 v50, vcc, 0xfc000000, v26
	v_lshl_add_u64 v[46:47], v[26:27], 0, s[20:21]
	s_nop 0
	v_addc_co_u32_e32 v51, vcc, -1, v27, vcc
	v_add_co_u32_e32 v52, vcc, 0xdfc00000, v26
	global_load_dwordx4 v[224:227], v[48:49], off offset:-16
	global_load_dwordx4 v[228:231], v[46:47], off offset:16
	v_addc_co_u32_e32 v53, vcc, -1, v27, vcc
	v_add_co_u32_e32 v48, vcc, s3, v26
	global_load_dwordx4 v[232:235], v[50:51], off offset:-16
	global_load_dwordx4 v[240:243], v[52:53], off offset:-16
	v_addc_co_u32_e32 v49, vcc, -1, v27, vcc
	v_add_co_u32_e32 v50, vcc, s23, v26
	v_add_u32_e32 v86, s8, v86
	s_nop 0
	v_addc_co_u32_e32 v51, vcc, -1, v27, vcc
	global_load_dwordx4 v[244:247], v[48:49], off offset:-16
	global_load_dwordx4 v[248:251], v[50:51], off offset:-16
	v_add_co_u32_e32 v254, vcc, 0xc7c00000, v26
	v_cmp_lt_i32_e64 s[0:1], s28, v86
	s_nop 0
	v_addc_co_u32_e32 v255, vcc, -1, v27, vcc
	s_or_b64 s[10:11], s[0:1], s[10:11]
	v_lshl_add_u64 v[26:27], v[26:27], 0, s[24:25]
	s_waitcnt vmcnt(23)
	v_lshlrev_b32_e32 v50, 16, v22
	s_waitcnt vmcnt(22)
	v_lshlrev_b32_e32 v58, 16, v16
	v_and_b32_e32 v59, 0xffff0000, v16
	s_waitcnt vmcnt(21)
	v_lshlrev_b32_e32 v83, 16, v63
	s_waitcnt vmcnt(20)
	v_lshlrev_b32_e32 v117, 16, v67
	v_and_b32_e32 v82, 0xffff0000, v63
	v_and_b32_e32 v116, 0xffff0000, v67
	s_waitcnt vmcnt(19)
	v_and_b32_e32 v63, 0xffff0000, v69
	s_waitcnt vmcnt(18)
	v_lshlrev_b32_e32 v16, 16, v75
	v_lshlrev_b32_e32 v85, 16, v71
	v_lshlrev_b32_e32 v118, 16, v66
	v_and_b32_e32 v119, 0xffff0000, v66
	v_lshlrev_b32_e32 v66, 16, v62
	v_and_b32_e32 v67, 0xffff0000, v62
	v_lshlrev_b32_e32 v76, 16, v73
	v_lshlrev_b32_e32 v128, 16, v64
	v_and_b32_e32 v129, 0xffff0000, v64
	v_lshlrev_b32_e32 v130, 16, v60
	v_and_b32_e32 v131, 0xffff0000, v60
	v_lshlrev_b32_e32 v78, 16, v72
	v_and_b32_e32 v79, 0xffff0000, v72
	v_mul_f32_e32 v137, 0xbfb8aa3b, v63
	s_waitcnt vmcnt(16)
	v_lshlrev_b32_e32 v142, 16, v99
	v_mul_f32_e32 v143, 0xbfb8aa3b, v16
	v_mul_f32_e32 v85, 0xbfb8aa3b, v85
	v_and_b32_e32 v144, 0xffff0000, v99
	v_pk_add_f32 v[62:63], v[118:119], v[66:67]
	v_mul_f32_e32 v145, 0xbfb8aa3b, v76
	v_pk_add_f32 v[66:67], v[128:129], v[130:131]
	v_mul_f32_e32 v130, 0xbfb8aa3b, v78
	v_mul_f32_e32 v131, 0xbfb8aa3b, v79
	v_and_b32_e32 v51, 0xffff0000, v22
	v_and_b32_e32 v81, 0xffff0000, v70
	v_and_b32_e32 v22, 0xffff0000, v75
	v_lshlrev_b32_e32 v124, 16, v61
	v_and_b32_e32 v125, 0xffff0000, v61
	v_and_b32_e32 v77, 0xffff0000, v73
	v_pk_add_f32 v[60:61], v[116:117], v[82:83]
	v_lshlrev_b32_e32 v73, 16, v96
	v_and_b32_e32 v75, 0xffff0000, v96
	v_lshlrev_b32_e32 v133, 16, v97
	v_and_b32_e32 v135, 0xffff0000, v97
	v_lshlrev_b32_e32 v139, 16, v98
	v_and_b32_e32 v141, 0xffff0000, v98
	v_lshlrev_b32_e32 v96, 16, v95
	v_and_b32_e32 v97, 0xffff0000, v95
	v_lshlrev_b32_e32 v98, 16, v94
	v_and_b32_e32 v99, 0xffff0000, v94
	v_lshlrev_b32_e32 v116, 16, v92
	v_and_b32_e32 v117, 0xffff0000, v92
	v_exp_f32_e32 v147, v137
	v_exp_f32_e32 v150, v143
	v_exp_f32_e32 v151, v85
	v_mul_f32_e32 v85, 0xbfb8aa3b, v142
	v_mul_f32_e32 v137, 0xbfb8aa3b, v144
	v_exp_f32_e32 v153, v145
	v_exp_f32_e32 v154, v130
	v_exp_f32_e32 v155, v131
	s_waitcnt vmcnt(15)
	v_lshlrev_b32_e32 v130, 16, v103
	v_and_b32_e32 v131, 0xffff0000, v103
	v_lshlrev_b32_e32 v142, 16, v102
	v_and_b32_e32 v143, 0xffff0000, v102
	v_lshlrev_b32_e32 v144, 16, v100
	v_and_b32_e32 v145, 0xffff0000, v100
	v_lshlrev_b32_e32 v52, 16, v21
	v_and_b32_e32 v53, 0xffff0000, v21
	v_mul_f32_e32 v81, 0xbfb8aa3b, v81
	v_lshlrev_b32_e32 v94, 16, v93
	v_and_b32_e32 v95, 0xffff0000, v93
	v_lshlrev_b32_e32 v102, 16, v101
	v_and_b32_e32 v103, 0xffff0000, v101
	v_pk_add_f32 v[96:97], v[96:97], v[130:131]
	s_waitcnt vmcnt(14)
	v_lshlrev_b32_e32 v130, 16, v107
	v_and_b32_e32 v131, 0xffff0000, v107
	v_pk_add_f32 v[98:99], v[98:99], v[142:143]
	v_lshlrev_b32_e32 v142, 16, v106
	v_and_b32_e32 v143, 0xffff0000, v106
	v_pk_add_f32 v[106:107], v[116:117], v[144:145]
	v_pk_mul_f32 v[126:127], v[52:53], v[52:53]
	v_mov_b32_e32 v140, v59
	v_exp_f32_e32 v149, v81
	v_mul_f32_e32 v81, 0xbfb8aa3b, v141
	v_pk_add_f32 v[94:95], v[94:95], v[102:103]
	v_lshlrev_b32_e32 v102, 16, v105
	v_and_b32_e32 v103, 0xffff0000, v105
	v_lshlrev_b32_e32 v116, 16, v104
	v_and_b32_e32 v117, 0xffff0000, v104
	s_waitcnt vmcnt(13)
	v_lshlrev_b32_e32 v104, 16, v108
	v_and_b32_e32 v105, 0xffff0000, v108
	v_mov_b32_e32 v141, v107
	v_lshlrev_b32_e32 v56, 16, v18
	v_and_b32_e32 v57, 0xffff0000, v18
	v_lshlrev_b32_e32 v18, 16, v17
	v_mov_b32_e32 v138, v58
	v_mov_b32_e32 v92, v126
	v_mul_f32_e32 v126, 0xbfb8aa3b, v133
	v_mul_f32_e32 v133, 0xbfb8aa3b, v135
	v_mul_f32_e32 v135, 0xbfb8aa3b, v139
	v_mov_b32_e32 v139, v106
	v_mul_f32_e32 v168, 0xbfb8aa3b, v104
	v_mul_f32_e32 v169, 0xbfb8aa3b, v105
	v_pk_mul_f32 v[104:105], v[140:141], v[140:141]
	v_lshlrev_b32_e32 v54, 16, v20
	v_and_b32_e32 v55, 0xffff0000, v20
	v_lshlrev_b32_e32 v20, 16, v19
	v_and_b32_e32 v21, 0xffff0000, v19
	v_and_b32_e32 v19, 0xffff0000, v17
	v_mov_b32_e32 v134, v18
	v_exp_f32_e32 v159, v135
	v_mov_b32_e32 v135, v94
	v_pk_fma_f32 v[104:105], v[138:139], v[138:139], v[104:105]
	v_mov_b32_e32 v136, v19
	v_exp_f32_e32 v162, v137
	v_mov_b32_e32 v137, v95
	v_pk_fma_f32 v[104:105], v[134:135], v[134:135], v[104:105]
	v_mov_b32_e32 v132, v56
	v_exp_f32_e32 v158, v133
	v_mov_b32_e32 v133, v98
	v_pk_fma_f32 v[104:105], v[136:137], v[136:137], v[104:105]
	v_mov_b32_e32 v84, v57
	v_exp_f32_e32 v161, v85
	v_mov_b32_e32 v85, v99
	v_pk_fma_f32 v[104:105], v[132:133], v[132:133], v[104:105]
	v_mov_b32_e32 v80, v20
	v_mul_f32_e32 v75, 0xbfb8aa3b, v75
	v_exp_f32_e32 v160, v81
	v_mov_b32_e32 v81, v96
	v_pk_fma_f32 v[84:85], v[84:85], v[84:85], v[104:105]
	v_lshlrev_b32_e32 v44, 16, v69
	v_lshlrev_b32_e32 v69, 16, v70
	v_and_b32_e32 v91, 0xffff0000, v71
	v_pk_mul_f32 v[120:121], v[50:51], v[50:51]
	v_lshlrev_b32_e32 v70, 16, v74
	v_and_b32_e32 v71, 0xffff0000, v74
	v_lshlrev_b32_e32 v122, 16, v65
	v_and_b32_e32 v123, 0xffff0000, v65
	v_mov_b32_e32 v74, v21
	v_exp_f32_e32 v157, v75
	v_mov_b32_e32 v75, v97
	v_pk_fma_f32 v[80:81], v[80:81], v[80:81], v[84:85]
	v_mov_b32_e32 v72, v54
	v_mul_f32_e32 v69, 0xbfb8aa3b, v69
	v_pk_add_f32 v[64:65], v[122:123], v[124:125]
	v_mov_b32_e32 v118, v120
	v_mul_f32_e32 v120, 0xbfb8aa3b, v73
	v_mov_b32_e32 v73, v66
	v_pk_fma_f32 v[74:75], v[74:75], v[74:75], v[80:81]
	v_lshlrev_b32_e32 v17, 16, v68
	v_and_b32_e32 v28, 0xffff0000, v68
	v_mov_b32_e32 v68, v55
	v_mul_f32_e32 v93, 0xbfb8aa3b, v22
	v_exp_f32_e32 v148, v69
	v_pk_mul_f32 v[128:129], v[64:65], v[64:65]
	v_mov_b32_e32 v69, v67
	v_pk_fma_f32 v[72:73], v[72:73], v[72:73], v[74:75]
	v_exp_f32_e32 v156, v93
	v_mov_b32_e32 v93, v128
	v_pk_fma_f32 v[68:69], v[68:69], v[68:69], v[72:73]
	v_lshlrev_b32_e32 v49, 16, v23
	v_and_b32_e32 v23, 0xffff0000, v23
	v_mul_f32_e32 v119, 0xbfb8aa3b, v71
	v_pk_mul_f32 v[124:125], v[62:63], v[62:63]
	v_mov_b32_e32 v128, v127
	v_pk_add_f32 v[68:69], v[92:93], v[68:69]
	v_mov_b32_e32 v48, v23
	v_exp_f32_e32 v152, v119
	v_mov_b32_e32 v119, v124
	v_pk_add_f32 v[68:69], v[128:129], v[68:69]
	v_pk_mul_f32 v[82:83], v[48:49], v[48:49]
	v_pk_mul_f32 v[122:123], v[60:61], v[60:61]
	v_mov_b32_e32 v124, v121
	v_pk_add_f32 v[68:69], v[118:119], v[68:69]
	v_mov_b32_e32 v100, v83
	v_mov_b32_e32 v101, v123
	v_pk_add_f32 v[68:69], v[124:125], v[68:69]
	v_mov_b32_e32 v83, v122
	v_pk_add_f32 v[68:69], v[100:101], v[68:69]
	v_mul_f32_e32 v17, 0xbfb8aa3b, v17
	v_pk_add_f32 v[68:69], v[82:83], v[68:69]
	ds_bpermute_b32 v73, v87, v69
	ds_bpermute_b32 v72, v87, v68
	v_mul_f32_e32 v44, 0xbfb8aa3b, v44
	v_mul_f32_e32 v48, 0xbfb8aa3b, v70
	v_exp_f32_e32 v17, v17
	v_exp_f32_e32 v44, v44
	s_waitcnt lgkmcnt(0)
	v_pk_add_f32 v[68:69], v[68:69], v[72:73]
	ds_bpermute_b32 v73, v88, v69
	ds_bpermute_b32 v72, v88, v68
	v_exp_f32_e32 v48, v48
	v_exp_f32_e32 v120, v120
	v_exp_f32_e32 v126, v126
	v_mul_f32_e32 v123, 0xbfb8aa3b, v130
	s_waitcnt lgkmcnt(0)
	v_pk_add_f32 v[68:69], v[68:69], v[72:73]
	ds_bpermute_b32 v73, v89, v69
	ds_bpermute_b32 v72, v89, v68
	v_mul_f32_e32 v127, 0xbfb8aa3b, v131
	s_waitcnt vmcnt(12)
	v_lshlrev_b32_e32 v167, 16, v112
	v_and_b32_e32 v112, 0xffff0000, v112
	v_lshlrev_b32_e32 v108, 16, v109
	s_waitcnt lgkmcnt(0)
	v_pk_add_f32 v[68:69], v[68:69], v[72:73]
	ds_bpermute_b32 v73, v90, v69
	ds_bpermute_b32 v72, v90, v68
	v_and_b32_e32 v109, 0xffff0000, v109
	v_lshlrev_b32_e32 v121, 16, v110
	v_and_b32_e32 v110, 0xffff0000, v110
	v_exp_f32_e32 v173, v123
	v_exp_f32_e32 v174, v127
	v_mul_f32_e32 v123, 0xbfb8aa3b, v167
	v_mul_f32_e32 v112, 0xbfb8aa3b, v112
	v_lshlrev_b32_e32 v122, 16, v111
	v_lshlrev_b32_e32 v170, 16, v113
	v_mul_f32_e32 v108, 0xbfb8aa3b, v108
	v_and_b32_e32 v113, 0xffff0000, v113
	v_mul_f32_e32 v109, 0xbfb8aa3b, v109
	v_lshlrev_b32_e32 v171, 16, v114
	v_and_b32_e32 v114, 0xffff0000, v114
	v_mul_f32_e32 v110, 0xbfb8aa3b, v110
	v_add_f32_e32 v127, 1.0, v150
	v_add_f32_e32 v140, 1.0, v151
	v_exp_f32_e32 v150, v123
	v_exp_f32_e32 v151, v112
	v_mul_f32_e32 v122, 0xbfb8aa3b, v122
	v_exp_f32_e32 v167, v169
	v_exp_f32_e32 v169, v108
	v_mul_f32_e32 v108, 0xbfb8aa3b, v170
	v_exp_f32_e32 v170, v109
	v_mul_f32_e32 v109, 0xbfb8aa3b, v113
	v_mul_f32_e32 v113, 0xbfb8aa3b, v171
	v_exp_f32_e32 v171, v110
	v_mul_f32_e32 v110, 0xbfb8aa3b, v114
	v_add_f32_e32 v17, 1.0, v17
	v_add_f32_e32 v44, 1.0, v44
	v_mul_f32_e32 v146, 0xbfb8aa3b, v77
	v_exp_f32_e32 v176, v122
	v_add_f32_e32 v122, 1.0, v149
	v_add_f32_e32 v48, 1.0, v48
	v_add_f32_e32 v141, 1.0, v152
	v_add_f32_e32 v149, 1.0, v155
	v_add_f32_e32 v138, 1.0, v156
	v_exp_f32_e32 v152, v108
	v_exp_f32_e32 v155, v110
	v_rcp_f32_e32 v108, v17
	v_add_f32_e32 v17, 1.0, v120
	v_rcp_f32_e32 v110, v44
	v_add_f32_e32 v44, 1.0, v126
	v_mul_f32_e32 v28, 0xbfb8aa3b, v28
	v_mul_f32_e32 v91, 0xbfb8aa3b, v91
	v_exp_f32_e32 v146, v146
	v_rcp_f32_e32 v120, v48
	v_rcp_f32_e32 v48, v138
	v_rcp_f32_e32 v134, v17
	v_rcp_f32_e32 v138, v44
	v_add_f32_e32 v17, 1.0, v173
	v_add_f32_e32 v44, 1.0, v174
	s_waitcnt lgkmcnt(0)
	v_pk_add_f32 v[68:69], v[68:69], v[72:73]
	v_exp_f32_e32 v28, v28
	v_exp_f32_e32 v91, v91
	v_rcp_f32_e32 v132, v17
	v_rcp_f32_e32 v133, v44
	v_add_f32_e32 v17, 1.0, v150
	v_add_f32_e32 v44, 1.0, v151
	v_pk_fma_f32 v[68:69], v[68:69], s[22:23], v[24:25] op_sel_hi:[1,0,1]
	v_and_b32_e32 v111, 0xffff0000, v111
	v_mul_f32_e32 v144, 0xbfb8aa3b, v142
	v_mul_f32_e32 v145, 0xbfb8aa3b, v143
	v_mul_f32_e32 v163, 0xbfb8aa3b, v102
	v_mul_f32_e32 v164, 0xbfb8aa3b, v103
	v_mul_f32_e32 v165, 0xbfb8aa3b, v116
	v_mul_f32_e32 v166, 0xbfb8aa3b, v117
	v_rcp_f32_e32 v84, v17
	v_rcp_f32_e32 v85, v44
	v_mul_f32_e32 v17, 0x4b800000, v69
	v_mul_f32_e32 v44, 0x4b800000, v68
	v_cmp_gt_f32_e32 vcc, s27, v68
	v_cmp_gt_f32_e64 s[0:1], s27, v69
	v_mul_f32_e32 v121, 0xbfb8aa3b, v121
	v_lshlrev_b32_e32 v172, 16, v115
	v_and_b32_e32 v115, 0xffff0000, v115
	v_mul_f32_e32 v111, 0xbfb8aa3b, v111
	v_exp_f32_e32 v144, v144
	v_exp_f32_e32 v145, v145
	v_exp_f32_e32 v163, v163
	v_exp_f32_e32 v164, v164
	v_exp_f32_e32 v165, v165
	v_exp_f32_e32 v166, v166
	v_exp_f32_e32 v168, v168
	v_cndmask_b32_e64 v17, v69, v17, s[0:1]
	v_cndmask_b32_e32 v44, v68, v44, vcc
	v_exp_f32_e32 v175, v121
	v_mul_f32_e32 v114, 0xbfb8aa3b, v172
	v_exp_f32_e32 v172, v111
	v_mul_f32_e32 v111, 0xbfb8aa3b, v115
	v_add_f32_e32 v115, 1.0, v147
	v_add_f32_e32 v121, 1.0, v148
	v_add_f32_e32 v147, 1.0, v153
	v_add_f32_e32 v146, 1.0, v146
	v_add_f32_e32 v148, 1.0, v154
	v_exp_f32_e32 v153, v109
	v_exp_f32_e32 v154, v113
	v_rsq_f32_e32 v17, v17
	v_rsq_f32_e32 v68, v44
	v_add_f32_e32 v28, 1.0, v28
	v_add_f32_e32 v91, 1.0, v91
	v_exp_f32_e32 v156, v114
	v_exp_f32_e32 v177, v111
	v_rcp_f32_e32 v112, v121
	v_rcp_f32_e32 v113, v122
	v_rcp_f32_e32 v121, v141
	v_rcp_f32_e32 v122, v147
	v_rcp_f32_e32 v123, v146
	v_rcp_f32_e32 v109, v28
	v_add_f32_e32 v139, 1.0, v157
	v_rcp_f32_e32 v111, v115
	v_add_f32_e32 v115, 1.0, v158
	v_add_f32_e32 v158, 1.0, v160
	v_rcp_f32_e32 v28, v127
	v_rcp_f32_e32 v114, v91
	v_add_f32_e32 v91, 1.0, v162
	v_rcp_f32_e32 v126, v148
	v_rcp_f32_e32 v127, v149
	v_add_f32_e32 v157, 1.0, v159
	v_add_f32_e32 v160, 1.0, v161
	v_rcp_f32_e32 v135, v139
	v_rcp_f32_e32 v139, v115
	v_rcp_f32_e32 v141, v158
	v_rcp_f32_e32 v115, v91
	v_add_f32_e32 v91, 1.0, v144
	v_add_f32_e32 v137, 1.0, v145
	v_add_f32_e32 v144, 1.0, v163
	v_add_f32_e32 v145, 1.0, v164
	v_add_f32_e32 v146, 1.0, v165
	v_add_f32_e32 v147, 1.0, v166
	v_add_f32_e32 v148, 1.0, v168
	v_add_f32_e32 v158, 1.0, v169
	v_rcp_f32_e32 v159, v140
	v_rcp_f32_e32 v140, v157
	v_rcp_f32_e32 v157, v160
	v_add_f32_e32 v149, 1.0, v167
	v_add_f32_e32 v160, 1.0, v170
	v_rcp_f32_e32 v136, v91
	v_rcp_f32_e32 v137, v137
	v_rcp_f32_e32 v144, v144
	v_rcp_f32_e32 v145, v145
	v_rcp_f32_e32 v146, v146
	v_rcp_f32_e32 v147, v147
	v_rcp_f32_e32 v104, v148
	v_rcp_f32_e32 v148, v158
	v_add_f32_e32 v91, 1.0, v152
	v_add_f32_e32 v158, 1.0, v153
	v_add_f32_e32 v154, 1.0, v154
	v_add_f32_e32 v155, 1.0, v155
	v_mul_f32_e32 v44, 0x45800000, v17
	v_mul_f32_e32 v69, 0x45800000, v68
	v_add_f32_e32 v161, 1.0, v175
	v_add_f32_e32 v162, 1.0, v171
	v_rcp_f32_e32 v105, v149
	v_rcp_f32_e32 v149, v160
	v_add_f32_e32 v156, 1.0, v156
	v_add_f32_e32 v160, 1.0, v177
	v_pk_mul_f32 v[70:71], v[120:121], v[70:71]
	v_pk_mul_f32 v[76:77], v[122:123], v[76:77]
	v_rcp_f32_e32 v120, v91
	v_rcp_f32_e32 v121, v158
	v_rcp_f32_e32 v122, v154
	v_rcp_f32_e32 v123, v155
	v_cndmask_b32_e64 v44, v17, v44, s[0:1]
	v_cndmask_b32_e32 v68, v68, v69, vcc
	v_add_f32_e32 v163, 1.0, v176
	v_add_f32_e32 v164, 1.0, v172
	v_rcp_f32_e32 v150, v161
	v_rcp_f32_e32 v151, v162
	v_pk_mul_f32 v[78:79], v[126:127], v[78:79]
	v_rcp_f32_e32 v126, v156
	v_rcp_f32_e32 v127, v160
	v_pk_mul_f32 v[72:73], v[106:107], v[44:45] op_sel_hi:[1,0]
	v_pk_mul_f32 v[82:83], v[94:95], v[44:45] op_sel_hi:[1,0]
	v_pk_mul_f32 v[92:93], v[98:99], v[44:45] op_sel_hi:[1,0]
	v_pk_mul_f32 v[94:95], v[96:97], v[44:45] op_sel_hi:[1,0]
	v_pk_mul_f32 v[66:67], v[66:67], v[44:45] op_sel_hi:[1,0]
	v_pk_mul_f32 v[64:65], v[64:65], v[44:45] op_sel_hi:[1,0]
	v_pk_mul_f32 v[62:63], v[62:63], v[44:45] op_sel_hi:[1,0]
	v_mul_f32_e32 v17, v61, v44
	v_mul_f32_e32 v44, v60, v44
	v_mul_f32_e32 v91, v68, v49
	v_mov_b32_e32 v49, v68
	v_rcp_f32_e32 v152, v163
	v_rcp_f32_e32 v153, v164
	v_pk_mul_f32 v[58:59], v[68:69], v[58:59] op_sel_hi:[0,1]
	v_pk_mul_f32 v[18:19], v[68:69], v[18:19] op_sel_hi:[0,1]
	v_pk_mul_f32 v[56:57], v[68:69], v[56:57] op_sel_hi:[0,1]
	v_mul_f32_e32 v44, v3, v44
	v_pk_mul_f32 v[22:23], v[48:49], v[22:23]
	v_pk_mul_f32 v[80:81], v[136:137], v[142:143]
	v_pk_mul_f32 v[102:103], v[144:145], v[102:103]
	v_pk_mul_f32 v[116:117], v[146:147], v[116:117]
	v_pk_mul_f32 v[20:21], v[68:69], v[20:21] op_sel_hi:[0,1]
	v_pk_mul_f32 v[54:55], v[68:69], v[54:55] op_sel_hi:[0,1]
	v_pk_mul_f32 v[52:53], v[68:69], v[52:53] op_sel_hi:[0,1]
	v_pk_mul_f32 v[50:51], v[68:69], v[50:51] op_sel_hi:[0,1]
	v_pk_mul_f32 v[60:61], v[12:13], v[72:73]
	v_pk_mul_f32 v[68:69], v[14:15], v[82:83]
	v_pk_mul_f32 v[72:73], v[8:9], v[92:93]
	v_pk_mul_f32 v[62:63], v[0:1], v[62:63]
	v_pk_mul_f32 v[16:17], v[28:29], v[16:17]
	v_pk_mul_f32 v[58:59], v[30:31], v[58:59]
	v_pk_mul_f32 v[18:19], v[32:33], v[18:19]
	v_pk_mul_f32 v[56:57], v[34:35], v[56:57]
	v_pk_mul_f32 v[22:23], v[44:45], v[22:23]
	v_pk_mul_f32 v[74:75], v[132:133], v[130:131]
	v_pk_mul_f32 v[82:83], v[10:11], v[94:95]
	v_pk_mul_f32 v[66:67], v[4:5], v[66:67]
	v_pk_mul_f32 v[64:65], v[6:7], v[64:65]
	v_pk_mul_f32 v[20:21], v[36:37], v[20:21]
	v_pk_mul_f32 v[54:55], v[38:39], v[54:55]
	v_pk_mul_f32 v[52:53], v[40:41], v[52:53]
	v_pk_mul_f32 v[50:51], v[42:43], v[50:51]
	v_mul_f32_e32 v28, v2, v91
	v_pk_mul_f32 v[48:49], v[116:117], v[60:61]
	v_pk_mul_f32 v[60:61], v[102:103], v[68:69]
	v_pk_mul_f32 v[68:69], v[80:81], v[72:73]
	v_pk_mul_f32 v[62:63], v[70:71], v[62:63]
	v_mul_f32_e32 v70, v16, v17
	v_pk_mul_f32 v[16:17], v[84:85], v[58:59]
	v_pk_mul_f32 v[18:19], v[120:121], v[18:19]
	v_pk_mul_f32 v[56:57], v[122:123], v[56:57]
	v_pk_mul_f32 v[22:23], v[114:115], v[22:23]
	v_pk_mul_f32 v[72:73], v[74:75], v[82:83]
	v_pk_mul_f32 v[66:67], v[78:79], v[66:67]
	v_pk_mul_f32 v[64:65], v[76:77], v[64:65]
	v_pk_mul_f32 v[20:21], v[126:127], v[20:21]
	v_pk_mul_f32 v[54:55], v[134:135], v[54:55]
	v_pk_mul_f32 v[52:53], v[138:139], v[52:53]
	v_pk_mul_f32 v[50:51], v[140:141], v[50:51]
	v_mul_f32_e32 v58, v157, v28
	v_mul_f32_e32 v70, v159, v70
	v_pk_fma_f32 v[16:17], v[104:105], v[48:49], v[16:17]
	v_pk_fma_f32 v[18:19], v[148:149], v[60:61], v[18:19]
	v_pk_fma_f32 v[48:49], v[150:151], v[68:69], v[56:57]
	v_mov_b32_e32 v71, v22
	v_mov_b32_e32 v59, v23
	v_pk_fma_f32 v[20:21], v[152:153], v[72:73], v[20:21]
	v_pk_fma_f32 v[54:55], v[108:109], v[66:67], v[54:55]
	v_pk_fma_f32 v[52:53], v[110:111], v[64:65], v[52:53]
	v_pk_fma_f32 v[50:51], v[112:113], v[62:63], v[50:51]
	v_cvt_pk_bf16_f32 v16, v16, v17
	v_cvt_pk_bf16_f32 v17, v18, v19
	v_cvt_pk_bf16_f32 v18, v48, v49
	v_pk_add_f32 v[48:49], v[70:71], v[58:59]
	v_cvt_pk_bf16_f32 v19, v20, v21
	v_cvt_pk_bf16_f32 v20, v54, v55
	v_cvt_pk_bf16_f32 v21, v52, v53
	v_cvt_pk_bf16_f32 v22, v50, v51
	v_cvt_pk_bf16_f32 v23, v48, v49
	global_store_dwordx4 v[252:253], v[16:19], off offset:-16
	global_store_dwordx4 v[252:253], v[20:23], off
.Lmp0_loop:
	s_cmp_lg_u64 s[10:11], 0
	s_cbranch_scc1 .Lmp0_finalB
	v_add_co_u32_e32 v48, vcc, 0xf8000000, v26
	v_lshl_add_u64 v[50:51], v[26:27], 0, s[12:13]
	v_lshl_add_u64 v[54:55], v[26:27], 0, s[14:15]
	v_addc_co_u32_e32 v49, vcc, -1, v27, vcc
	global_load_dwordx4 v[20:23], v[26:27], off
	global_load_dwordx4 v[16:19], v[26:27], off offset:-16
	v_lshl_add_u64 v[52:53], v[26:27], 0, s[16:17]
	v_lshl_add_u64 v[56:57], v[26:27], 0, s[18:19]
	global_load_dwordx4 v[60:63], v[54:55], off offset:16
	global_load_dwordx4 v[64:67], v[50:51], off offset:16
	global_load_dwordx4 v[68:71], v[56:57], off offset:16
	global_load_dwordx4 v[72:75], v[52:53], off offset:16
	v_add_co_u32_e32 v50, vcc, 0xfc000000, v26
	v_lshl_add_u64 v[46:47], v[26:27], 0, s[20:21]
	s_nop 0
	v_addc_co_u32_e32 v51, vcc, -1, v27, vcc
	v_add_co_u32_e32 v52, vcc, 0xdfc00000, v26
	global_load_dwordx4 v[92:95], v[48:49], off offset:-16
	global_load_dwordx4 v[96:99], v[46:47], off offset:16
	v_addc_co_u32_e32 v53, vcc, -1, v27, vcc
	v_add_co_u32_e32 v48, vcc, s3, v26
	global_load_dwordx4 v[100:103], v[50:51], off offset:-16
	global_load_dwordx4 v[104:107], v[52:53], off offset:-16
	v_addc_co_u32_e32 v49, vcc, -1, v27, vcc
	v_add_co_u32_e32 v50, vcc, s23, v26
	v_add_u32_e32 v86, s8, v86
	s_nop 0
	v_addc_co_u32_e32 v51, vcc, -1, v27, vcc
	global_load_dwordx4 v[108:111], v[48:49], off offset:-16
	global_load_dwordx4 v[112:115], v[50:51], off offset:-16
	v_add_co_u32_e32 v252, vcc, 0xc7c00000, v26
	v_cmp_lt_i32_e64 s[0:1], s28, v86
	s_nop 0
	v_addc_co_u32_e32 v253, vcc, -1, v27, vcc
	s_or_b64 s[10:11], s[0:1], s[10:11]
	v_lshl_add_u64 v[26:27], v[26:27], 0, s[24:25]
	s_waitcnt vmcnt(25)
	v_lshlrev_b32_e32 v50, 16, v186
	s_waitcnt vmcnt(24)
	v_lshlrev_b32_e32 v58, 16, v180
	v_and_b32_e32 v59, 0xffff0000, v180
	s_waitcnt vmcnt(23)
	v_lshlrev_b32_e32 v83, 16, v191
	s_waitcnt vmcnt(22)
	v_lshlrev_b32_e32 v117, 16, v195
	v_and_b32_e32 v82, 0xffff0000, v191
	v_and_b32_e32 v116, 0xffff0000, v195
	s_waitcnt vmcnt(21)
	v_and_b32_e32 v191, 0xffff0000, v197
	s_waitcnt vmcnt(20)
	v_lshlrev_b32_e32 v180, 16, v223
	v_lshlrev_b32_e32 v85, 16, v199
	v_lshlrev_b32_e32 v118, 16, v194
	v_and_b32_e32 v119, 0xffff0000, v194
	v_lshlrev_b32_e32 v194, 16, v190
	v_and_b32_e32 v195, 0xffff0000, v190
	v_lshlrev_b32_e32 v76, 16, v221
	v_lshlrev_b32_e32 v128, 16, v192
	v_and_b32_e32 v129, 0xffff0000, v192
	v_lshlrev_b32_e32 v130, 16, v188
	v_and_b32_e32 v131, 0xffff0000, v188
	v_lshlrev_b32_e32 v78, 16, v220
	v_and_b32_e32 v79, 0xffff0000, v220
	v_mul_f32_e32 v137, 0xbfb8aa3b, v191
	s_waitcnt vmcnt(18)
	v_lshlrev_b32_e32 v142, 16, v231
	v_mul_f32_e32 v143, 0xbfb8aa3b, v180
	v_mul_f32_e32 v85, 0xbfb8aa3b, v85
	v_and_b32_e32 v144, 0xffff0000, v231
	v_pk_add_f32 v[190:191], v[118:119], v[194:195]
	v_mul_f32_e32 v145, 0xbfb8aa3b, v76
	v_pk_add_f32 v[194:195], v[128:129], v[130:131]
	v_mul_f32_e32 v130, 0xbfb8aa3b, v78
	v_mul_f32_e32 v131, 0xbfb8aa3b, v79
	v_and_b32_e32 v51, 0xffff0000, v186
	v_and_b32_e32 v81, 0xffff0000, v198
	v_and_b32_e32 v186, 0xffff0000, v223
	v_lshlrev_b32_e32 v124, 16, v189
	v_and_b32_e32 v125, 0xffff0000, v189
	v_and_b32_e32 v77, 0xffff0000, v221
	v_pk_add_f32 v[188:189], v[116:117], v[82:83]
	v_lshlrev_b32_e32 v221, 16, v228
	v_and_b32_e32 v223, 0xffff0000, v228
	v_lshlrev_b32_e32 v133, 16, v229
	v_and_b32_e32 v135, 0xffff0000, v229
	v_lshlrev_b32_e32 v139, 16, v230
	v_and_b32_e32 v141, 0xffff0000, v230
	v_lshlrev_b32_e32 v228, 16, v227
	v_and_b32_e32 v229, 0xffff0000, v227
	v_lshlrev_b32_e32 v230, 16, v226
	v_and_b32_e32 v231, 0xffff0000, v226
	v_lshlrev_b32_e32 v116, 16, v224
	v_and_b32_e32 v117, 0xffff0000, v224
	v_exp_f32_e32 v147, v137
	v_exp_f32_e32 v150, v143
	v_exp_f32_e32 v151, v85
	v_mul_f32_e32 v85, 0xbfb8aa3b, v142
	v_mul_f32_e32 v137, 0xbfb8aa3b, v144
	v_exp_f32_e32 v153, v145
	v_exp_f32_e32 v154, v130
	v_exp_f32_e32 v155, v131
	s_waitcnt vmcnt(17)
	v_lshlrev_b32_e32 v130, 16, v235
	v_and_b32_e32 v131, 0xffff0000, v235
	v_lshlrev_b32_e32 v142, 16, v234
	v_and_b32_e32 v143, 0xffff0000, v234
	v_lshlrev_b32_e32 v144, 16, v232
	v_and_b32_e32 v145, 0xffff0000, v232
	v_lshlrev_b32_e32 v52, 16, v185
	v_and_b32_e32 v53, 0xffff0000, v185
	v_mul_f32_e32 v81, 0xbfb8aa3b, v81
	v_lshlrev_b32_e32 v226, 16, v225
	v_and_b32_e32 v227, 0xffff0000, v225
	v_lshlrev_b32_e32 v234, 16, v233
	v_and_b32_e32 v235, 0xffff0000, v233
	v_pk_add_f32 v[228:229], v[228:229], v[130:131]
	s_waitcnt vmcnt(16)
	v_lshlrev_b32_e32 v130, 16, v243
	v_and_b32_e32 v131, 0xffff0000, v243
	v_pk_add_f32 v[230:231], v[230:231], v[142:143]
	v_lshlrev_b32_e32 v142, 16, v242
	v_and_b32_e32 v143, 0xffff0000, v242
	v_pk_add_f32 v[242:243], v[116:117], v[144:145]
	v_pk_mul_f32 v[126:127], v[52:53], v[52:53]
	v_mov_b32_e32 v140, v59
	v_exp_f32_e32 v149, v81
	v_mul_f32_e32 v81, 0xbfb8aa3b, v141
	v_pk_add_f32 v[226:227], v[226:227], v[234:235]
	v_lshlrev_b32_e32 v234, 16, v241
	v_and_b32_e32 v235, 0xffff0000, v241
	v_lshlrev_b32_e32 v116, 16, v240
	v_and_b32_e32 v117, 0xffff0000, v240
	s_waitcnt vmcnt(15)
	v_lshlrev_b32_e32 v240, 16, v244
	v_and_b32_e32 v241, 0xffff0000, v244
	v_mov_b32_e32 v141, v243
	v_lshlrev_b32_e32 v56, 16, v182
	v_and_b32_e32 v57, 0xffff0000, v182
	v_lshlrev_b32_e32 v182, 16, v181
	v_mov_b32_e32 v138, v58
	v_mov_b32_e32 v224, v126
	v_mul_f32_e32 v126, 0xbfb8aa3b, v133
	v_mul_f32_e32 v133, 0xbfb8aa3b, v135
	v_mul_f32_e32 v135, 0xbfb8aa3b, v139
	v_mov_b32_e32 v139, v242
	v_mul_f32_e32 v168, 0xbfb8aa3b, v240
	v_mul_f32_e32 v169, 0xbfb8aa3b, v241
	v_pk_mul_f32 v[240:241], v[140:141], v[140:141]
	v_lshlrev_b32_e32 v54, 16, v184
	v_and_b32_e32 v55, 0xffff0000, v184
	v_lshlrev_b32_e32 v184, 16, v183
	v_and_b32_e32 v185, 0xffff0000, v183
	v_and_b32_e32 v183, 0xffff0000, v181
	v_mov_b32_e32 v134, v182
	v_exp_f32_e32 v159, v135
	v_mov_b32_e32 v135, v226
	v_pk_fma_f32 v[240:241], v[138:139], v[138:139], v[240:241]
	v_mov_b32_e32 v136, v183
	v_exp_f32_e32 v162, v137
	v_mov_b32_e32 v137, v227
	v_pk_fma_f32 v[240:241], v[134:135], v[134:135], v[240:241]
	v_mov_b32_e32 v132, v56
	v_exp_f32_e32 v158, v133
	v_mov_b32_e32 v133, v230
	v_pk_fma_f32 v[240:241], v[136:137], v[136:137], v[240:241]
	v_mov_b32_e32 v84, v57
	v_exp_f32_e32 v161, v85
	v_mov_b32_e32 v85, v231
	v_pk_fma_f32 v[240:241], v[132:133], v[132:133], v[240:241]
	v_mov_b32_e32 v80, v184
	v_mul_f32_e32 v223, 0xbfb8aa3b, v223
	v_exp_f32_e32 v160, v81
	v_mov_b32_e32 v81, v228
	v_pk_fma_f32 v[84:85], v[84:85], v[84:85], v[240:241]
	v_lshlrev_b32_e32 v44, 16, v197
	v_lshlrev_b32_e32 v197, 16, v198
	v_and_b32_e32 v91, 0xffff0000, v199
	v_pk_mul_f32 v[120:121], v[50:51], v[50:51]
	v_lshlrev_b32_e32 v198, 16, v222
	v_and_b32_e32 v199, 0xffff0000, v222
	v_lshlrev_b32_e32 v122, 16, v193
	v_and_b32_e32 v123, 0xffff0000, v193
	v_mov_b32_e32 v222, v185
	v_exp_f32_e32 v157, v223
	v_mov_b32_e32 v223, v229
	v_pk_fma_f32 v[80:81], v[80:81], v[80:81], v[84:85]
	v_mov_b32_e32 v220, v54
	v_mul_f32_e32 v197, 0xbfb8aa3b, v197
	v_pk_add_f32 v[192:193], v[122:123], v[124:125]
	v_mov_b32_e32 v118, v120
	v_mul_f32_e32 v120, 0xbfb8aa3b, v221
	v_mov_b32_e32 v221, v194
	v_pk_fma_f32 v[222:223], v[222:223], v[222:223], v[80:81]
	v_lshlrev_b32_e32 v181, 16, v196
	v_and_b32_e32 v28, 0xffff0000, v196
	v_mov_b32_e32 v196, v55
	v_mul_f32_e32 v225, 0xbfb8aa3b, v186
	v_exp_f32_e32 v148, v197
	v_pk_mul_f32 v[128:129], v[192:193], v[192:193]
	v_mov_b32_e32 v197, v195
	v_pk_fma_f32 v[220:221], v[220:221], v[220:221], v[222:223]
	v_exp_f32_e32 v156, v225
	v_mov_b32_e32 v225, v128
	v_pk_fma_f32 v[196:197], v[196:197], v[196:197], v[220:221]
	v_lshlrev_b32_e32 v49, 16, v187
	v_and_b32_e32 v187, 0xffff0000, v187
	v_mul_f32_e32 v119, 0xbfb8aa3b, v199
	v_pk_mul_f32 v[124:125], v[190:191], v[190:191]
	v_mov_b32_e32 v128, v127
	v_pk_add_f32 v[196:197], v[224:225], v[196:197]
	v_mov_b32_e32 v48, v187
	v_exp_f32_e32 v152, v119
	v_mov_b32_e32 v119, v124
	v_pk_add_f32 v[196:197], v[128:129], v[196:197]
	v_pk_mul_f32 v[82:83], v[48:49], v[48:49]
	v_pk_mul_f32 v[122:123], v[188:189], v[188:189]
	v_mov_b32_e32 v124, v121
	v_pk_add_f32 v[196:197], v[118:119], v[196:197]
	v_mov_b32_e32 v232, v83
	v_mov_b32_e32 v233, v123
	v_pk_add_f32 v[196:197], v[124:125], v[196:197]
	v_mov_b32_e32 v83, v122
	v_pk_add_f32 v[196:197], v[232:233], v[196:197]
	v_mul_f32_e32 v181, 0xbfb8aa3b, v181
	v_pk_add_f32 v[196:197], v[82:83], v[196:197]
	ds_bpermute_b32 v221, v87, v197
	ds_bpermute_b32 v220, v87, v196
	v_mul_f32_e32 v44, 0xbfb8aa3b, v44
	v_mul_f32_e32 v48, 0xbfb8aa3b, v198
	v_exp_f32_e32 v181, v181
	v_exp_f32_e32 v44, v44
	s_waitcnt lgkmcnt(0)
	v_pk_add_f32 v[196:197], v[196:197], v[220:221]
	ds_bpermute_b32 v221, v88, v197
	ds_bpermute_b32 v220, v88, v196
	v_exp_f32_e32 v48, v48
	v_exp_f32_e32 v120, v120
	v_exp_f32_e32 v126, v126
	v_mul_f32_e32 v123, 0xbfb8aa3b, v130
	s_waitcnt lgkmcnt(0)
	v_pk_add_f32 v[196:197], v[196:197], v[220:221]
	ds_bpermute_b32 v221, v89, v197
	ds_bpermute_b32 v220, v89, v196
	v_mul_f32_e32 v127, 0xbfb8aa3b, v131
	s_waitcnt vmcnt(14)
	v_lshlrev_b32_e32 v167, 16, v248
	v_and_b32_e32 v248, 0xffff0000, v248
	v_lshlrev_b32_e32 v244, 16, v245
	s_waitcnt lgkmcnt(0)
	v_pk_add_f32 v[196:197], v[196:197], v[220:221]
	ds_bpermute_b32 v221, v90, v197
	ds_bpermute_b32 v220, v90, v196
	v_and_b32_e32 v245, 0xffff0000, v245
	v_lshlrev_b32_e32 v121, 16, v246
	v_and_b32_e32 v246, 0xffff0000, v246
	v_exp_f32_e32 v173, v123
	v_exp_f32_e32 v174, v127
	v_mul_f32_e32 v123, 0xbfb8aa3b, v167
	v_mul_f32_e32 v248, 0xbfb8aa3b, v248
	v_lshlrev_b32_e32 v122, 16, v247
	v_lshlrev_b32_e32 v170, 16, v249
	v_mul_f32_e32 v244, 0xbfb8aa3b, v244
	v_and_b32_e32 v249, 0xffff0000, v249
	v_mul_f32_e32 v245, 0xbfb8aa3b, v245
	v_lshlrev_b32_e32 v171, 16, v250
	v_and_b32_e32 v250, 0xffff0000, v250
	v_mul_f32_e32 v246, 0xbfb8aa3b, v246
	v_add_f32_e32 v127, 1.0, v150
	v_add_f32_e32 v140, 1.0, v151
	v_exp_f32_e32 v150, v123
	v_exp_f32_e32 v151, v248
	v_mul_f32_e32 v122, 0xbfb8aa3b, v122
	v_exp_f32_e32 v167, v169
	v_exp_f32_e32 v169, v244
	v_mul_f32_e32 v244, 0xbfb8aa3b, v170
	v_exp_f32_e32 v170, v245
	v_mul_f32_e32 v245, 0xbfb8aa3b, v249
	v_mul_f32_e32 v249, 0xbfb8aa3b, v171
	v_exp_f32_e32 v171, v246
	v_mul_f32_e32 v246, 0xbfb8aa3b, v250
	v_add_f32_e32 v181, 1.0, v181
	v_add_f32_e32 v44, 1.0, v44
	v_mul_f32_e32 v146, 0xbfb8aa3b, v77
	v_exp_f32_e32 v176, v122
	v_add_f32_e32 v122, 1.0, v149
	v_add_f32_e32 v48, 1.0, v48
	v_add_f32_e32 v141, 1.0, v152
	v_add_f32_e32 v149, 1.0, v155
	v_add_f32_e32 v138, 1.0, v156
	v_exp_f32_e32 v152, v244
	v_exp_f32_e32 v155, v246
	v_rcp_f32_e32 v244, v181
	v_add_f32_e32 v181, 1.0, v120
	v_rcp_f32_e32 v246, v44
	v_add_f32_e32 v44, 1.0, v126
	v_mul_f32_e32 v28, 0xbfb8aa3b, v28
	v_mul_f32_e32 v91, 0xbfb8aa3b, v91
	v_exp_f32_e32 v146, v146
	v_rcp_f32_e32 v120, v48
	v_rcp_f32_e32 v48, v138
	v_rcp_f32_e32 v134, v181
	v_rcp_f32_e32 v138, v44
	v_add_f32_e32 v181, 1.0, v173
	v_add_f32_e32 v44, 1.0, v174
	s_waitcnt lgkmcnt(0)
	v_pk_add_f32 v[196:197], v[196:197], v[220:221]
	v_exp_f32_e32 v28, v28
	v_exp_f32_e32 v91, v91
	v_rcp_f32_e32 v132, v181
	v_rcp_f32_e32 v133, v44
	v_add_f32_e32 v181, 1.0, v150
	v_add_f32_e32 v44, 1.0, v151
	v_pk_fma_f32 v[196:197], v[196:197], s[22:23], v[24:25] op_sel_hi:[1,0,1]
	v_and_b32_e32 v247, 0xffff0000, v247
	v_mul_f32_e32 v144, 0xbfb8aa3b, v142
	v_mul_f32_e32 v145, 0xbfb8aa3b, v143
	v_mul_f32_e32 v163, 0xbfb8aa3b, v234
	v_mul_f32_e32 v164, 0xbfb8aa3b, v235
	v_mul_f32_e32 v165, 0xbfb8aa3b, v116
	v_mul_f32_e32 v166, 0xbfb8aa3b, v117
	v_rcp_f32_e32 v84, v181
	v_rcp_f32_e32 v85, v44
	v_mul_f32_e32 v181, 0x4b800000, v197
	v_mul_f32_e32 v44, 0x4b800000, v196
	v_cmp_gt_f32_e32 vcc, s27, v196
	v_cmp_gt_f32_e64 s[0:1], s27, v197
	v_mul_f32_e32 v121, 0xbfb8aa3b, v121
	v_lshlrev_b32_e32 v172, 16, v251
	v_and_b32_e32 v251, 0xffff0000, v251
	v_mul_f32_e32 v247, 0xbfb8aa3b, v247
	v_exp_f32_e32 v144, v144
	v_exp_f32_e32 v145, v145
	v_exp_f32_e32 v163, v163
	v_exp_f32_e32 v164, v164
	v_exp_f32_e32 v165, v165
	v_exp_f32_e32 v166, v166
	v_exp_f32_e32 v168, v168
	v_cndmask_b32_e64 v181, v197, v181, s[0:1]
	v_cndmask_b32_e32 v44, v196, v44, vcc
	v_exp_f32_e32 v175, v121
	v_mul_f32_e32 v250, 0xbfb8aa3b, v172
	v_exp_f32_e32 v172, v247
	v_mul_f32_e32 v247, 0xbfb8aa3b, v251
	v_add_f32_e32 v251, 1.0, v147
	v_add_f32_e32 v121, 1.0, v148
	v_add_f32_e32 v147, 1.0, v153
	v_add_f32_e32 v146, 1.0, v146
	v_add_f32_e32 v148, 1.0, v154
	v_exp_f32_e32 v153, v245
	v_exp_f32_e32 v154, v249
	v_rsq_f32_e32 v181, v181
	v_rsq_f32_e32 v196, v44
	v_add_f32_e32 v28, 1.0, v28
	v_add_f32_e32 v91, 1.0, v91
	v_exp_f32_e32 v156, v250
	v_exp_f32_e32 v177, v247
	v_rcp_f32_e32 v248, v121
	v_rcp_f32_e32 v249, v122
	v_rcp_f32_e32 v121, v141
	v_rcp_f32_e32 v122, v147
	v_rcp_f32_e32 v123, v146
	v_rcp_f32_e32 v245, v28
	v_add_f32_e32 v139, 1.0, v157
	v_rcp_f32_e32 v247, v251
	v_add_f32_e32 v251, 1.0, v158
	v_add_f32_e32 v158, 1.0, v160
	v_rcp_f32_e32 v28, v127
	v_rcp_f32_e32 v250, v91
	v_add_f32_e32 v91, 1.0, v162
	v_rcp_f32_e32 v126, v148
	v_rcp_f32_e32 v127, v149
	v_add_f32_e32 v157, 1.0, v159
	v_add_f32_e32 v160, 1.0, v161
	v_rcp_f32_e32 v135, v139
	v_rcp_f32_e32 v139, v251
	v_rcp_f32_e32 v141, v158
	v_rcp_f32_e32 v251, v91
	v_add_f32_e32 v91, 1.0, v144
	v_add_f32_e32 v137, 1.0, v145
	v_add_f32_e32 v144, 1.0, v163
	v_add_f32_e32 v145, 1.0, v164
	v_add_f32_e32 v146, 1.0, v165
	v_add_f32_e32 v147, 1.0, v166
	v_add_f32_e32 v148, 1.0, v168
	v_add_f32_e32 v158, 1.0, v169
	v_rcp_f32_e32 v159, v140
	v_rcp_f32_e32 v140, v157
	v_rcp_f32_e32 v157, v160
	v_add_f32_e32 v149, 1.0, v167
	v_add_f32_e32 v160, 1.0, v170
	v_rcp_f32_e32 v136, v91
	v_rcp_f32_e32 v137, v137
	v_rcp_f32_e32 v144, v144
	v_rcp_f32_e32 v145, v145
	v_rcp_f32_e32 v146, v146
	v_rcp_f32_e32 v147, v147
	v_rcp_f32_e32 v240, v148
	v_rcp_f32_e32 v148, v158
	v_add_f32_e32 v91, 1.0, v152
	v_add_f32_e32 v158, 1.0, v153
	v_add_f32_e32 v154, 1.0, v154
	v_add_f32_e32 v155, 1.0, v155
	v_mul_f32_e32 v44, 0x45800000, v181
	v_mul_f32_e32 v197, 0x45800000, v196
	v_add_f32_e32 v161, 1.0, v175
	v_add_f32_e32 v162, 1.0, v171
	v_rcp_f32_e32 v241, v149
	v_rcp_f32_e32 v149, v160
	v_add_f32_e32 v156, 1.0, v156
	v_add_f32_e32 v160, 1.0, v177
	v_pk_mul_f32 v[198:199], v[120:121], v[198:199]
	v_pk_mul_f32 v[76:77], v[122:123], v[76:77]
	v_rcp_f32_e32 v120, v91
	v_rcp_f32_e32 v121, v158
	v_rcp_f32_e32 v122, v154
	v_rcp_f32_e32 v123, v155
	v_cndmask_b32_e64 v44, v181, v44, s[0:1]
	v_cndmask_b32_e32 v196, v196, v197, vcc
	v_add_f32_e32 v163, 1.0, v176
	v_add_f32_e32 v164, 1.0, v172
	v_rcp_f32_e32 v150, v161
	v_rcp_f32_e32 v151, v162
	v_pk_mul_f32 v[78:79], v[126:127], v[78:79]
	v_rcp_f32_e32 v126, v156
	v_rcp_f32_e32 v127, v160
	v_pk_mul_f32 v[220:221], v[242:243], v[44:45] op_sel_hi:[1,0]
	v_pk_mul_f32 v[82:83], v[226:227], v[44:45] op_sel_hi:[1,0]
	v_pk_mul_f32 v[224:225], v[230:231], v[44:45] op_sel_hi:[1,0]
	v_pk_mul_f32 v[226:227], v[228:229], v[44:45] op_sel_hi:[1,0]
	v_pk_mul_f32 v[194:195], v[194:195], v[44:45] op_sel_hi:[1,0]
	v_pk_mul_f32 v[192:193], v[192:193], v[44:45] op_sel_hi:[1,0]
	v_pk_mul_f32 v[190:191], v[190:191], v[44:45] op_sel_hi:[1,0]
	v_mul_f32_e32 v181, v189, v44
	v_mul_f32_e32 v44, v188, v44
	v_mul_f32_e32 v91, v196, v49
	v_mov_b32_e32 v49, v196
	v_rcp_f32_e32 v152, v163
	v_rcp_f32_e32 v153, v164
	v_pk_mul_f32 v[58:59], v[196:197], v[58:59] op_sel_hi:[0,1]
	v_pk_mul_f32 v[182:183], v[196:197], v[182:183] op_sel_hi:[0,1]
	v_pk_mul_f32 v[56:57], v[196:197], v[56:57] op_sel_hi:[0,1]
	v_mul_f32_e32 v44, v3, v44
	v_pk_mul_f32 v[186:187], v[48:49], v[186:187]
	v_pk_mul_f32 v[80:81], v[136:137], v[142:143]
	v_pk_mul_f32 v[234:235], v[144:145], v[234:235]
	v_pk_mul_f32 v[116:117], v[146:147], v[116:117]
	v_pk_mul_f32 v[184:185], v[196:197], v[184:185] op_sel_hi:[0,1]
	v_pk_mul_f32 v[54:55], v[196:197], v[54:55] op_sel_hi:[0,1]
	v_pk_mul_f32 v[52:53], v[196:197], v[52:53] op_sel_hi:[0,1]
	v_pk_mul_f32 v[50:51], v[196:197], v[50:51] op_sel_hi:[0,1]
	v_pk_mul_f32 v[188:189], v[12:13], v[220:221]
	v_pk_mul_f32 v[196:197], v[14:15], v[82:83]
	v_pk_mul_f32 v[220:221], v[8:9], v[224:225]
	v_pk_mul_f32 v[190:191], v[0:1], v[190:191]
	v_pk_mul_f32 v[180:181], v[28:29], v[180:181]
	v_pk_mul_f32 v[58:59], v[30:31], v[58:59]
	v_pk_mul_f32 v[182:183], v[32:33], v[182:183]
	v_pk_mul_f32 v[56:57], v[34:35], v[56:57]
	v_pk_mul_f32 v[186:187], v[44:45], v[186:187]
	v_pk_mul_f32 v[222:223], v[132:133], v[130:131]
	v_pk_mul_f32 v[82:83], v[10:11], v[226:227]
	v_pk_mul_f32 v[194:195], v[4:5], v[194:195]
	v_pk_mul_f32 v[192:193], v[6:7], v[192:193]
	v_pk_mul_f32 v[184:185], v[36:37], v[184:185]
	v_pk_mul_f32 v[54:55], v[38:39], v[54:55]
	v_pk_mul_f32 v[52:53], v[40:41], v[52:53]
	v_pk_mul_f32 v[50:51], v[42:43], v[50:51]
	v_mul_f32_e32 v28, v2, v91
	v_pk_mul_f32 v[48:49], v[116:117], v[188:189]
	v_pk_mul_f32 v[188:189], v[234:235], v[196:197]
	v_pk_mul_f32 v[196:197], v[80:81], v[220:221]
	v_pk_mul_f32 v[190:191], v[198:199], v[190:191]
	v_mul_f32_e32 v198, v180, v181
	v_pk_mul_f32 v[180:181], v[84:85], v[58:59]
	v_pk_mul_f32 v[182:183], v[120:121], v[182:183]
	v_pk_mul_f32 v[56:57], v[122:123], v[56:57]
	v_pk_mul_f32 v[186:187], v[250:251], v[186:187]
	v_pk_mul_f32 v[220:221], v[222:223], v[82:83]
	v_pk_mul_f32 v[194:195], v[78:79], v[194:195]
	v_pk_mul_f32 v[192:193], v[76:77], v[192:193]
	v_pk_mul_f32 v[184:185], v[126:127], v[184:185]
	v_pk_mul_f32 v[54:55], v[134:135], v[54:55]
	v_pk_mul_f32 v[52:53], v[138:139], v[52:53]
	v_pk_mul_f32 v[50:51], v[140:141], v[50:51]
	v_mul_f32_e32 v58, v157, v28
	v_mul_f32_e32 v198, v159, v198
	v_pk_fma_f32 v[180:181], v[240:241], v[48:49], v[180:181]
	v_pk_fma_f32 v[182:183], v[148:149], v[188:189], v[182:183]
	v_pk_fma_f32 v[48:49], v[150:151], v[196:197], v[56:57]
	v_mov_b32_e32 v199, v186
	v_mov_b32_e32 v59, v187
	v_pk_fma_f32 v[184:185], v[152:153], v[220:221], v[184:185]
	v_pk_fma_f32 v[54:55], v[244:245], v[194:195], v[54:55]
	v_pk_fma_f32 v[52:53], v[246:247], v[192:193], v[52:53]
	v_pk_fma_f32 v[50:51], v[248:249], v[190:191], v[50:51]
	v_cvt_pk_bf16_f32 v180, v180, v181
	v_cvt_pk_bf16_f32 v181, v182, v183
	v_cvt_pk_bf16_f32 v182, v48, v49
	v_pk_add_f32 v[48:49], v[198:199], v[58:59]
	v_cvt_pk_bf16_f32 v183, v184, v185
	v_cvt_pk_bf16_f32 v184, v54, v55
	v_cvt_pk_bf16_f32 v185, v52, v53
	v_cvt_pk_bf16_f32 v186, v50, v51
	v_cvt_pk_bf16_f32 v187, v48, v49
	global_store_dwordx4 v[254:255], v[180:183], off offset:-16
	global_store_dwordx4 v[254:255], v[184:187], off
	s_cmp_lg_u64 s[10:11], 0
	s_cbranch_scc1 .Lmp0_finalA
	v_add_co_u32_e32 v48, vcc, 0xf8000000, v26
	v_lshl_add_u64 v[50:51], v[26:27], 0, s[12:13]
	v_lshl_add_u64 v[54:55], v[26:27], 0, s[14:15]
	v_addc_co_u32_e32 v49, vcc, -1, v27, vcc
	global_load_dwordx4 v[184:187], v[26:27], off
	global_load_dwordx4 v[180:183], v[26:27], off offset:-16
	v_lshl_add_u64 v[52:53], v[26:27], 0, s[16:17]
	v_lshl_add_u64 v[56:57], v[26:27], 0, s[18:19]
	global_load_dwordx4 v[188:191], v[54:55], off offset:16
	global_load_dwordx4 v[192:195], v[50:51], off offset:16
	global_load_dwordx4 v[196:199], v[56:57], off offset:16
	global_load_dwordx4 v[220:223], v[52:53], off offset:16
	v_add_co_u32_e32 v50, vcc, 0xfc000000, v26
	v_lshl_add_u64 v[46:47], v[26:27], 0, s[20:21]
	s_nop 0
	v_addc_co_u32_e32 v51, vcc, -1, v27, vcc
	v_add_co_u32_e32 v52, vcc, 0xdfc00000, v26
	global_load_dwordx4 v[224:227], v[48:49], off offset:-16
	global_load_dwordx4 v[228:231], v[46:47], off offset:16
	v_addc_co_u32_e32 v53, vcc, -1, v27, vcc
	v_add_co_u32_e32 v48, vcc, s3, v26
	global_load_dwordx4 v[232:235], v[50:51], off offset:-16
	global_load_dwordx4 v[240:243], v[52:53], off offset:-16
	v_addc_co_u32_e32 v49, vcc, -1, v27, vcc
	v_add_co_u32_e32 v50, vcc, s23, v26
	v_add_u32_e32 v86, s8, v86
	s_nop 0
	v_addc_co_u32_e32 v51, vcc, -1, v27, vcc
	global_load_dwordx4 v[244:247], v[48:49], off offset:-16
	global_load_dwordx4 v[248:251], v[50:51], off offset:-16
	v_add_co_u32_e32 v254, vcc, 0xc7c00000, v26
	v_cmp_lt_i32_e64 s[0:1], s28, v86
	s_nop 0
	v_addc_co_u32_e32 v255, vcc, -1, v27, vcc
	s_or_b64 s[10:11], s[0:1], s[10:11]
	v_lshl_add_u64 v[26:27], v[26:27], 0, s[24:25]
	s_waitcnt vmcnt(25)
	v_lshlrev_b32_e32 v50, 16, v22
	s_waitcnt vmcnt(24)
	v_lshlrev_b32_e32 v58, 16, v16
	v_and_b32_e32 v59, 0xffff0000, v16
	s_waitcnt vmcnt(23)
	v_lshlrev_b32_e32 v83, 16, v63
	s_waitcnt vmcnt(22)
	v_lshlrev_b32_e32 v117, 16, v67
	v_and_b32_e32 v82, 0xffff0000, v63
	v_and_b32_e32 v116, 0xffff0000, v67
	s_waitcnt vmcnt(21)
	v_and_b32_e32 v63, 0xffff0000, v69
	s_waitcnt vmcnt(20)
	v_lshlrev_b32_e32 v16, 16, v75
	v_lshlrev_b32_e32 v85, 16, v71
	v_lshlrev_b32_e32 v118, 16, v66
	v_and_b32_e32 v119, 0xffff0000, v66
	v_lshlrev_b32_e32 v66, 16, v62
	v_and_b32_e32 v67, 0xffff0000, v62
	v_lshlrev_b32_e32 v76, 16, v73
	v_lshlrev_b32_e32 v128, 16, v64
	v_and_b32_e32 v129, 0xffff0000, v64
	v_lshlrev_b32_e32 v130, 16, v60
	v_and_b32_e32 v131, 0xffff0000, v60
	v_lshlrev_b32_e32 v78, 16, v72
	v_and_b32_e32 v79, 0xffff0000, v72
	v_mul_f32_e32 v137, 0xbfb8aa3b, v63
	s_waitcnt vmcnt(18)
	v_lshlrev_b32_e32 v142, 16, v99
	v_mul_f32_e32 v143, 0xbfb8aa3b, v16
	v_mul_f32_e32 v85, 0xbfb8aa3b, v85
	v_and_b32_e32 v144, 0xffff0000, v99
	v_pk_add_f32 v[62:63], v[118:119], v[66:67]
	v_mul_f32_e32 v145, 0xbfb8aa3b, v76
	v_pk_add_f32 v[66:67], v[128:129], v[130:131]
	v_mul_f32_e32 v130, 0xbfb8aa3b, v78
	v_mul_f32_e32 v131, 0xbfb8aa3b, v79
	v_and_b32_e32 v51, 0xffff0000, v22
	v_and_b32_e32 v81, 0xffff0000, v70
	v_and_b32_e32 v22, 0xffff0000, v75
	v_lshlrev_b32_e32 v124, 16, v61
	v_and_b32_e32 v125, 0xffff0000, v61
	v_and_b32_e32 v77, 0xffff0000, v73
	v_pk_add_f32 v[60:61], v[116:117], v[82:83]
	v_lshlrev_b32_e32 v73, 16, v96
	v_and_b32_e32 v75, 0xffff0000, v96
	v_lshlrev_b32_e32 v133, 16, v97
	v_and_b32_e32 v135, 0xffff0000, v97
	v_lshlrev_b32_e32 v139, 16, v98
	v_and_b32_e32 v141, 0xffff0000, v98
	v_lshlrev_b32_e32 v96, 16, v95
	v_and_b32_e32 v97, 0xffff0000, v95
	v_lshlrev_b32_e32 v98, 16, v94
	v_and_b32_e32 v99, 0xffff0000, v94
	v_lshlrev_b32_e32 v116, 16, v92
	v_and_b32_e32 v117, 0xffff0000, v92
	v_exp_f32_e32 v147, v137
	v_exp_f32_e32 v150, v143
	v_exp_f32_e32 v151, v85
	v_mul_f32_e32 v85, 0xbfb8aa3b, v142
	v_mul_f32_e32 v137, 0xbfb8aa3b, v144
	v_exp_f32_e32 v153, v145
	v_exp_f32_e32 v154, v130
	v_exp_f32_e32 v155, v131
	s_waitcnt vmcnt(17)
	v_lshlrev_b32_e32 v130, 16, v103
	v_and_b32_e32 v131, 0xffff0000, v103
	v_lshlrev_b32_e32 v142, 16, v102
	v_and_b32_e32 v143, 0xffff0000, v102
	v_lshlrev_b32_e32 v144, 16, v100
	v_and_b32_e32 v145, 0xffff0000, v100
	v_lshlrev_b32_e32 v52, 16, v21
	v_and_b32_e32 v53, 0xffff0000, v21
	v_mul_f32_e32 v81, 0xbfb8aa3b, v81
	v_lshlrev_b32_e32 v94, 16, v93
	v_and_b32_e32 v95, 0xffff0000, v93
	v_lshlrev_b32_e32 v102, 16, v101
	v_and_b32_e32 v103, 0xffff0000, v101
	v_pk_add_f32 v[96:97], v[96:97], v[130:131]
	s_waitcnt vmcnt(16)
	v_lshlrev_b32_e32 v130, 16, v107
	v_and_b32_e32 v131, 0xffff0000, v107
	v_pk_add_f32 v[98:99], v[98:99], v[142:143]
	v_lshlrev_b32_e32 v142, 16, v106
	v_and_b32_e32 v143, 0xffff0000, v106
	v_pk_add_f32 v[106:107], v[116:117], v[144:145]
	v_pk_mul_f32 v[126:127], v[52:53], v[52:53]
	v_mov_b32_e32 v140, v59
	v_exp_f32_e32 v149, v81
	v_mul_f32_e32 v81, 0xbfb8aa3b, v141
	v_pk_add_f32 v[94:95], v[94:95], v[102:103]
	v_lshlrev_b32_e32 v102, 16, v105
	v_and_b32_e32 v103, 0xffff0000, v105
	v_lshlrev_b32_e32 v116, 16, v104
	v_and_b32_e32 v117, 0xffff0000, v104
	s_waitcnt vmcnt(15)
	v_lshlrev_b32_e32 v104, 16, v108
	v_and_b32_e32 v105, 0xffff0000, v108
	v_mov_b32_e32 v141, v107
	v_lshlrev_b32_e32 v56, 16, v18
	v_and_b32_e32 v57, 0xffff0000, v18
	v_lshlrev_b32_e32 v18, 16, v17
	v_mov_b32_e32 v138, v58
	v_mov_b32_e32 v92, v126
	v_mul_f32_e32 v126, 0xbfb8aa3b, v133
	v_mul_f32_e32 v133, 0xbfb8aa3b, v135
	v_mul_f32_e32 v135, 0xbfb8aa3b, v139
	v_mov_b32_e32 v139, v106
	v_mul_f32_e32 v168, 0xbfb8aa3b, v104
	v_mul_f32_e32 v169, 0xbfb8aa3b, v105
	v_pk_mul_f32 v[104:105], v[140:141], v[140:141]
	v_lshlrev_b32_e32 v54, 16, v20
	v_and_b32_e32 v55, 0xffff0000, v20
	v_lshlrev_b32_e32 v20, 16, v19
	v_and_b32_e32 v21, 0xffff0000, v19
	v_and_b32_e32 v19, 0xffff0000, v17
	v_mov_b32_e32 v134, v18
	v_exp_f32_e32 v159, v135
	v_mov_b32_e32 v135, v94
	v_pk_fma_f32 v[104:105], v[138:139], v[138:139], v[104:105]
	v_mov_b32_e32 v136, v19
	v_exp_f32_e32 v162, v137
	v_mov_b32_e32 v137, v95
	v_pk_fma_f32 v[104:105], v[134:135], v[134:135], v[104:105]
	v_mov_b32_e32 v132, v56
	v_exp_f32_e32 v158, v133
	v_mov_b32_e32 v133, v98
	v_pk_fma_f32 v[104:105], v[136:137], v[136:137], v[104:105]
	v_mov_b32_e32 v84, v57
	v_exp_f32_e32 v161, v85
	v_mov_b32_e32 v85, v99
	v_pk_fma_f32 v[104:105], v[132:133], v[132:133], v[104:105]
	v_mov_b32_e32 v80, v20
	v_mul_f32_e32 v75, 0xbfb8aa3b, v75
	v_exp_f32_e32 v160, v81
	v_mov_b32_e32 v81, v96
	v_pk_fma_f32 v[84:85], v[84:85], v[84:85], v[104:105]
	v_lshlrev_b32_e32 v44, 16, v69
	v_lshlrev_b32_e32 v69, 16, v70
	v_and_b32_e32 v91, 0xffff0000, v71
	v_pk_mul_f32 v[120:121], v[50:51], v[50:51]
	v_lshlrev_b32_e32 v70, 16, v74
	v_and_b32_e32 v71, 0xffff0000, v74
	v_lshlrev_b32_e32 v122, 16, v65
	v_and_b32_e32 v123, 0xffff0000, v65
	v_mov_b32_e32 v74, v21
	v_exp_f32_e32 v157, v75
	v_mov_b32_e32 v75, v97
	v_pk_fma_f32 v[80:81], v[80:81], v[80:81], v[84:85]
	v_mov_b32_e32 v72, v54
	v_mul_f32_e32 v69, 0xbfb8aa3b, v69
	v_pk_add_f32 v[64:65], v[122:123], v[124:125]
	v_mov_b32_e32 v118, v120
	v_mul_f32_e32 v120, 0xbfb8aa3b, v73
	v_mov_b32_e32 v73, v66
	v_pk_fma_f32 v[74:75], v[74:75], v[74:75], v[80:81]
	v_lshlrev_b32_e32 v17, 16, v68
	v_and_b32_e32 v28, 0xffff0000, v68
	v_mov_b32_e32 v68, v55
	v_mul_f32_e32 v93, 0xbfb8aa3b, v22
	v_exp_f32_e32 v148, v69
	v_pk_mul_f32 v[128:129], v[64:65], v[64:65]
	v_mov_b32_e32 v69, v67
	v_pk_fma_f32 v[72:73], v[72:73], v[72:73], v[74:75]
	v_exp_f32_e32 v156, v93
	v_mov_b32_e32 v93, v128
	v_pk_fma_f32 v[68:69], v[68:69], v[68:69], v[72:73]
	v_lshlrev_b32_e32 v49, 16, v23
	v_and_b32_e32 v23, 0xffff0000, v23
	v_mul_f32_e32 v119, 0xbfb8aa3b, v71
	v_pk_mul_f32 v[124:125], v[62:63], v[62:63]
	v_mov_b32_e32 v128, v127
	v_pk_add_f32 v[68:69], v[92:93], v[68:69]
	v_mov_b32_e32 v48, v23
	v_exp_f32_e32 v152, v119
	v_mov_b32_e32 v119, v124
	v_pk_add_f32 v[68:69], v[128:129], v[68:69]
	v_pk_mul_f32 v[82:83], v[48:49], v[48:49]
	v_pk_mul_f32 v[122:123], v[60:61], v[60:61]
	v_mov_b32_e32 v124, v121
	v_pk_add_f32 v[68:69], v[118:119], v[68:69]
	v_mov_b32_e32 v100, v83
	v_mov_b32_e32 v101, v123
	v_pk_add_f32 v[68:69], v[124:125], v[68:69]
	v_mov_b32_e32 v83, v122
	v_pk_add_f32 v[68:69], v[100:101], v[68:69]
	v_mul_f32_e32 v17, 0xbfb8aa3b, v17
	v_pk_add_f32 v[68:69], v[82:83], v[68:69]
	ds_bpermute_b32 v73, v87, v69
	ds_bpermute_b32 v72, v87, v68
	v_mul_f32_e32 v44, 0xbfb8aa3b, v44
	v_mul_f32_e32 v48, 0xbfb8aa3b, v70
	v_exp_f32_e32 v17, v17
	v_exp_f32_e32 v44, v44
	s_waitcnt lgkmcnt(0)
	v_pk_add_f32 v[68:69], v[68:69], v[72:73]
	ds_bpermute_b32 v73, v88, v69
	ds_bpermute_b32 v72, v88, v68
	v_exp_f32_e32 v48, v48
	v_exp_f32_e32 v120, v120
	v_exp_f32_e32 v126, v126
	v_mul_f32_e32 v123, 0xbfb8aa3b, v130
	s_waitcnt lgkmcnt(0)
	v_pk_add_f32 v[68:69], v[68:69], v[72:73]
	ds_bpermute_b32 v73, v89, v69
	ds_bpermute_b32 v72, v89, v68
	v_mul_f32_e32 v127, 0xbfb8aa3b, v131
	s_waitcnt vmcnt(14)
	v_lshlrev_b32_e32 v167, 16, v112
	v_and_b32_e32 v112, 0xffff0000, v112
	v_lshlrev_b32_e32 v108, 16, v109
	s_waitcnt lgkmcnt(0)
	v_pk_add_f32 v[68:69], v[68:69], v[72:73]
	ds_bpermute_b32 v73, v90, v69
	ds_bpermute_b32 v72, v90, v68
	v_and_b32_e32 v109, 0xffff0000, v109
	v_lshlrev_b32_e32 v121, 16, v110
	v_and_b32_e32 v110, 0xffff0000, v110
	v_exp_f32_e32 v173, v123
	v_exp_f32_e32 v174, v127
	v_mul_f32_e32 v123, 0xbfb8aa3b, v167
	v_mul_f32_e32 v112, 0xbfb8aa3b, v112
	v_lshlrev_b32_e32 v122, 16, v111
	v_lshlrev_b32_e32 v170, 16, v113
	v_mul_f32_e32 v108, 0xbfb8aa3b, v108
	v_and_b32_e32 v113, 0xffff0000, v113
	v_mul_f32_e32 v109, 0xbfb8aa3b, v109
	v_lshlrev_b32_e32 v171, 16, v114
	v_and_b32_e32 v114, 0xffff0000, v114
	v_mul_f32_e32 v110, 0xbfb8aa3b, v110
	v_add_f32_e32 v127, 1.0, v150
	v_add_f32_e32 v140, 1.0, v151
	v_exp_f32_e32 v150, v123
	v_exp_f32_e32 v151, v112
	v_mul_f32_e32 v122, 0xbfb8aa3b, v122
	v_exp_f32_e32 v167, v169
	v_exp_f32_e32 v169, v108
	v_mul_f32_e32 v108, 0xbfb8aa3b, v170
	v_exp_f32_e32 v170, v109
	v_mul_f32_e32 v109, 0xbfb8aa3b, v113
	v_mul_f32_e32 v113, 0xbfb8aa3b, v171
	v_exp_f32_e32 v171, v110
	v_mul_f32_e32 v110, 0xbfb8aa3b, v114
	v_add_f32_e32 v17, 1.0, v17
	v_add_f32_e32 v44, 1.0, v44
	v_mul_f32_e32 v146, 0xbfb8aa3b, v77
	v_exp_f32_e32 v176, v122
	v_add_f32_e32 v122, 1.0, v149
	v_add_f32_e32 v48, 1.0, v48
	v_add_f32_e32 v141, 1.0, v152
	v_add_f32_e32 v149, 1.0, v155
	v_add_f32_e32 v138, 1.0, v156
	v_exp_f32_e32 v152, v108
	v_exp_f32_e32 v155, v110
	v_rcp_f32_e32 v108, v17
	v_add_f32_e32 v17, 1.0, v120
	v_rcp_f32_e32 v110, v44
	v_add_f32_e32 v44, 1.0, v126
	v_mul_f32_e32 v28, 0xbfb8aa3b, v28
	v_mul_f32_e32 v91, 0xbfb8aa3b, v91
	v_exp_f32_e32 v146, v146
	v_rcp_f32_e32 v120, v48
	v_rcp_f32_e32 v48, v138
	v_rcp_f32_e32 v134, v17
	v_rcp_f32_e32 v138, v44
	v_add_f32_e32 v17, 1.0, v173
	v_add_f32_e32 v44, 1.0, v174
	s_waitcnt lgkmcnt(0)
	v_pk_add_f32 v[68:69], v[68:69], v[72:73]
	v_exp_f32_e32 v28, v28
	v_exp_f32_e32 v91, v91
	v_rcp_f32_e32 v132, v17
	v_rcp_f32_e32 v133, v44
	v_add_f32_e32 v17, 1.0, v150
	v_add_f32_e32 v44, 1.0, v151
	v_pk_fma_f32 v[68:69], v[68:69], s[22:23], v[24:25] op_sel_hi:[1,0,1]
	v_and_b32_e32 v111, 0xffff0000, v111
	v_mul_f32_e32 v144, 0xbfb8aa3b, v142
	v_mul_f32_e32 v145, 0xbfb8aa3b, v143
	v_mul_f32_e32 v163, 0xbfb8aa3b, v102
	v_mul_f32_e32 v164, 0xbfb8aa3b, v103
	v_mul_f32_e32 v165, 0xbfb8aa3b, v116
	v_mul_f32_e32 v166, 0xbfb8aa3b, v117
	v_rcp_f32_e32 v84, v17
	v_rcp_f32_e32 v85, v44
	v_mul_f32_e32 v17, 0x4b800000, v69
	v_mul_f32_e32 v44, 0x4b800000, v68
	v_cmp_gt_f32_e32 vcc, s27, v68
	v_cmp_gt_f32_e64 s[0:1], s27, v69
	v_mul_f32_e32 v121, 0xbfb8aa3b, v121
	v_lshlrev_b32_e32 v172, 16, v115
	v_and_b32_e32 v115, 0xffff0000, v115
	v_mul_f32_e32 v111, 0xbfb8aa3b, v111
	v_exp_f32_e32 v144, v144
	v_exp_f32_e32 v145, v145
	v_exp_f32_e32 v163, v163
	v_exp_f32_e32 v164, v164
	v_exp_f32_e32 v165, v165
	v_exp_f32_e32 v166, v166
	v_exp_f32_e32 v168, v168
	v_cndmask_b32_e64 v17, v69, v17, s[0:1]
	v_cndmask_b32_e32 v44, v68, v44, vcc
	v_exp_f32_e32 v175, v121
	v_mul_f32_e32 v114, 0xbfb8aa3b, v172
	v_exp_f32_e32 v172, v111
	v_mul_f32_e32 v111, 0xbfb8aa3b, v115
	v_add_f32_e32 v115, 1.0, v147
	v_add_f32_e32 v121, 1.0, v148
	v_add_f32_e32 v147, 1.0, v153
	v_add_f32_e32 v146, 1.0, v146
	v_add_f32_e32 v148, 1.0, v154
	v_exp_f32_e32 v153, v109
	v_exp_f32_e32 v154, v113
	v_rsq_f32_e32 v17, v17
	v_rsq_f32_e32 v68, v44
	v_add_f32_e32 v28, 1.0, v28
	v_add_f32_e32 v91, 1.0, v91
	v_exp_f32_e32 v156, v114
	v_exp_f32_e32 v177, v111
	v_rcp_f32_e32 v112, v121
	v_rcp_f32_e32 v113, v122
	v_rcp_f32_e32 v121, v141
	v_rcp_f32_e32 v122, v147
	v_rcp_f32_e32 v123, v146
	v_rcp_f32_e32 v109, v28
	v_add_f32_e32 v139, 1.0, v157
	v_rcp_f32_e32 v111, v115
	v_add_f32_e32 v115, 1.0, v158
	v_add_f32_e32 v158, 1.0, v160
	v_rcp_f32_e32 v28, v127
	v_rcp_f32_e32 v114, v91
	v_add_f32_e32 v91, 1.0, v162
	v_rcp_f32_e32 v126, v148
	v_rcp_f32_e32 v127, v149
	v_add_f32_e32 v157, 1.0, v159
	v_add_f32_e32 v160, 1.0, v161
	v_rcp_f32_e32 v135, v139
	v_rcp_f32_e32 v139, v115
	v_rcp_f32_e32 v141, v158
	v_rcp_f32_e32 v115, v91
	v_add_f32_e32 v91, 1.0, v144
	v_add_f32_e32 v137, 1.0, v145
	v_add_f32_e32 v144, 1.0, v163
	v_add_f32_e32 v145, 1.0, v164
	v_add_f32_e32 v146, 1.0, v165
	v_add_f32_e32 v147, 1.0, v166
	v_add_f32_e32 v148, 1.0, v168
	v_add_f32_e32 v158, 1.0, v169
	v_rcp_f32_e32 v159, v140
	v_rcp_f32_e32 v140, v157
	v_rcp_f32_e32 v157, v160
	v_add_f32_e32 v149, 1.0, v167
	v_add_f32_e32 v160, 1.0, v170
	v_rcp_f32_e32 v136, v91
	v_rcp_f32_e32 v137, v137
	v_rcp_f32_e32 v144, v144
	v_rcp_f32_e32 v145, v145
	v_rcp_f32_e32 v146, v146
	v_rcp_f32_e32 v147, v147
	v_rcp_f32_e32 v104, v148
	v_rcp_f32_e32 v148, v158
	v_add_f32_e32 v91, 1.0, v152
	v_add_f32_e32 v158, 1.0, v153
	v_add_f32_e32 v154, 1.0, v154
	v_add_f32_e32 v155, 1.0, v155
	v_mul_f32_e32 v44, 0x45800000, v17
	v_mul_f32_e32 v69, 0x45800000, v68
	v_add_f32_e32 v161, 1.0, v175
	v_add_f32_e32 v162, 1.0, v171
	v_rcp_f32_e32 v105, v149
	v_rcp_f32_e32 v149, v160
	v_add_f32_e32 v156, 1.0, v156
	v_add_f32_e32 v160, 1.0, v177
	v_pk_mul_f32 v[70:71], v[120:121], v[70:71]
	v_pk_mul_f32 v[76:77], v[122:123], v[76:77]
	v_rcp_f32_e32 v120, v91
	v_rcp_f32_e32 v121, v158
	v_rcp_f32_e32 v122, v154
	v_rcp_f32_e32 v123, v155
	v_cndmask_b32_e64 v44, v17, v44, s[0:1]
	v_cndmask_b32_e32 v68, v68, v69, vcc
	v_add_f32_e32 v163, 1.0, v176
	v_add_f32_e32 v164, 1.0, v172
	v_rcp_f32_e32 v150, v161
	v_rcp_f32_e32 v151, v162
	v_pk_mul_f32 v[78:79], v[126:127], v[78:79]
	v_rcp_f32_e32 v126, v156
	v_rcp_f32_e32 v127, v160
	v_pk_mul_f32 v[72:73], v[106:107], v[44:45] op_sel_hi:[1,0]
	v_pk_mul_f32 v[82:83], v[94:95], v[44:45] op_sel_hi:[1,0]
	v_pk_mul_f32 v[92:93], v[98:99], v[44:45] op_sel_hi:[1,0]
	v_pk_mul_f32 v[94:95], v[96:97], v[44:45] op_sel_hi:[1,0]
	v_pk_mul_f32 v[66:67], v[66:67], v[44:45] op_sel_hi:[1,0]
	v_pk_mul_f32 v[64:65], v[64:65], v[44:45] op_sel_hi:[1,0]
	v_pk_mul_f32 v[62:63], v[62:63], v[44:45] op_sel_hi:[1,0]
	v_mul_f32_e32 v17, v61, v44
	v_mul_f32_e32 v44, v60, v44
	v_mul_f32_e32 v91, v68, v49
	v_mov_b32_e32 v49, v68
	v_rcp_f32_e32 v152, v163
	v_rcp_f32_e32 v153, v164
	v_pk_mul_f32 v[58:59], v[68:69], v[58:59] op_sel_hi:[0,1]
	v_pk_mul_f32 v[18:19], v[68:69], v[18:19] op_sel_hi:[0,1]
	v_pk_mul_f32 v[56:57], v[68:69], v[56:57] op_sel_hi:[0,1]
	v_mul_f32_e32 v44, v3, v44
	v_pk_mul_f32 v[22:23], v[48:49], v[22:23]
	v_pk_mul_f32 v[80:81], v[136:137], v[142:143]
	v_pk_mul_f32 v[102:103], v[144:145], v[102:103]
	v_pk_mul_f32 v[116:117], v[146:147], v[116:117]
	v_pk_mul_f32 v[20:21], v[68:69], v[20:21] op_sel_hi:[0,1]
	v_pk_mul_f32 v[54:55], v[68:69], v[54:55] op_sel_hi:[0,1]
	v_pk_mul_f32 v[52:53], v[68:69], v[52:53] op_sel_hi:[0,1]
	v_pk_mul_f32 v[50:51], v[68:69], v[50:51] op_sel_hi:[0,1]
	v_pk_mul_f32 v[60:61], v[12:13], v[72:73]
	v_pk_mul_f32 v[68:69], v[14:15], v[82:83]
	v_pk_mul_f32 v[72:73], v[8:9], v[92:93]
	v_pk_mul_f32 v[62:63], v[0:1], v[62:63]
	v_pk_mul_f32 v[16:17], v[28:29], v[16:17]
	v_pk_mul_f32 v[58:59], v[30:31], v[58:59]
	v_pk_mul_f32 v[18:19], v[32:33], v[18:19]
	v_pk_mul_f32 v[56:57], v[34:35], v[56:57]
	v_pk_mul_f32 v[22:23], v[44:45], v[22:23]
	v_pk_mul_f32 v[74:75], v[132:133], v[130:131]
	v_pk_mul_f32 v[82:83], v[10:11], v[94:95]
	v_pk_mul_f32 v[66:67], v[4:5], v[66:67]
	v_pk_mul_f32 v[64:65], v[6:7], v[64:65]
	v_pk_mul_f32 v[20:21], v[36:37], v[20:21]
	v_pk_mul_f32 v[54:55], v[38:39], v[54:55]
	v_pk_mul_f32 v[52:53], v[40:41], v[52:53]
	v_pk_mul_f32 v[50:51], v[42:43], v[50:51]
	v_mul_f32_e32 v28, v2, v91
	v_pk_mul_f32 v[48:49], v[116:117], v[60:61]
	v_pk_mul_f32 v[60:61], v[102:103], v[68:69]
	v_pk_mul_f32 v[68:69], v[80:81], v[72:73]
	v_pk_mul_f32 v[62:63], v[70:71], v[62:63]
	v_mul_f32_e32 v70, v16, v17
	v_pk_mul_f32 v[16:17], v[84:85], v[58:59]
	v_pk_mul_f32 v[18:19], v[120:121], v[18:19]
	v_pk_mul_f32 v[56:57], v[122:123], v[56:57]
	v_pk_mul_f32 v[22:23], v[114:115], v[22:23]
	v_pk_mul_f32 v[72:73], v[74:75], v[82:83]
	v_pk_mul_f32 v[66:67], v[78:79], v[66:67]
	v_pk_mul_f32 v[64:65], v[76:77], v[64:65]
	v_pk_mul_f32 v[20:21], v[126:127], v[20:21]
	v_pk_mul_f32 v[54:55], v[134:135], v[54:55]
	v_pk_mul_f32 v[52:53], v[138:139], v[52:53]
	v_pk_mul_f32 v[50:51], v[140:141], v[50:51]
	v_mul_f32_e32 v58, v157, v28
	v_mul_f32_e32 v70, v159, v70
	v_pk_fma_f32 v[16:17], v[104:105], v[48:49], v[16:17]
	v_pk_fma_f32 v[18:19], v[148:149], v[60:61], v[18:19]
	v_pk_fma_f32 v[48:49], v[150:151], v[68:69], v[56:57]
	v_mov_b32_e32 v71, v22
	v_mov_b32_e32 v59, v23
	v_pk_fma_f32 v[20:21], v[152:153], v[72:73], v[20:21]
	v_pk_fma_f32 v[54:55], v[108:109], v[66:67], v[54:55]
	v_pk_fma_f32 v[52:53], v[110:111], v[64:65], v[52:53]
	v_pk_fma_f32 v[50:51], v[112:113], v[62:63], v[50:51]
	v_cvt_pk_bf16_f32 v16, v16, v17
	v_cvt_pk_bf16_f32 v17, v18, v19
	v_cvt_pk_bf16_f32 v18, v48, v49
	v_pk_add_f32 v[48:49], v[70:71], v[58:59]
	v_cvt_pk_bf16_f32 v19, v20, v21
	v_cvt_pk_bf16_f32 v20, v54, v55
	v_cvt_pk_bf16_f32 v21, v52, v53
	v_cvt_pk_bf16_f32 v22, v50, v51
	v_cvt_pk_bf16_f32 v23, v48, v49
	global_store_dwordx4 v[252:253], v[16:19], off offset:-16
	global_store_dwordx4 v[252:253], v[20:23], off
	s_branch .Lmp0_loop
.Lmp0_finalA:
	s_waitcnt vmcnt(11)
	v_lshlrev_b32_e32 v50, 16, v22
	s_waitcnt vmcnt(10)
	v_lshlrev_b32_e32 v58, 16, v16
	v_and_b32_e32 v59, 0xffff0000, v16
	s_waitcnt vmcnt(9)
	v_lshlrev_b32_e32 v83, 16, v63
	s_waitcnt vmcnt(8)
	v_lshlrev_b32_e32 v117, 16, v67
	v_and_b32_e32 v82, 0xffff0000, v63
	v_and_b32_e32 v116, 0xffff0000, v67
	s_waitcnt vmcnt(7)
	v_and_b32_e32 v63, 0xffff0000, v69
	s_waitcnt vmcnt(6)
	v_lshlrev_b32_e32 v16, 16, v75
	v_lshlrev_b32_e32 v85, 16, v71
	v_lshlrev_b32_e32 v118, 16, v66
	v_and_b32_e32 v119, 0xffff0000, v66
	v_lshlrev_b32_e32 v66, 16, v62
	v_and_b32_e32 v67, 0xffff0000, v62
	v_lshlrev_b32_e32 v76, 16, v73
	v_lshlrev_b32_e32 v128, 16, v64
	v_and_b32_e32 v129, 0xffff0000, v64
	v_lshlrev_b32_e32 v130, 16, v60
	v_and_b32_e32 v131, 0xffff0000, v60
	v_lshlrev_b32_e32 v78, 16, v72
	v_and_b32_e32 v79, 0xffff0000, v72
	v_mul_f32_e32 v137, 0xbfb8aa3b, v63
	s_waitcnt vmcnt(4)
	v_lshlrev_b32_e32 v142, 16, v99
	v_mul_f32_e32 v143, 0xbfb8aa3b, v16
	v_mul_f32_e32 v85, 0xbfb8aa3b, v85
	v_and_b32_e32 v144, 0xffff0000, v99
	v_pk_add_f32 v[62:63], v[118:119], v[66:67]
	v_mul_f32_e32 v145, 0xbfb8aa3b, v76
	v_pk_add_f32 v[66:67], v[128:129], v[130:131]
	v_mul_f32_e32 v130, 0xbfb8aa3b, v78
	v_mul_f32_e32 v131, 0xbfb8aa3b, v79
	v_and_b32_e32 v51, 0xffff0000, v22
	v_and_b32_e32 v81, 0xffff0000, v70
	v_and_b32_e32 v22, 0xffff0000, v75
	v_lshlrev_b32_e32 v124, 16, v61
	v_and_b32_e32 v125, 0xffff0000, v61
	v_and_b32_e32 v77, 0xffff0000, v73
	v_pk_add_f32 v[60:61], v[116:117], v[82:83]
	v_lshlrev_b32_e32 v73, 16, v96
	v_and_b32_e32 v75, 0xffff0000, v96
	v_lshlrev_b32_e32 v133, 16, v97
	v_and_b32_e32 v135, 0xffff0000, v97
	v_lshlrev_b32_e32 v139, 16, v98
	v_and_b32_e32 v141, 0xffff0000, v98
	v_lshlrev_b32_e32 v96, 16, v95
	v_and_b32_e32 v97, 0xffff0000, v95
	v_lshlrev_b32_e32 v98, 16, v94
	v_and_b32_e32 v99, 0xffff0000, v94
	v_lshlrev_b32_e32 v116, 16, v92
	v_and_b32_e32 v117, 0xffff0000, v92
	v_exp_f32_e32 v147, v137
	v_exp_f32_e32 v150, v143
	v_exp_f32_e32 v151, v85
	v_mul_f32_e32 v85, 0xbfb8aa3b, v142
	v_mul_f32_e32 v137, 0xbfb8aa3b, v144
	v_exp_f32_e32 v153, v145
	v_exp_f32_e32 v154, v130
	v_exp_f32_e32 v155, v131
	s_waitcnt vmcnt(3)
	v_lshlrev_b32_e32 v130, 16, v103
	v_and_b32_e32 v131, 0xffff0000, v103
	v_lshlrev_b32_e32 v142, 16, v102
	v_and_b32_e32 v143, 0xffff0000, v102
	v_lshlrev_b32_e32 v144, 16, v100
	v_and_b32_e32 v145, 0xffff0000, v100
	v_lshlrev_b32_e32 v52, 16, v21
	v_and_b32_e32 v53, 0xffff0000, v21
	v_mul_f32_e32 v81, 0xbfb8aa3b, v81
	v_lshlrev_b32_e32 v94, 16, v93
	v_and_b32_e32 v95, 0xffff0000, v93
	v_lshlrev_b32_e32 v102, 16, v101
	v_and_b32_e32 v103, 0xffff0000, v101
	v_pk_add_f32 v[96:97], v[96:97], v[130:131]
	s_waitcnt vmcnt(2)
	v_lshlrev_b32_e32 v130, 16, v107
	v_and_b32_e32 v131, 0xffff0000, v107
	v_pk_add_f32 v[98:99], v[98:99], v[142:143]
	v_lshlrev_b32_e32 v142, 16, v106
	v_and_b32_e32 v143, 0xffff0000, v106
	v_pk_add_f32 v[106:107], v[116:117], v[144:145]
	v_pk_mul_f32 v[126:127], v[52:53], v[52:53]
	v_mov_b32_e32 v140, v59
	v_exp_f32_e32 v149, v81
	v_mul_f32_e32 v81, 0xbfb8aa3b, v141
	v_pk_add_f32 v[94:95], v[94:95], v[102:103]
	v_lshlrev_b32_e32 v102, 16, v105
	v_and_b32_e32 v103, 0xffff0000, v105
	v_lshlrev_b32_e32 v116, 16, v104
	v_and_b32_e32 v117, 0xffff0000, v104
	s_waitcnt vmcnt(1)
	v_lshlrev_b32_e32 v104, 16, v108
	v_and_b32_e32 v105, 0xffff0000, v108
	v_mov_b32_e32 v141, v107
	v_lshlrev_b32_e32 v56, 16, v18
	v_and_b32_e32 v57, 0xffff0000, v18
	v_lshlrev_b32_e32 v18, 16, v17
	v_mov_b32_e32 v138, v58
	v_mov_b32_e32 v92, v126
	v_mul_f32_e32 v126, 0xbfb8aa3b, v133
	v_mul_f32_e32 v133, 0xbfb8aa3b, v135
	v_mul_f32_e32 v135, 0xbfb8aa3b, v139
	v_mov_b32_e32 v139, v106
	v_mul_f32_e32 v168, 0xbfb8aa3b, v104
	v_mul_f32_e32 v169, 0xbfb8aa3b, v105
	v_pk_mul_f32 v[104:105], v[140:141], v[140:141]
	v_lshlrev_b32_e32 v54, 16, v20
	v_and_b32_e32 v55, 0xffff0000, v20
	v_lshlrev_b32_e32 v20, 16, v19
	v_and_b32_e32 v21, 0xffff0000, v19
	v_and_b32_e32 v19, 0xffff0000, v17
	v_mov_b32_e32 v134, v18
	v_exp_f32_e32 v159, v135
	v_mov_b32_e32 v135, v94
	v_pk_fma_f32 v[104:105], v[138:139], v[138:139], v[104:105]
	v_mov_b32_e32 v136, v19
	v_exp_f32_e32 v162, v137
	v_mov_b32_e32 v137, v95
	v_pk_fma_f32 v[104:105], v[134:135], v[134:135], v[104:105]
	v_mov_b32_e32 v132, v56
	v_exp_f32_e32 v158, v133
	v_mov_b32_e32 v133, v98
	v_pk_fma_f32 v[104:105], v[136:137], v[136:137], v[104:105]
	v_mov_b32_e32 v84, v57
	v_exp_f32_e32 v161, v85
	v_mov_b32_e32 v85, v99
	v_pk_fma_f32 v[104:105], v[132:133], v[132:133], v[104:105]
	v_mov_b32_e32 v80, v20
	v_mul_f32_e32 v75, 0xbfb8aa3b, v75
	v_exp_f32_e32 v160, v81
	v_mov_b32_e32 v81, v96
	v_pk_fma_f32 v[84:85], v[84:85], v[84:85], v[104:105]
	v_lshlrev_b32_e32 v44, 16, v69
	v_lshlrev_b32_e32 v69, 16, v70
	v_and_b32_e32 v91, 0xffff0000, v71
	v_pk_mul_f32 v[120:121], v[50:51], v[50:51]
	v_lshlrev_b32_e32 v70, 16, v74
	v_and_b32_e32 v71, 0xffff0000, v74
	v_lshlrev_b32_e32 v122, 16, v65
	v_and_b32_e32 v123, 0xffff0000, v65
	v_mov_b32_e32 v74, v21
	v_exp_f32_e32 v157, v75
	v_mov_b32_e32 v75, v97
	v_pk_fma_f32 v[80:81], v[80:81], v[80:81], v[84:85]
	v_mov_b32_e32 v72, v54
	v_mul_f32_e32 v69, 0xbfb8aa3b, v69
	v_pk_add_f32 v[64:65], v[122:123], v[124:125]
	v_mov_b32_e32 v118, v120
	v_mul_f32_e32 v120, 0xbfb8aa3b, v73
	v_mov_b32_e32 v73, v66
	v_pk_fma_f32 v[74:75], v[74:75], v[74:75], v[80:81]
	v_lshlrev_b32_e32 v17, 16, v68
	v_and_b32_e32 v28, 0xffff0000, v68
	v_mov_b32_e32 v68, v55
	v_mul_f32_e32 v93, 0xbfb8aa3b, v22
	v_exp_f32_e32 v148, v69
	v_pk_mul_f32 v[128:129], v[64:65], v[64:65]
	v_mov_b32_e32 v69, v67
	v_pk_fma_f32 v[72:73], v[72:73], v[72:73], v[74:75]
	v_exp_f32_e32 v156, v93
	v_mov_b32_e32 v93, v128
	v_pk_fma_f32 v[68:69], v[68:69], v[68:69], v[72:73]
	v_lshlrev_b32_e32 v49, 16, v23
	v_and_b32_e32 v23, 0xffff0000, v23
	v_mul_f32_e32 v119, 0xbfb8aa3b, v71
	v_pk_mul_f32 v[124:125], v[62:63], v[62:63]
	v_mov_b32_e32 v128, v127
	v_pk_add_f32 v[68:69], v[92:93], v[68:69]
	v_mov_b32_e32 v48, v23
	v_exp_f32_e32 v152, v119
	v_mov_b32_e32 v119, v124
	v_pk_add_f32 v[68:69], v[128:129], v[68:69]
	v_pk_mul_f32 v[82:83], v[48:49], v[48:49]
	v_pk_mul_f32 v[122:123], v[60:61], v[60:61]
	v_mov_b32_e32 v124, v121
	v_pk_add_f32 v[68:69], v[118:119], v[68:69]
	v_mov_b32_e32 v100, v83
	v_mov_b32_e32 v101, v123
	v_pk_add_f32 v[68:69], v[124:125], v[68:69]
	v_mov_b32_e32 v83, v122
	v_pk_add_f32 v[68:69], v[100:101], v[68:69]
	v_mul_f32_e32 v17, 0xbfb8aa3b, v17
	v_pk_add_f32 v[68:69], v[82:83], v[68:69]
	ds_bpermute_b32 v73, v87, v69
	ds_bpermute_b32 v72, v87, v68
	v_mul_f32_e32 v44, 0xbfb8aa3b, v44
	v_mul_f32_e32 v48, 0xbfb8aa3b, v70
	v_exp_f32_e32 v17, v17
	v_exp_f32_e32 v44, v44
	s_waitcnt lgkmcnt(0)
	v_pk_add_f32 v[68:69], v[68:69], v[72:73]
	ds_bpermute_b32 v73, v88, v69
	ds_bpermute_b32 v72, v88, v68
	v_exp_f32_e32 v48, v48
	v_exp_f32_e32 v120, v120
	v_exp_f32_e32 v126, v126
	v_mul_f32_e32 v123, 0xbfb8aa3b, v130
	s_waitcnt lgkmcnt(0)
	v_pk_add_f32 v[68:69], v[68:69], v[72:73]
	ds_bpermute_b32 v73, v89, v69
	ds_bpermute_b32 v72, v89, v68
	v_mul_f32_e32 v127, 0xbfb8aa3b, v131
	s_waitcnt vmcnt(0)
	v_lshlrev_b32_e32 v167, 16, v112
	v_and_b32_e32 v112, 0xffff0000, v112
	v_lshlrev_b32_e32 v108, 16, v109
	s_waitcnt lgkmcnt(0)
	v_pk_add_f32 v[68:69], v[68:69], v[72:73]
	ds_bpermute_b32 v73, v90, v69
	ds_bpermute_b32 v72, v90, v68
	v_and_b32_e32 v109, 0xffff0000, v109
	v_lshlrev_b32_e32 v121, 16, v110
	v_and_b32_e32 v110, 0xffff0000, v110
	v_exp_f32_e32 v173, v123
	v_exp_f32_e32 v174, v127
	v_mul_f32_e32 v123, 0xbfb8aa3b, v167
	v_mul_f32_e32 v112, 0xbfb8aa3b, v112
	v_lshlrev_b32_e32 v122, 16, v111
	v_lshlrev_b32_e32 v170, 16, v113
	v_mul_f32_e32 v108, 0xbfb8aa3b, v108
	v_and_b32_e32 v113, 0xffff0000, v113
	v_mul_f32_e32 v109, 0xbfb8aa3b, v109
	v_lshlrev_b32_e32 v171, 16, v114
	v_and_b32_e32 v114, 0xffff0000, v114
	v_mul_f32_e32 v110, 0xbfb8aa3b, v110
	v_add_f32_e32 v127, 1.0, v150
	v_add_f32_e32 v140, 1.0, v151
	v_exp_f32_e32 v150, v123
	v_exp_f32_e32 v151, v112
	v_mul_f32_e32 v122, 0xbfb8aa3b, v122
	v_exp_f32_e32 v167, v169
	v_exp_f32_e32 v169, v108
	v_mul_f32_e32 v108, 0xbfb8aa3b, v170
	v_exp_f32_e32 v170, v109
	v_mul_f32_e32 v109, 0xbfb8aa3b, v113
	v_mul_f32_e32 v113, 0xbfb8aa3b, v171
	v_exp_f32_e32 v171, v110
	v_mul_f32_e32 v110, 0xbfb8aa3b, v114
	v_add_f32_e32 v17, 1.0, v17
	v_add_f32_e32 v44, 1.0, v44
	v_mul_f32_e32 v146, 0xbfb8aa3b, v77
	v_exp_f32_e32 v176, v122
	v_add_f32_e32 v122, 1.0, v149
	v_add_f32_e32 v48, 1.0, v48
	v_add_f32_e32 v141, 1.0, v152
	v_add_f32_e32 v149, 1.0, v155
	v_add_f32_e32 v138, 1.0, v156
	v_exp_f32_e32 v152, v108
	v_exp_f32_e32 v155, v110
	v_rcp_f32_e32 v108, v17
	v_add_f32_e32 v17, 1.0, v120
	v_rcp_f32_e32 v110, v44
	v_add_f32_e32 v44, 1.0, v126
	v_mul_f32_e32 v28, 0xbfb8aa3b, v28
	v_mul_f32_e32 v91, 0xbfb8aa3b, v91
	v_exp_f32_e32 v146, v146
	v_rcp_f32_e32 v120, v48
	v_rcp_f32_e32 v48, v138
	v_rcp_f32_e32 v134, v17
	v_rcp_f32_e32 v138, v44
	v_add_f32_e32 v17, 1.0, v173
	v_add_f32_e32 v44, 1.0, v174
	s_waitcnt lgkmcnt(0)
	v_pk_add_f32 v[68:69], v[68:69], v[72:73]
	v_exp_f32_e32 v28, v28
	v_exp_f32_e32 v91, v91
	v_rcp_f32_e32 v132, v17
	v_rcp_f32_e32 v133, v44
	v_add_f32_e32 v17, 1.0, v150
	v_add_f32_e32 v44, 1.0, v151
	v_pk_fma_f32 v[68:69], v[68:69], s[22:23], v[24:25] op_sel_hi:[1,0,1]
	v_and_b32_e32 v111, 0xffff0000, v111
	v_mul_f32_e32 v144, 0xbfb8aa3b, v142
	v_mul_f32_e32 v145, 0xbfb8aa3b, v143
	v_mul_f32_e32 v163, 0xbfb8aa3b, v102
	v_mul_f32_e32 v164, 0xbfb8aa3b, v103
	v_mul_f32_e32 v165, 0xbfb8aa3b, v116
	v_mul_f32_e32 v166, 0xbfb8aa3b, v117
	v_rcp_f32_e32 v84, v17
	v_rcp_f32_e32 v85, v44
	v_mul_f32_e32 v17, 0x4b800000, v69
	v_mul_f32_e32 v44, 0x4b800000, v68
	v_cmp_gt_f32_e32 vcc, s27, v68
	v_cmp_gt_f32_e64 s[0:1], s27, v69
	v_mul_f32_e32 v121, 0xbfb8aa3b, v121
	v_lshlrev_b32_e32 v172, 16, v115
	v_and_b32_e32 v115, 0xffff0000, v115
	v_mul_f32_e32 v111, 0xbfb8aa3b, v111
	v_exp_f32_e32 v144, v144
	v_exp_f32_e32 v145, v145
	v_exp_f32_e32 v163, v163
	v_exp_f32_e32 v164, v164
	v_exp_f32_e32 v165, v165
	v_exp_f32_e32 v166, v166
	v_exp_f32_e32 v168, v168
	v_cndmask_b32_e64 v17, v69, v17, s[0:1]
	v_cndmask_b32_e32 v44, v68, v44, vcc
	v_exp_f32_e32 v175, v121
	v_mul_f32_e32 v114, 0xbfb8aa3b, v172
	v_exp_f32_e32 v172, v111
	v_mul_f32_e32 v111, 0xbfb8aa3b, v115
	v_add_f32_e32 v115, 1.0, v147
	v_add_f32_e32 v121, 1.0, v148
	v_add_f32_e32 v147, 1.0, v153
	v_add_f32_e32 v146, 1.0, v146
	v_add_f32_e32 v148, 1.0, v154
	v_exp_f32_e32 v153, v109
	v_exp_f32_e32 v154, v113
	v_rsq_f32_e32 v17, v17
	v_rsq_f32_e32 v68, v44
	v_add_f32_e32 v28, 1.0, v28
	v_add_f32_e32 v91, 1.0, v91
	v_exp_f32_e32 v156, v114
	v_exp_f32_e32 v177, v111
	v_rcp_f32_e32 v112, v121
	v_rcp_f32_e32 v113, v122
	v_rcp_f32_e32 v121, v141
	v_rcp_f32_e32 v122, v147
	v_rcp_f32_e32 v123, v146
	v_rcp_f32_e32 v109, v28
	v_add_f32_e32 v139, 1.0, v157
	v_rcp_f32_e32 v111, v115
	v_add_f32_e32 v115, 1.0, v158
	v_add_f32_e32 v158, 1.0, v160
	v_rcp_f32_e32 v28, v127
	v_rcp_f32_e32 v114, v91
	v_add_f32_e32 v91, 1.0, v162
	v_rcp_f32_e32 v126, v148
	v_rcp_f32_e32 v127, v149
	v_add_f32_e32 v157, 1.0, v159
	v_add_f32_e32 v160, 1.0, v161
	v_rcp_f32_e32 v135, v139
	v_rcp_f32_e32 v139, v115
	v_rcp_f32_e32 v141, v158
	v_rcp_f32_e32 v115, v91
	v_add_f32_e32 v91, 1.0, v144
	v_add_f32_e32 v137, 1.0, v145
	v_add_f32_e32 v144, 1.0, v163
	v_add_f32_e32 v145, 1.0, v164
	v_add_f32_e32 v146, 1.0, v165
	v_add_f32_e32 v147, 1.0, v166
	v_add_f32_e32 v148, 1.0, v168
	v_add_f32_e32 v158, 1.0, v169
	v_rcp_f32_e32 v159, v140
	v_rcp_f32_e32 v140, v157
	v_rcp_f32_e32 v157, v160
	v_add_f32_e32 v149, 1.0, v167
	v_add_f32_e32 v160, 1.0, v170
	v_rcp_f32_e32 v136, v91
	v_rcp_f32_e32 v137, v137
	v_rcp_f32_e32 v144, v144
	v_rcp_f32_e32 v145, v145
	v_rcp_f32_e32 v146, v146
	v_rcp_f32_e32 v147, v147
	v_rcp_f32_e32 v104, v148
	v_rcp_f32_e32 v148, v158
	v_add_f32_e32 v91, 1.0, v152
	v_add_f32_e32 v158, 1.0, v153
	v_add_f32_e32 v154, 1.0, v154
	v_add_f32_e32 v155, 1.0, v155
	v_mul_f32_e32 v44, 0x45800000, v17
	v_mul_f32_e32 v69, 0x45800000, v68
	v_add_f32_e32 v161, 1.0, v175
	v_add_f32_e32 v162, 1.0, v171
	v_rcp_f32_e32 v105, v149
	v_rcp_f32_e32 v149, v160
	v_add_f32_e32 v156, 1.0, v156
	v_add_f32_e32 v160, 1.0, v177
	v_pk_mul_f32 v[70:71], v[120:121], v[70:71]
	v_pk_mul_f32 v[76:77], v[122:123], v[76:77]
	v_rcp_f32_e32 v120, v91
	v_rcp_f32_e32 v121, v158
	v_rcp_f32_e32 v122, v154
	v_rcp_f32_e32 v123, v155
	v_cndmask_b32_e64 v44, v17, v44, s[0:1]
	v_cndmask_b32_e32 v68, v68, v69, vcc
	v_add_f32_e32 v163, 1.0, v176
	v_add_f32_e32 v164, 1.0, v172
	v_rcp_f32_e32 v150, v161
	v_rcp_f32_e32 v151, v162
	v_pk_mul_f32 v[78:79], v[126:127], v[78:79]
	v_rcp_f32_e32 v126, v156
	v_rcp_f32_e32 v127, v160
	v_pk_mul_f32 v[72:73], v[106:107], v[44:45] op_sel_hi:[1,0]
	v_pk_mul_f32 v[82:83], v[94:95], v[44:45] op_sel_hi:[1,0]
	v_pk_mul_f32 v[92:93], v[98:99], v[44:45] op_sel_hi:[1,0]
	v_pk_mul_f32 v[94:95], v[96:97], v[44:45] op_sel_hi:[1,0]
	v_pk_mul_f32 v[66:67], v[66:67], v[44:45] op_sel_hi:[1,0]
	v_pk_mul_f32 v[64:65], v[64:65], v[44:45] op_sel_hi:[1,0]
	v_pk_mul_f32 v[62:63], v[62:63], v[44:45] op_sel_hi:[1,0]
	v_mul_f32_e32 v17, v61, v44
	v_mul_f32_e32 v44, v60, v44
	v_mul_f32_e32 v91, v68, v49
	v_mov_b32_e32 v49, v68
	v_rcp_f32_e32 v152, v163
	v_rcp_f32_e32 v153, v164
	v_pk_mul_f32 v[58:59], v[68:69], v[58:59] op_sel_hi:[0,1]
	v_pk_mul_f32 v[18:19], v[68:69], v[18:19] op_sel_hi:[0,1]
	v_pk_mul_f32 v[56:57], v[68:69], v[56:57] op_sel_hi:[0,1]
	v_mul_f32_e32 v44, v3, v44
	v_pk_mul_f32 v[22:23], v[48:49], v[22:23]
	v_pk_mul_f32 v[80:81], v[136:137], v[142:143]
	v_pk_mul_f32 v[102:103], v[144:145], v[102:103]
	v_pk_mul_f32 v[116:117], v[146:147], v[116:117]
	v_pk_mul_f32 v[20:21], v[68:69], v[20:21] op_sel_hi:[0,1]
	v_pk_mul_f32 v[54:55], v[68:69], v[54:55] op_sel_hi:[0,1]
	v_pk_mul_f32 v[52:53], v[68:69], v[52:53] op_sel_hi:[0,1]
	v_pk_mul_f32 v[50:51], v[68:69], v[50:51] op_sel_hi:[0,1]
	v_pk_mul_f32 v[60:61], v[12:13], v[72:73]
	v_pk_mul_f32 v[68:69], v[14:15], v[82:83]
	v_pk_mul_f32 v[72:73], v[8:9], v[92:93]
	v_pk_mul_f32 v[62:63], v[0:1], v[62:63]
	v_pk_mul_f32 v[16:17], v[28:29], v[16:17]
	v_pk_mul_f32 v[58:59], v[30:31], v[58:59]
	v_pk_mul_f32 v[18:19], v[32:33], v[18:19]
	v_pk_mul_f32 v[56:57], v[34:35], v[56:57]
	v_pk_mul_f32 v[22:23], v[44:45], v[22:23]
	v_pk_mul_f32 v[74:75], v[132:133], v[130:131]
	v_pk_mul_f32 v[82:83], v[10:11], v[94:95]
	v_pk_mul_f32 v[66:67], v[4:5], v[66:67]
	v_pk_mul_f32 v[64:65], v[6:7], v[64:65]
	v_pk_mul_f32 v[20:21], v[36:37], v[20:21]
	v_pk_mul_f32 v[54:55], v[38:39], v[54:55]
	v_pk_mul_f32 v[52:53], v[40:41], v[52:53]
	v_pk_mul_f32 v[50:51], v[42:43], v[50:51]
	v_mul_f32_e32 v28, v2, v91
	v_pk_mul_f32 v[48:49], v[116:117], v[60:61]
	v_pk_mul_f32 v[60:61], v[102:103], v[68:69]
	v_pk_mul_f32 v[68:69], v[80:81], v[72:73]
	v_pk_mul_f32 v[62:63], v[70:71], v[62:63]
	v_mul_f32_e32 v70, v16, v17
	v_pk_mul_f32 v[16:17], v[84:85], v[58:59]
	v_pk_mul_f32 v[18:19], v[120:121], v[18:19]
	v_pk_mul_f32 v[56:57], v[122:123], v[56:57]
	v_pk_mul_f32 v[22:23], v[114:115], v[22:23]
	v_pk_mul_f32 v[72:73], v[74:75], v[82:83]
	v_pk_mul_f32 v[66:67], v[78:79], v[66:67]
	v_pk_mul_f32 v[64:65], v[76:77], v[64:65]
	v_pk_mul_f32 v[20:21], v[126:127], v[20:21]
	v_pk_mul_f32 v[54:55], v[134:135], v[54:55]
	v_pk_mul_f32 v[52:53], v[138:139], v[52:53]
	v_pk_mul_f32 v[50:51], v[140:141], v[50:51]
	v_mul_f32_e32 v58, v157, v28
	v_mul_f32_e32 v70, v159, v70
	v_pk_fma_f32 v[16:17], v[104:105], v[48:49], v[16:17]
	v_pk_fma_f32 v[18:19], v[148:149], v[60:61], v[18:19]
	v_pk_fma_f32 v[48:49], v[150:151], v[68:69], v[56:57]
	v_mov_b32_e32 v71, v22
	v_mov_b32_e32 v59, v23
	v_pk_fma_f32 v[20:21], v[152:153], v[72:73], v[20:21]
	v_pk_fma_f32 v[54:55], v[108:109], v[66:67], v[54:55]
	v_pk_fma_f32 v[52:53], v[110:111], v[64:65], v[52:53]
	v_pk_fma_f32 v[50:51], v[112:113], v[62:63], v[50:51]
	v_cvt_pk_bf16_f32 v16, v16, v17
	v_cvt_pk_bf16_f32 v17, v18, v19
	v_cvt_pk_bf16_f32 v18, v48, v49
	v_pk_add_f32 v[48:49], v[70:71], v[58:59]
	v_cvt_pk_bf16_f32 v19, v20, v21
	v_cvt_pk_bf16_f32 v20, v54, v55
	v_cvt_pk_bf16_f32 v21, v52, v53
	v_cvt_pk_bf16_f32 v22, v50, v51
	v_cvt_pk_bf16_f32 v23, v48, v49
	global_store_dwordx4 v[252:253], v[16:19], off offset:-16
	global_store_dwordx4 v[252:253], v[20:23], off
	s_branch .Lmp0_done
.Lmp0_finalB:
	s_waitcnt vmcnt(11)
	v_lshlrev_b32_e32 v50, 16, v186
	s_waitcnt vmcnt(10)
	v_lshlrev_b32_e32 v58, 16, v180
	v_and_b32_e32 v59, 0xffff0000, v180
	s_waitcnt vmcnt(9)
	v_lshlrev_b32_e32 v83, 16, v191
	s_waitcnt vmcnt(8)
	v_lshlrev_b32_e32 v117, 16, v195
	v_and_b32_e32 v82, 0xffff0000, v191
	v_and_b32_e32 v116, 0xffff0000, v195
	s_waitcnt vmcnt(7)
	v_and_b32_e32 v191, 0xffff0000, v197
	s_waitcnt vmcnt(6)
	v_lshlrev_b32_e32 v180, 16, v223
	v_lshlrev_b32_e32 v85, 16, v199
	v_lshlrev_b32_e32 v118, 16, v194
	v_and_b32_e32 v119, 0xffff0000, v194
	v_lshlrev_b32_e32 v194, 16, v190
	v_and_b32_e32 v195, 0xffff0000, v190
	v_lshlrev_b32_e32 v76, 16, v221
	v_lshlrev_b32_e32 v128, 16, v192
	v_and_b32_e32 v129, 0xffff0000, v192
	v_lshlrev_b32_e32 v130, 16, v188
	v_and_b32_e32 v131, 0xffff0000, v188
	v_lshlrev_b32_e32 v78, 16, v220
	v_and_b32_e32 v79, 0xffff0000, v220
	v_mul_f32_e32 v137, 0xbfb8aa3b, v191
	s_waitcnt vmcnt(4)
	v_lshlrev_b32_e32 v142, 16, v231
	v_mul_f32_e32 v143, 0xbfb8aa3b, v180
	v_mul_f32_e32 v85, 0xbfb8aa3b, v85
	v_and_b32_e32 v144, 0xffff0000, v231
	v_pk_add_f32 v[190:191], v[118:119], v[194:195]
	v_mul_f32_e32 v145, 0xbfb8aa3b, v76
	v_pk_add_f32 v[194:195], v[128:129], v[130:131]
	v_mul_f32_e32 v130, 0xbfb8aa3b, v78
	v_mul_f32_e32 v131, 0xbfb8aa3b, v79
	v_and_b32_e32 v51, 0xffff0000, v186
	v_and_b32_e32 v81, 0xffff0000, v198
	v_and_b32_e32 v186, 0xffff0000, v223
	v_lshlrev_b32_e32 v124, 16, v189
	v_and_b32_e32 v125, 0xffff0000, v189
	v_and_b32_e32 v77, 0xffff0000, v221
	v_pk_add_f32 v[188:189], v[116:117], v[82:83]
	v_lshlrev_b32_e32 v221, 16, v228
	v_and_b32_e32 v223, 0xffff0000, v228
	v_lshlrev_b32_e32 v133, 16, v229
	v_and_b32_e32 v135, 0xffff0000, v229
	v_lshlrev_b32_e32 v139, 16, v230
	v_and_b32_e32 v141, 0xffff0000, v230
	v_lshlrev_b32_e32 v228, 16, v227
	v_and_b32_e32 v229, 0xffff0000, v227
	v_lshlrev_b32_e32 v230, 16, v226
	v_and_b32_e32 v231, 0xffff0000, v226
	v_lshlrev_b32_e32 v116, 16, v224
	v_and_b32_e32 v117, 0xffff0000, v224
	v_exp_f32_e32 v147, v137
	v_exp_f32_e32 v150, v143
	v_exp_f32_e32 v151, v85
	v_mul_f32_e32 v85, 0xbfb8aa3b, v142
	v_mul_f32_e32 v137, 0xbfb8aa3b, v144
	v_exp_f32_e32 v153, v145
	v_exp_f32_e32 v154, v130
	v_exp_f32_e32 v155, v131
	s_waitcnt vmcnt(3)
	v_lshlrev_b32_e32 v130, 16, v235
	v_and_b32_e32 v131, 0xffff0000, v235
	v_lshlrev_b32_e32 v142, 16, v234
	v_and_b32_e32 v143, 0xffff0000, v234
	v_lshlrev_b32_e32 v144, 16, v232
	v_and_b32_e32 v145, 0xffff0000, v232
	v_lshlrev_b32_e32 v52, 16, v185
	v_and_b32_e32 v53, 0xffff0000, v185
	v_mul_f32_e32 v81, 0xbfb8aa3b, v81
	v_lshlrev_b32_e32 v226, 16, v225
	v_and_b32_e32 v227, 0xffff0000, v225
	v_lshlrev_b32_e32 v234, 16, v233
	v_and_b32_e32 v235, 0xffff0000, v233
	v_pk_add_f32 v[228:229], v[228:229], v[130:131]
	s_waitcnt vmcnt(2)
	v_lshlrev_b32_e32 v130, 16, v243
	v_and_b32_e32 v131, 0xffff0000, v243
	v_pk_add_f32 v[230:231], v[230:231], v[142:143]
	v_lshlrev_b32_e32 v142, 16, v242
	v_and_b32_e32 v143, 0xffff0000, v242
	v_pk_add_f32 v[242:243], v[116:117], v[144:145]
	v_pk_mul_f32 v[126:127], v[52:53], v[52:53]
	v_mov_b32_e32 v140, v59
	v_exp_f32_e32 v149, v81
	v_mul_f32_e32 v81, 0xbfb8aa3b, v141
	v_pk_add_f32 v[226:227], v[226:227], v[234:235]
	v_lshlrev_b32_e32 v234, 16, v241
	v_and_b32_e32 v235, 0xffff0000, v241
	v_lshlrev_b32_e32 v116, 16, v240
	v_and_b32_e32 v117, 0xffff0000, v240
	s_waitcnt vmcnt(1)
	v_lshlrev_b32_e32 v240, 16, v244
	v_and_b32_e32 v241, 0xffff0000, v244
	v_mov_b32_e32 v141, v243
	v_lshlrev_b32_e32 v56, 16, v182
	v_and_b32_e32 v57, 0xffff0000, v182
	v_lshlrev_b32_e32 v182, 16, v181
	v_mov_b32_e32 v138, v58
	v_mov_b32_e32 v224, v126
	v_mul_f32_e32 v126, 0xbfb8aa3b, v133
	v_mul_f32_e32 v133, 0xbfb8aa3b, v135
	v_mul_f32_e32 v135, 0xbfb8aa3b, v139
	v_mov_b32_e32 v139, v242
	v_mul_f32_e32 v168, 0xbfb8aa3b, v240
	v_mul_f32_e32 v169, 0xbfb8aa3b, v241
	v_pk_mul_f32 v[240:241], v[140:141], v[140:141]
	v_lshlrev_b32_e32 v54, 16, v184
	v_and_b32_e32 v55, 0xffff0000, v184
	v_lshlrev_b32_e32 v184, 16, v183
	v_and_b32_e32 v185, 0xffff0000, v183
	v_and_b32_e32 v183, 0xffff0000, v181
	v_mov_b32_e32 v134, v182
	v_exp_f32_e32 v159, v135
	v_mov_b32_e32 v135, v226
	v_pk_fma_f32 v[240:241], v[138:139], v[138:139], v[240:241]
	v_mov_b32_e32 v136, v183
	v_exp_f32_e32 v162, v137
	v_mov_b32_e32 v137, v227
	v_pk_fma_f32 v[240:241], v[134:135], v[134:135], v[240:241]
	v_mov_b32_e32 v132, v56
	v_exp_f32_e32 v158, v133
	v_mov_b32_e32 v133, v230
	v_pk_fma_f32 v[240:241], v[136:137], v[136:137], v[240:241]
	v_mov_b32_e32 v84, v57
	v_exp_f32_e32 v161, v85
	v_mov_b32_e32 v85, v231
	v_pk_fma_f32 v[240:241], v[132:133], v[132:133], v[240:241]
	v_mov_b32_e32 v80, v184
	v_mul_f32_e32 v223, 0xbfb8aa3b, v223
	v_exp_f32_e32 v160, v81
	v_mov_b32_e32 v81, v228
	v_pk_fma_f32 v[84:85], v[84:85], v[84:85], v[240:241]
	v_lshlrev_b32_e32 v44, 16, v197
	v_lshlrev_b32_e32 v197, 16, v198
	v_and_b32_e32 v91, 0xffff0000, v199
	v_pk_mul_f32 v[120:121], v[50:51], v[50:51]
	v_lshlrev_b32_e32 v198, 16, v222
	v_and_b32_e32 v199, 0xffff0000, v222
	v_lshlrev_b32_e32 v122, 16, v193
	v_and_b32_e32 v123, 0xffff0000, v193
	v_mov_b32_e32 v222, v185
	v_exp_f32_e32 v157, v223
	v_mov_b32_e32 v223, v229
	v_pk_fma_f32 v[80:81], v[80:81], v[80:81], v[84:85]
	v_mov_b32_e32 v220, v54
	v_mul_f32_e32 v197, 0xbfb8aa3b, v197
	v_pk_add_f32 v[192:193], v[122:123], v[124:125]
	v_mov_b32_e32 v118, v120
	v_mul_f32_e32 v120, 0xbfb8aa3b, v221
	v_mov_b32_e32 v221, v194
	v_pk_fma_f32 v[222:223], v[222:223], v[222:223], v[80:81]
	v_lshlrev_b32_e32 v181, 16, v196
	v_and_b32_e32 v28, 0xffff0000, v196
	v_mov_b32_e32 v196, v55
	v_mul_f32_e32 v225, 0xbfb8aa3b, v186
	v_exp_f32_e32 v148, v197
	v_pk_mul_f32 v[128:129], v[192:193], v[192:193]
	v_mov_b32_e32 v197, v195
	v_pk_fma_f32 v[220:221], v[220:221], v[220:221], v[222:223]
	v_exp_f32_e32 v156, v225
	v_mov_b32_e32 v225, v128
	v_pk_fma_f32 v[196:197], v[196:197], v[196:197], v[220:221]
	v_lshlrev_b32_e32 v49, 16, v187
	v_and_b32_e32 v187, 0xffff0000, v187
	v_mul_f32_e32 v119, 0xbfb8aa3b, v199
	v_pk_mul_f32 v[124:125], v[190:191], v[190:191]
	v_mov_b32_e32 v128, v127
	v_pk_add_f32 v[196:197], v[224:225], v[196:197]
	v_mov_b32_e32 v48, v187
	v_exp_f32_e32 v152, v119
	v_mov_b32_e32 v119, v124
	v_pk_add_f32 v[196:197], v[128:129], v[196:197]
	v_pk_mul_f32 v[82:83], v[48:49], v[48:49]
	v_pk_mul_f32 v[122:123], v[188:189], v[188:189]
	v_mov_b32_e32 v124, v121
	v_pk_add_f32 v[196:197], v[118:119], v[196:197]
	v_mov_b32_e32 v232, v83
	v_mov_b32_e32 v233, v123
	v_pk_add_f32 v[196:197], v[124:125], v[196:197]
	v_mov_b32_e32 v83, v122
	v_pk_add_f32 v[196:197], v[232:233], v[196:197]
	v_mul_f32_e32 v181, 0xbfb8aa3b, v181
	v_pk_add_f32 v[196:197], v[82:83], v[196:197]
	ds_bpermute_b32 v221, v87, v197
	ds_bpermute_b32 v220, v87, v196
	v_mul_f32_e32 v44, 0xbfb8aa3b, v44
	v_mul_f32_e32 v48, 0xbfb8aa3b, v198
	v_exp_f32_e32 v181, v181
	v_exp_f32_e32 v44, v44
	s_waitcnt lgkmcnt(0)
	v_pk_add_f32 v[196:197], v[196:197], v[220:221]
	ds_bpermute_b32 v221, v88, v197
	ds_bpermute_b32 v220, v88, v196
	v_exp_f32_e32 v48, v48
	v_exp_f32_e32 v120, v120
	v_exp_f32_e32 v126, v126
	v_mul_f32_e32 v123, 0xbfb8aa3b, v130
	s_waitcnt lgkmcnt(0)
	v_pk_add_f32 v[196:197], v[196:197], v[220:221]
	ds_bpermute_b32 v221, v89, v197
	ds_bpermute_b32 v220, v89, v196
	v_mul_f32_e32 v127, 0xbfb8aa3b, v131
	s_waitcnt vmcnt(0)
	v_lshlrev_b32_e32 v167, 16, v248
	v_and_b32_e32 v248, 0xffff0000, v248
	v_lshlrev_b32_e32 v244, 16, v245
	s_waitcnt lgkmcnt(0)
	v_pk_add_f32 v[196:197], v[196:197], v[220:221]
	ds_bpermute_b32 v221, v90, v197
	ds_bpermute_b32 v220, v90, v196
	v_and_b32_e32 v245, 0xffff0000, v245
	v_lshlrev_b32_e32 v121, 16, v246
	v_and_b32_e32 v246, 0xffff0000, v246
	v_exp_f32_e32 v173, v123
	v_exp_f32_e32 v174, v127
	v_mul_f32_e32 v123, 0xbfb8aa3b, v167
	v_mul_f32_e32 v248, 0xbfb8aa3b, v248
	v_lshlrev_b32_e32 v122, 16, v247
	v_lshlrev_b32_e32 v170, 16, v249
	v_mul_f32_e32 v244, 0xbfb8aa3b, v244
	v_and_b32_e32 v249, 0xffff0000, v249
	v_mul_f32_e32 v245, 0xbfb8aa3b, v245
	v_lshlrev_b32_e32 v171, 16, v250
	v_and_b32_e32 v250, 0xffff0000, v250
	v_mul_f32_e32 v246, 0xbfb8aa3b, v246
	v_add_f32_e32 v127, 1.0, v150
	v_add_f32_e32 v140, 1.0, v151
	v_exp_f32_e32 v150, v123
	v_exp_f32_e32 v151, v248
	v_mul_f32_e32 v122, 0xbfb8aa3b, v122
	v_exp_f32_e32 v167, v169
	v_exp_f32_e32 v169, v244
	v_mul_f32_e32 v244, 0xbfb8aa3b, v170
	v_exp_f32_e32 v170, v245
	v_mul_f32_e32 v245, 0xbfb8aa3b, v249
	v_mul_f32_e32 v249, 0xbfb8aa3b, v171
	v_exp_f32_e32 v171, v246
	v_mul_f32_e32 v246, 0xbfb8aa3b, v250
	v_add_f32_e32 v181, 1.0, v181
	v_add_f32_e32 v44, 1.0, v44
	v_mul_f32_e32 v146, 0xbfb8aa3b, v77
	v_exp_f32_e32 v176, v122
	v_add_f32_e32 v122, 1.0, v149
	v_add_f32_e32 v48, 1.0, v48
	v_add_f32_e32 v141, 1.0, v152
	v_add_f32_e32 v149, 1.0, v155
	v_add_f32_e32 v138, 1.0, v156
	v_exp_f32_e32 v152, v244
	v_exp_f32_e32 v155, v246
	v_rcp_f32_e32 v244, v181
	v_add_f32_e32 v181, 1.0, v120
	v_rcp_f32_e32 v246, v44
	v_add_f32_e32 v44, 1.0, v126
	v_mul_f32_e32 v28, 0xbfb8aa3b, v28
	v_mul_f32_e32 v91, 0xbfb8aa3b, v91
	v_exp_f32_e32 v146, v146
	v_rcp_f32_e32 v120, v48
	v_rcp_f32_e32 v48, v138
	v_rcp_f32_e32 v134, v181
	v_rcp_f32_e32 v138, v44
	v_add_f32_e32 v181, 1.0, v173
	v_add_f32_e32 v44, 1.0, v174
	s_waitcnt lgkmcnt(0)
	v_pk_add_f32 v[196:197], v[196:197], v[220:221]
	v_exp_f32_e32 v28, v28
	v_exp_f32_e32 v91, v91
	v_rcp_f32_e32 v132, v181
	v_rcp_f32_e32 v133, v44
	v_add_f32_e32 v181, 1.0, v150
	v_add_f32_e32 v44, 1.0, v151
	v_pk_fma_f32 v[196:197], v[196:197], s[22:23], v[24:25] op_sel_hi:[1,0,1]
	v_and_b32_e32 v247, 0xffff0000, v247
	v_mul_f32_e32 v144, 0xbfb8aa3b, v142
	v_mul_f32_e32 v145, 0xbfb8aa3b, v143
	v_mul_f32_e32 v163, 0xbfb8aa3b, v234
	v_mul_f32_e32 v164, 0xbfb8aa3b, v235
	v_mul_f32_e32 v165, 0xbfb8aa3b, v116
	v_mul_f32_e32 v166, 0xbfb8aa3b, v117
	v_rcp_f32_e32 v84, v181
	v_rcp_f32_e32 v85, v44
	v_mul_f32_e32 v181, 0x4b800000, v197
	v_mul_f32_e32 v44, 0x4b800000, v196
	v_cmp_gt_f32_e32 vcc, s27, v196
	v_cmp_gt_f32_e64 s[0:1], s27, v197
	v_mul_f32_e32 v121, 0xbfb8aa3b, v121
	v_lshlrev_b32_e32 v172, 16, v251
	v_and_b32_e32 v251, 0xffff0000, v251
	v_mul_f32_e32 v247, 0xbfb8aa3b, v247
	v_exp_f32_e32 v144, v144
	v_exp_f32_e32 v145, v145
	v_exp_f32_e32 v163, v163
	v_exp_f32_e32 v164, v164
	v_exp_f32_e32 v165, v165
	v_exp_f32_e32 v166, v166
	v_exp_f32_e32 v168, v168
	v_cndmask_b32_e64 v181, v197, v181, s[0:1]
	v_cndmask_b32_e32 v44, v196, v44, vcc
	v_exp_f32_e32 v175, v121
	v_mul_f32_e32 v250, 0xbfb8aa3b, v172
	v_exp_f32_e32 v172, v247
	v_mul_f32_e32 v247, 0xbfb8aa3b, v251
	v_add_f32_e32 v251, 1.0, v147
	v_add_f32_e32 v121, 1.0, v148
	v_add_f32_e32 v147, 1.0, v153
	v_add_f32_e32 v146, 1.0, v146
	v_add_f32_e32 v148, 1.0, v154
	v_exp_f32_e32 v153, v245
	v_exp_f32_e32 v154, v249
	v_rsq_f32_e32 v181, v181
	v_rsq_f32_e32 v196, v44
	v_add_f32_e32 v28, 1.0, v28
	v_add_f32_e32 v91, 1.0, v91
	v_exp_f32_e32 v156, v250
	v_exp_f32_e32 v177, v247
	v_rcp_f32_e32 v248, v121
	v_rcp_f32_e32 v249, v122
	v_rcp_f32_e32 v121, v141
	v_rcp_f32_e32 v122, v147
	v_rcp_f32_e32 v123, v146
	v_rcp_f32_e32 v245, v28
	v_add_f32_e32 v139, 1.0, v157
	v_rcp_f32_e32 v247, v251
	v_add_f32_e32 v251, 1.0, v158
	v_add_f32_e32 v158, 1.0, v160
	v_rcp_f32_e32 v28, v127
	v_rcp_f32_e32 v250, v91
	v_add_f32_e32 v91, 1.0, v162
	v_rcp_f32_e32 v126, v148
	v_rcp_f32_e32 v127, v149
	v_add_f32_e32 v157, 1.0, v159
	v_add_f32_e32 v160, 1.0, v161
	v_rcp_f32_e32 v135, v139
	v_rcp_f32_e32 v139, v251
	v_rcp_f32_e32 v141, v158
	v_rcp_f32_e32 v251, v91
	v_add_f32_e32 v91, 1.0, v144
	v_add_f32_e32 v137, 1.0, v145
	v_add_f32_e32 v144, 1.0, v163
	v_add_f32_e32 v145, 1.0, v164
	v_add_f32_e32 v146, 1.0, v165
	v_add_f32_e32 v147, 1.0, v166
	v_add_f32_e32 v148, 1.0, v168
	v_add_f32_e32 v158, 1.0, v169
	v_rcp_f32_e32 v159, v140
	v_rcp_f32_e32 v140, v157
	v_rcp_f32_e32 v157, v160
	v_add_f32_e32 v149, 1.0, v167
	v_add_f32_e32 v160, 1.0, v170
	v_rcp_f32_e32 v136, v91
	v_rcp_f32_e32 v137, v137
	v_rcp_f32_e32 v144, v144
	v_rcp_f32_e32 v145, v145
	v_rcp_f32_e32 v146, v146
	v_rcp_f32_e32 v147, v147
	v_rcp_f32_e32 v240, v148
	v_rcp_f32_e32 v148, v158
	v_add_f32_e32 v91, 1.0, v152
	v_add_f32_e32 v158, 1.0, v153
	v_add_f32_e32 v154, 1.0, v154
	v_add_f32_e32 v155, 1.0, v155
	v_mul_f32_e32 v44, 0x45800000, v181
	v_mul_f32_e32 v197, 0x45800000, v196
	v_add_f32_e32 v161, 1.0, v175
	v_add_f32_e32 v162, 1.0, v171
	v_rcp_f32_e32 v241, v149
	v_rcp_f32_e32 v149, v160
	v_add_f32_e32 v156, 1.0, v156
	v_add_f32_e32 v160, 1.0, v177
	v_pk_mul_f32 v[198:199], v[120:121], v[198:199]
	v_pk_mul_f32 v[76:77], v[122:123], v[76:77]
	v_rcp_f32_e32 v120, v91
	v_rcp_f32_e32 v121, v158
	v_rcp_f32_e32 v122, v154
	v_rcp_f32_e32 v123, v155
	v_cndmask_b32_e64 v44, v181, v44, s[0:1]
	v_cndmask_b32_e32 v196, v196, v197, vcc
	v_add_f32_e32 v163, 1.0, v176
	v_add_f32_e32 v164, 1.0, v172
	v_rcp_f32_e32 v150, v161
	v_rcp_f32_e32 v151, v162
	v_pk_mul_f32 v[78:79], v[126:127], v[78:79]
	v_rcp_f32_e32 v126, v156
	v_rcp_f32_e32 v127, v160
	v_pk_mul_f32 v[220:221], v[242:243], v[44:45] op_sel_hi:[1,0]
	v_pk_mul_f32 v[82:83], v[226:227], v[44:45] op_sel_hi:[1,0]
	v_pk_mul_f32 v[224:225], v[230:231], v[44:45] op_sel_hi:[1,0]
	v_pk_mul_f32 v[226:227], v[228:229], v[44:45] op_sel_hi:[1,0]
	v_pk_mul_f32 v[194:195], v[194:195], v[44:45] op_sel_hi:[1,0]
	v_pk_mul_f32 v[192:193], v[192:193], v[44:45] op_sel_hi:[1,0]
	v_pk_mul_f32 v[190:191], v[190:191], v[44:45] op_sel_hi:[1,0]
	v_mul_f32_e32 v181, v189, v44
	v_mul_f32_e32 v44, v188, v44
	v_mul_f32_e32 v91, v196, v49
	v_mov_b32_e32 v49, v196
	v_rcp_f32_e32 v152, v163
	v_rcp_f32_e32 v153, v164
	v_pk_mul_f32 v[58:59], v[196:197], v[58:59] op_sel_hi:[0,1]
	v_pk_mul_f32 v[182:183], v[196:197], v[182:183] op_sel_hi:[0,1]
	v_pk_mul_f32 v[56:57], v[196:197], v[56:57] op_sel_hi:[0,1]
	v_mul_f32_e32 v44, v3, v44
	v_pk_mul_f32 v[186:187], v[48:49], v[186:187]
	v_pk_mul_f32 v[80:81], v[136:137], v[142:143]
	v_pk_mul_f32 v[234:235], v[144:145], v[234:235]
	v_pk_mul_f32 v[116:117], v[146:147], v[116:117]
	v_pk_mul_f32 v[184:185], v[196:197], v[184:185] op_sel_hi:[0,1]
	v_pk_mul_f32 v[54:55], v[196:197], v[54:55] op_sel_hi:[0,1]
	v_pk_mul_f32 v[52:53], v[196:197], v[52:53] op_sel_hi:[0,1]
	v_pk_mul_f32 v[50:51], v[196:197], v[50:51] op_sel_hi:[0,1]
	v_pk_mul_f32 v[188:189], v[12:13], v[220:221]
	v_pk_mul_f32 v[196:197], v[14:15], v[82:83]
	v_pk_mul_f32 v[220:221], v[8:9], v[224:225]
	v_pk_mul_f32 v[190:191], v[0:1], v[190:191]
	v_pk_mul_f32 v[180:181], v[28:29], v[180:181]
	v_pk_mul_f32 v[58:59], v[30:31], v[58:59]
	v_pk_mul_f32 v[182:183], v[32:33], v[182:183]
	v_pk_mul_f32 v[56:57], v[34:35], v[56:57]
	v_pk_mul_f32 v[186:187], v[44:45], v[186:187]
	v_pk_mul_f32 v[222:223], v[132:133], v[130:131]
	v_pk_mul_f32 v[82:83], v[10:11], v[226:227]
	v_pk_mul_f32 v[194:195], v[4:5], v[194:195]
	v_pk_mul_f32 v[192:193], v[6:7], v[192:193]
	v_pk_mul_f32 v[184:185], v[36:37], v[184:185]
	v_pk_mul_f32 v[54:55], v[38:39], v[54:55]
	v_pk_mul_f32 v[52:53], v[40:41], v[52:53]
	v_pk_mul_f32 v[50:51], v[42:43], v[50:51]
	v_mul_f32_e32 v28, v2, v91
	v_pk_mul_f32 v[48:49], v[116:117], v[188:189]
	v_pk_mul_f32 v[188:189], v[234:235], v[196:197]
	v_pk_mul_f32 v[196:197], v[80:81], v[220:221]
	v_pk_mul_f32 v[190:191], v[198:199], v[190:191]
	v_mul_f32_e32 v198, v180, v181
	v_pk_mul_f32 v[180:181], v[84:85], v[58:59]
	v_pk_mul_f32 v[182:183], v[120:121], v[182:183]
	v_pk_mul_f32 v[56:57], v[122:123], v[56:57]
	v_pk_mul_f32 v[186:187], v[250:251], v[186:187]
	v_pk_mul_f32 v[220:221], v[222:223], v[82:83]
	v_pk_mul_f32 v[194:195], v[78:79], v[194:195]
	v_pk_mul_f32 v[192:193], v[76:77], v[192:193]
	v_pk_mul_f32 v[184:185], v[126:127], v[184:185]
	v_pk_mul_f32 v[54:55], v[134:135], v[54:55]
	v_pk_mul_f32 v[52:53], v[138:139], v[52:53]
	v_pk_mul_f32 v[50:51], v[140:141], v[50:51]
	v_mul_f32_e32 v58, v157, v28
	v_mul_f32_e32 v198, v159, v198
	v_pk_fma_f32 v[180:181], v[240:241], v[48:49], v[180:181]
	v_pk_fma_f32 v[182:183], v[148:149], v[188:189], v[182:183]
	v_pk_fma_f32 v[48:49], v[150:151], v[196:197], v[56:57]
	v_mov_b32_e32 v199, v186
	v_mov_b32_e32 v59, v187
	v_pk_fma_f32 v[184:185], v[152:153], v[220:221], v[184:185]
	v_pk_fma_f32 v[54:55], v[244:245], v[194:195], v[54:55]
	v_pk_fma_f32 v[52:53], v[246:247], v[192:193], v[52:53]
	v_pk_fma_f32 v[50:51], v[248:249], v[190:191], v[50:51]
	v_cvt_pk_bf16_f32 v180, v180, v181
	v_cvt_pk_bf16_f32 v181, v182, v183
	v_cvt_pk_bf16_f32 v182, v48, v49
	v_pk_add_f32 v[48:49], v[198:199], v[58:59]
	v_cvt_pk_bf16_f32 v183, v184, v185
	v_cvt_pk_bf16_f32 v184, v54, v55
	v_cvt_pk_bf16_f32 v185, v52, v53
	v_cvt_pk_bf16_f32 v186, v50, v51
	v_cvt_pk_bf16_f32 v187, v48, v49
	global_store_dwordx4 v[254:255], v[180:183], off offset:-16
	global_store_dwordx4 v[254:255], v[184:187], off
.Lmp0_done:
.LBB0_582:
	s_or_b64 exec, exec, s[6:7]

.LBB0_974:
	v_add_co_u32_e32 v48, vcc, 0xf8000000, v26
	v_lshl_add_u64 v[50:51], v[26:27], 0, s[12:13]
	v_lshl_add_u64 v[52:53], v[26:27], 0, s[14:15]
	v_addc_co_u32_e32 v49, vcc, -1, v27, vcc
	global_load_dwordx4 v[20:23], v[26:27], off
	global_load_dwordx4 v[16:19], v[26:27], off offset:-16
	v_lshl_add_u64 v[54:55], v[26:27], 0, s[16:17]
	v_lshl_add_u64 v[56:57], v[26:27], 0, s[18:19]
	global_load_dwordx4 v[60:63], v[52:53], off offset:16
	global_load_dwordx4 v[64:67], v[50:51], off offset:16
	global_load_dwordx4 v[68:71], v[56:57], off offset:16
	global_load_dwordx4 v[72:75], v[54:55], off offset:16
	v_add_co_u32_e32 v50, vcc, 0xfc000000, v26
	v_lshl_add_u64 v[46:47], v[26:27], 0, s[20:21]
	s_nop 0
	v_addc_co_u32_e32 v51, vcc, -1, v27, vcc
	v_add_co_u32_e32 v52, vcc, 0xdfc00000, v26
	global_load_dwordx4 v[92:95], v[48:49], off offset:-16
	global_load_dwordx4 v[96:99], v[46:47], off offset:16
	v_addc_co_u32_e32 v53, vcc, -1, v27, vcc
	v_add_co_u32_e32 v48, vcc, s3, v26
	global_load_dwordx4 v[100:103], v[50:51], off offset:-16
	global_load_dwordx4 v[104:107], v[52:53], off offset:-16
	v_addc_co_u32_e32 v49, vcc, -1, v27, vcc
	v_add_co_u32_e32 v50, vcc, s23, v26
	v_add_u32_e32 v86, s8, v86
	s_nop 0
	v_addc_co_u32_e32 v51, vcc, -1, v27, vcc
	global_load_dwordx4 v[108:111], v[48:49], off offset:-16
	global_load_dwordx4 v[112:115], v[50:51], off offset:-16
	v_add_co_u32_e32 v252, vcc, 0xcbc00000, v26
	v_cmp_lt_i32_e64 s[0:1], s28, v86
	s_nop 0
	v_addc_co_u32_e32 v253, vcc, -1, v27, vcc
	s_or_b64 s[10:11], s[0:1], s[10:11]
	v_lshl_add_u64 v[26:27], v[26:27], 0, s[24:25]
	s_cmp_lg_u64 s[10:11], 0
	s_cbranch_scc1 .Lmp1_finalA
	v_add_co_u32_e32 v48, vcc, 0xf8000000, v26
	v_lshl_add_u64 v[50:51], v[26:27], 0, s[12:13]
	v_lshl_add_u64 v[52:53], v[26:27], 0, s[14:15]
	v_addc_co_u32_e32 v49, vcc, -1, v27, vcc
	global_load_dwordx4 v[184:187], v[26:27], off
	global_load_dwordx4 v[180:183], v[26:27], off offset:-16
	v_lshl_add_u64 v[54:55], v[26:27], 0, s[16:17]
	v_lshl_add_u64 v[56:57], v[26:27], 0, s[18:19]
	global_load_dwordx4 v[188:191], v[52:53], off offset:16
	global_load_dwordx4 v[192:195], v[50:51], off offset:16
	global_load_dwordx4 v[196:199], v[56:57], off offset:16
	global_load_dwordx4 v[220:223], v[54:55], off offset:16
	v_add_co_u32_e32 v50, vcc, 0xfc000000, v26
	v_lshl_add_u64 v[46:47], v[26:27], 0, s[20:21]
	s_nop 0
	v_addc_co_u32_e32 v51, vcc, -1, v27, vcc
	v_add_co_u32_e32 v52, vcc, 0xdfc00000, v26
	global_load_dwordx4 v[224:227], v[48:49], off offset:-16
	global_load_dwordx4 v[228:231], v[46:47], off offset:16
	v_addc_co_u32_e32 v53, vcc, -1, v27, vcc
	v_add_co_u32_e32 v48, vcc, s3, v26
	global_load_dwordx4 v[232:235], v[50:51], off offset:-16
	global_load_dwordx4 v[240:243], v[52:53], off offset:-16
	v_addc_co_u32_e32 v49, vcc, -1, v27, vcc
	v_add_co_u32_e32 v50, vcc, s23, v26
	v_add_u32_e32 v86, s8, v86
	s_nop 0
	v_addc_co_u32_e32 v51, vcc, -1, v27, vcc
	global_load_dwordx4 v[244:247], v[48:49], off offset:-16
	global_load_dwordx4 v[248:251], v[50:51], off offset:-16
	v_add_co_u32_e32 v254, vcc, 0xcbc00000, v26
	v_cmp_lt_i32_e64 s[0:1], s28, v86
	s_nop 0
	v_addc_co_u32_e32 v255, vcc, -1, v27, vcc
	s_or_b64 s[10:11], s[0:1], s[10:11]
	v_lshl_add_u64 v[26:27], v[26:27], 0, s[24:25]
	s_waitcnt vmcnt(23)
	v_lshlrev_b32_e32 v50, 16, v22
	s_waitcnt vmcnt(22)
	v_lshlrev_b32_e32 v58, 16, v16
	v_and_b32_e32 v59, 0xffff0000, v16
	s_waitcnt vmcnt(21)
	v_lshlrev_b32_e32 v83, 16, v63
	s_waitcnt vmcnt(20)
	v_lshlrev_b32_e32 v117, 16, v67
	v_and_b32_e32 v82, 0xffff0000, v63
	v_and_b32_e32 v116, 0xffff0000, v67
	s_waitcnt vmcnt(19)
	v_and_b32_e32 v63, 0xffff0000, v69
	s_waitcnt vmcnt(18)
	v_lshlrev_b32_e32 v16, 16, v75
	v_lshlrev_b32_e32 v85, 16, v71
	v_lshlrev_b32_e32 v118, 16, v66
	v_and_b32_e32 v119, 0xffff0000, v66
	v_lshlrev_b32_e32 v66, 16, v62
	v_and_b32_e32 v67, 0xffff0000, v62
	v_lshlrev_b32_e32 v76, 16, v73
	v_lshlrev_b32_e32 v128, 16, v64
	v_and_b32_e32 v129, 0xffff0000, v64
	v_lshlrev_b32_e32 v130, 16, v60
	v_and_b32_e32 v131, 0xffff0000, v60
	v_lshlrev_b32_e32 v78, 16, v72
	v_and_b32_e32 v79, 0xffff0000, v72
	v_mul_f32_e32 v137, 0xbfb8aa3b, v63
	s_waitcnt vmcnt(16)
	v_lshlrev_b32_e32 v142, 16, v99
	v_mul_f32_e32 v143, 0xbfb8aa3b, v16
	v_mul_f32_e32 v85, 0xbfb8aa3b, v85
	v_and_b32_e32 v144, 0xffff0000, v99
	v_pk_add_f32 v[62:63], v[118:119], v[66:67]
	v_mul_f32_e32 v145, 0xbfb8aa3b, v76
	v_pk_add_f32 v[66:67], v[128:129], v[130:131]
	v_mul_f32_e32 v130, 0xbfb8aa3b, v78
	v_mul_f32_e32 v131, 0xbfb8aa3b, v79
	v_and_b32_e32 v51, 0xffff0000, v22
	v_and_b32_e32 v81, 0xffff0000, v70
	v_and_b32_e32 v22, 0xffff0000, v75
	v_lshlrev_b32_e32 v124, 16, v61
	v_and_b32_e32 v125, 0xffff0000, v61
	v_and_b32_e32 v77, 0xffff0000, v73
	v_pk_add_f32 v[60:61], v[116:117], v[82:83]
	v_lshlrev_b32_e32 v73, 16, v96
	v_and_b32_e32 v75, 0xffff0000, v96
	v_lshlrev_b32_e32 v133, 16, v97
	v_and_b32_e32 v135, 0xffff0000, v97
	v_lshlrev_b32_e32 v139, 16, v98
	v_and_b32_e32 v141, 0xffff0000, v98
	v_lshlrev_b32_e32 v96, 16, v95
	v_and_b32_e32 v97, 0xffff0000, v95
	v_lshlrev_b32_e32 v98, 16, v94
	v_and_b32_e32 v99, 0xffff0000, v94
	v_lshlrev_b32_e32 v116, 16, v92
	v_and_b32_e32 v117, 0xffff0000, v92
	v_exp_f32_e32 v147, v137
	v_exp_f32_e32 v150, v143
	v_exp_f32_e32 v151, v85
	v_mul_f32_e32 v85, 0xbfb8aa3b, v142
	v_mul_f32_e32 v137, 0xbfb8aa3b, v144
	v_exp_f32_e32 v153, v145
	v_exp_f32_e32 v154, v130
	v_exp_f32_e32 v155, v131
	s_waitcnt vmcnt(15)
	v_lshlrev_b32_e32 v130, 16, v103
	v_and_b32_e32 v131, 0xffff0000, v103
	v_lshlrev_b32_e32 v142, 16, v102
	v_and_b32_e32 v143, 0xffff0000, v102
	v_lshlrev_b32_e32 v144, 16, v100
	v_and_b32_e32 v145, 0xffff0000, v100
	v_lshlrev_b32_e32 v52, 16, v21
	v_and_b32_e32 v53, 0xffff0000, v21
	v_mul_f32_e32 v81, 0xbfb8aa3b, v81
	v_lshlrev_b32_e32 v94, 16, v93
	v_and_b32_e32 v95, 0xffff0000, v93
	v_lshlrev_b32_e32 v102, 16, v101
	v_and_b32_e32 v103, 0xffff0000, v101
	v_pk_add_f32 v[96:97], v[96:97], v[130:131]
	s_waitcnt vmcnt(14)
	v_lshlrev_b32_e32 v130, 16, v107
	v_and_b32_e32 v131, 0xffff0000, v107
	v_pk_add_f32 v[98:99], v[98:99], v[142:143]
	v_lshlrev_b32_e32 v142, 16, v106
	v_and_b32_e32 v143, 0xffff0000, v106
	v_pk_add_f32 v[106:107], v[116:117], v[144:145]
	v_pk_mul_f32 v[126:127], v[52:53], v[52:53]
	v_mov_b32_e32 v140, v59
	v_exp_f32_e32 v149, v81
	v_mul_f32_e32 v81, 0xbfb8aa3b, v141
	v_pk_add_f32 v[94:95], v[94:95], v[102:103]
	v_lshlrev_b32_e32 v102, 16, v105
	v_and_b32_e32 v103, 0xffff0000, v105
	v_lshlrev_b32_e32 v116, 16, v104
	v_and_b32_e32 v117, 0xffff0000, v104
	s_waitcnt vmcnt(13)
	v_lshlrev_b32_e32 v104, 16, v108
	v_and_b32_e32 v105, 0xffff0000, v108
	v_mov_b32_e32 v141, v107
	v_lshlrev_b32_e32 v56, 16, v18
	v_and_b32_e32 v57, 0xffff0000, v18
	v_lshlrev_b32_e32 v18, 16, v17
	v_mov_b32_e32 v138, v58
	v_mov_b32_e32 v92, v126
	v_mul_f32_e32 v126, 0xbfb8aa3b, v133
	v_mul_f32_e32 v133, 0xbfb8aa3b, v135
	v_mul_f32_e32 v135, 0xbfb8aa3b, v139
	v_mov_b32_e32 v139, v106
	v_mul_f32_e32 v168, 0xbfb8aa3b, v104
	v_mul_f32_e32 v169, 0xbfb8aa3b, v105
	v_pk_mul_f32 v[104:105], v[140:141], v[140:141]
	v_lshlrev_b32_e32 v54, 16, v20
	v_and_b32_e32 v55, 0xffff0000, v20
	v_lshlrev_b32_e32 v20, 16, v19
	v_and_b32_e32 v21, 0xffff0000, v19
	v_and_b32_e32 v19, 0xffff0000, v17
	v_mov_b32_e32 v134, v18
	v_exp_f32_e32 v159, v135
	v_mov_b32_e32 v135, v94
	v_pk_fma_f32 v[104:105], v[138:139], v[138:139], v[104:105]
	v_mov_b32_e32 v136, v19
	v_exp_f32_e32 v162, v137
	v_mov_b32_e32 v137, v95
	v_pk_fma_f32 v[104:105], v[134:135], v[134:135], v[104:105]
	v_mov_b32_e32 v132, v56
	v_exp_f32_e32 v158, v133
	v_mov_b32_e32 v133, v98
	v_pk_fma_f32 v[104:105], v[136:137], v[136:137], v[104:105]
	v_mov_b32_e32 v84, v57
	v_exp_f32_e32 v161, v85
	v_mov_b32_e32 v85, v99
	v_pk_fma_f32 v[104:105], v[132:133], v[132:133], v[104:105]
	v_mov_b32_e32 v80, v20
	v_mul_f32_e32 v75, 0xbfb8aa3b, v75
	v_exp_f32_e32 v160, v81
	v_mov_b32_e32 v81, v96
	v_pk_fma_f32 v[84:85], v[84:85], v[84:85], v[104:105]
	v_lshlrev_b32_e32 v44, 16, v69
	v_lshlrev_b32_e32 v69, 16, v70
	v_and_b32_e32 v91, 0xffff0000, v71
	v_pk_mul_f32 v[120:121], v[50:51], v[50:51]
	v_lshlrev_b32_e32 v70, 16, v74
	v_and_b32_e32 v71, 0xffff0000, v74
	v_lshlrev_b32_e32 v122, 16, v65
	v_and_b32_e32 v123, 0xffff0000, v65
	v_mov_b32_e32 v74, v21
	v_exp_f32_e32 v157, v75
	v_mov_b32_e32 v75, v97
	v_pk_fma_f32 v[80:81], v[80:81], v[80:81], v[84:85]
	v_mov_b32_e32 v72, v54
	v_mul_f32_e32 v69, 0xbfb8aa3b, v69
	v_pk_add_f32 v[64:65], v[122:123], v[124:125]
	v_mov_b32_e32 v118, v120
	v_mul_f32_e32 v120, 0xbfb8aa3b, v73
	v_mov_b32_e32 v73, v66
	v_pk_fma_f32 v[74:75], v[74:75], v[74:75], v[80:81]
	v_lshlrev_b32_e32 v17, 16, v68
	v_and_b32_e32 v28, 0xffff0000, v68
	v_mov_b32_e32 v68, v55
	v_mul_f32_e32 v93, 0xbfb8aa3b, v22
	v_exp_f32_e32 v148, v69
	v_pk_mul_f32 v[128:129], v[64:65], v[64:65]
	v_mov_b32_e32 v69, v67
	v_pk_fma_f32 v[72:73], v[72:73], v[72:73], v[74:75]
	v_exp_f32_e32 v156, v93
	v_mov_b32_e32 v93, v128
	v_pk_fma_f32 v[68:69], v[68:69], v[68:69], v[72:73]
	v_lshlrev_b32_e32 v49, 16, v23
	v_and_b32_e32 v23, 0xffff0000, v23
	v_mul_f32_e32 v119, 0xbfb8aa3b, v71
	v_pk_mul_f32 v[124:125], v[62:63], v[62:63]
	v_mov_b32_e32 v128, v127
	v_pk_add_f32 v[68:69], v[92:93], v[68:69]
	v_mov_b32_e32 v48, v23
	v_exp_f32_e32 v152, v119
	v_mov_b32_e32 v119, v124
	v_pk_add_f32 v[68:69], v[128:129], v[68:69]
	v_pk_mul_f32 v[82:83], v[48:49], v[48:49]
	v_pk_mul_f32 v[122:123], v[60:61], v[60:61]
	v_mov_b32_e32 v124, v121
	v_pk_add_f32 v[68:69], v[118:119], v[68:69]
	v_mov_b32_e32 v100, v83
	v_mov_b32_e32 v101, v123
	v_pk_add_f32 v[68:69], v[124:125], v[68:69]
	v_mov_b32_e32 v83, v122
	v_pk_add_f32 v[68:69], v[100:101], v[68:69]
	v_mul_f32_e32 v17, 0xbfb8aa3b, v17
	v_pk_add_f32 v[68:69], v[82:83], v[68:69]
	ds_bpermute_b32 v73, v87, v69
	ds_bpermute_b32 v72, v87, v68
	v_mul_f32_e32 v44, 0xbfb8aa3b, v44
	v_mul_f32_e32 v48, 0xbfb8aa3b, v70
	v_exp_f32_e32 v17, v17
	v_exp_f32_e32 v44, v44
	s_waitcnt lgkmcnt(0)
	v_pk_add_f32 v[68:69], v[68:69], v[72:73]
	ds_bpermute_b32 v73, v88, v69
	ds_bpermute_b32 v72, v88, v68
	v_exp_f32_e32 v48, v48
	v_exp_f32_e32 v120, v120
	v_exp_f32_e32 v126, v126
	v_mul_f32_e32 v123, 0xbfb8aa3b, v130
	s_waitcnt lgkmcnt(0)
	v_pk_add_f32 v[68:69], v[68:69], v[72:73]
	ds_bpermute_b32 v73, v89, v69
	ds_bpermute_b32 v72, v89, v68
	v_mul_f32_e32 v127, 0xbfb8aa3b, v131
	s_waitcnt vmcnt(12)
	v_lshlrev_b32_e32 v167, 16, v112
	v_and_b32_e32 v112, 0xffff0000, v112
	v_lshlrev_b32_e32 v108, 16, v109
	s_waitcnt lgkmcnt(0)
	v_pk_add_f32 v[68:69], v[68:69], v[72:73]
	ds_bpermute_b32 v73, v90, v69
	ds_bpermute_b32 v72, v90, v68
	v_and_b32_e32 v109, 0xffff0000, v109
	v_lshlrev_b32_e32 v121, 16, v110
	v_and_b32_e32 v110, 0xffff0000, v110
	v_exp_f32_e32 v173, v123
	v_exp_f32_e32 v174, v127
	v_mul_f32_e32 v123, 0xbfb8aa3b, v167
	v_mul_f32_e32 v112, 0xbfb8aa3b, v112
	v_lshlrev_b32_e32 v122, 16, v111
	v_lshlrev_b32_e32 v170, 16, v113
	v_mul_f32_e32 v108, 0xbfb8aa3b, v108
	v_and_b32_e32 v113, 0xffff0000, v113
	v_mul_f32_e32 v109, 0xbfb8aa3b, v109
	v_lshlrev_b32_e32 v171, 16, v114
	v_and_b32_e32 v114, 0xffff0000, v114
	v_mul_f32_e32 v110, 0xbfb8aa3b, v110
	v_add_f32_e32 v127, 1.0, v150
	v_add_f32_e32 v140, 1.0, v151
	v_exp_f32_e32 v150, v123
	v_exp_f32_e32 v151, v112
	v_mul_f32_e32 v122, 0xbfb8aa3b, v122
	v_exp_f32_e32 v167, v169
	v_exp_f32_e32 v169, v108
	v_mul_f32_e32 v108, 0xbfb8aa3b, v170
	v_exp_f32_e32 v170, v109
	v_mul_f32_e32 v109, 0xbfb8aa3b, v113
	v_mul_f32_e32 v113, 0xbfb8aa3b, v171
	v_exp_f32_e32 v171, v110
	v_mul_f32_e32 v110, 0xbfb8aa3b, v114
	v_add_f32_e32 v17, 1.0, v17
	v_add_f32_e32 v44, 1.0, v44
	v_mul_f32_e32 v146, 0xbfb8aa3b, v77
	v_exp_f32_e32 v176, v122
	v_add_f32_e32 v122, 1.0, v149
	v_add_f32_e32 v48, 1.0, v48
	v_add_f32_e32 v141, 1.0, v152
	v_add_f32_e32 v149, 1.0, v155
	v_add_f32_e32 v138, 1.0, v156
	v_exp_f32_e32 v152, v108
	v_exp_f32_e32 v155, v110
	v_rcp_f32_e32 v108, v17
	v_add_f32_e32 v17, 1.0, v120
	v_rcp_f32_e32 v110, v44
	v_add_f32_e32 v44, 1.0, v126
	v_mul_f32_e32 v28, 0xbfb8aa3b, v28
	v_mul_f32_e32 v91, 0xbfb8aa3b, v91
	v_exp_f32_e32 v146, v146
	v_rcp_f32_e32 v120, v48
	v_rcp_f32_e32 v48, v138
	v_rcp_f32_e32 v134, v17
	v_rcp_f32_e32 v138, v44
	v_add_f32_e32 v17, 1.0, v173
	v_add_f32_e32 v44, 1.0, v174
	s_waitcnt lgkmcnt(0)
	v_pk_add_f32 v[68:69], v[68:69], v[72:73]
	v_exp_f32_e32 v28, v28
	v_exp_f32_e32 v91, v91
	v_rcp_f32_e32 v132, v17
	v_rcp_f32_e32 v133, v44
	v_add_f32_e32 v17, 1.0, v150
	v_add_f32_e32 v44, 1.0, v151
	v_pk_fma_f32 v[68:69], v[68:69], s[22:23], v[24:25] op_sel_hi:[1,0,1]
	v_and_b32_e32 v111, 0xffff0000, v111
	v_mul_f32_e32 v144, 0xbfb8aa3b, v142
	v_mul_f32_e32 v145, 0xbfb8aa3b, v143
	v_mul_f32_e32 v163, 0xbfb8aa3b, v102
	v_mul_f32_e32 v164, 0xbfb8aa3b, v103
	v_mul_f32_e32 v165, 0xbfb8aa3b, v116
	v_mul_f32_e32 v166, 0xbfb8aa3b, v117
	v_rcp_f32_e32 v84, v17
	v_rcp_f32_e32 v85, v44
	v_mul_f32_e32 v17, 0x4b800000, v69
	v_mul_f32_e32 v44, 0x4b800000, v68
	v_cmp_gt_f32_e32 vcc, s27, v68
	v_cmp_gt_f32_e64 s[0:1], s27, v69
	v_mul_f32_e32 v121, 0xbfb8aa3b, v121
	v_lshlrev_b32_e32 v172, 16, v115
	v_and_b32_e32 v115, 0xffff0000, v115
	v_mul_f32_e32 v111, 0xbfb8aa3b, v111
	v_exp_f32_e32 v144, v144
	v_exp_f32_e32 v145, v145
	v_exp_f32_e32 v163, v163
	v_exp_f32_e32 v164, v164
	v_exp_f32_e32 v165, v165
	v_exp_f32_e32 v166, v166
	v_exp_f32_e32 v168, v168
	v_cndmask_b32_e64 v17, v69, v17, s[0:1]
	v_cndmask_b32_e32 v44, v68, v44, vcc
	v_exp_f32_e32 v175, v121
	v_mul_f32_e32 v114, 0xbfb8aa3b, v172
	v_exp_f32_e32 v172, v111
	v_mul_f32_e32 v111, 0xbfb8aa3b, v115
	v_add_f32_e32 v115, 1.0, v147
	v_add_f32_e32 v121, 1.0, v148
	v_add_f32_e32 v147, 1.0, v153
	v_add_f32_e32 v146, 1.0, v146
	v_add_f32_e32 v148, 1.0, v154
	v_exp_f32_e32 v153, v109
	v_exp_f32_e32 v154, v113
	v_rsq_f32_e32 v17, v17
	v_rsq_f32_e32 v68, v44
	v_add_f32_e32 v28, 1.0, v28
	v_add_f32_e32 v91, 1.0, v91
	v_exp_f32_e32 v156, v114
	v_exp_f32_e32 v177, v111
	v_rcp_f32_e32 v112, v121
	v_rcp_f32_e32 v113, v122
	v_rcp_f32_e32 v121, v141
	v_rcp_f32_e32 v122, v147
	v_rcp_f32_e32 v123, v146
	v_rcp_f32_e32 v109, v28
	v_add_f32_e32 v139, 1.0, v157
	v_rcp_f32_e32 v111, v115
	v_add_f32_e32 v115, 1.0, v158
	v_add_f32_e32 v158, 1.0, v160
	v_rcp_f32_e32 v28, v127
	v_rcp_f32_e32 v114, v91
	v_add_f32_e32 v91, 1.0, v162
	v_rcp_f32_e32 v126, v148
	v_rcp_f32_e32 v127, v149
	v_add_f32_e32 v157, 1.0, v159
	v_add_f32_e32 v160, 1.0, v161
	v_rcp_f32_e32 v135, v139
	v_rcp_f32_e32 v139, v115
	v_rcp_f32_e32 v141, v158
	v_rcp_f32_e32 v115, v91
	v_add_f32_e32 v91, 1.0, v144
	v_add_f32_e32 v137, 1.0, v145
	v_add_f32_e32 v144, 1.0, v163
	v_add_f32_e32 v145, 1.0, v164
	v_add_f32_e32 v146, 1.0, v165
	v_add_f32_e32 v147, 1.0, v166
	v_add_f32_e32 v148, 1.0, v168
	v_add_f32_e32 v158, 1.0, v169
	v_rcp_f32_e32 v159, v140
	v_rcp_f32_e32 v140, v157
	v_rcp_f32_e32 v157, v160
	v_add_f32_e32 v149, 1.0, v167
	v_add_f32_e32 v160, 1.0, v170
	v_rcp_f32_e32 v136, v91
	v_rcp_f32_e32 v137, v137
	v_rcp_f32_e32 v144, v144
	v_rcp_f32_e32 v145, v145
	v_rcp_f32_e32 v146, v146
	v_rcp_f32_e32 v147, v147
	v_rcp_f32_e32 v104, v148
	v_rcp_f32_e32 v148, v158
	v_add_f32_e32 v91, 1.0, v152
	v_add_f32_e32 v158, 1.0, v153
	v_add_f32_e32 v154, 1.0, v154
	v_add_f32_e32 v155, 1.0, v155
	v_mul_f32_e32 v44, 0x45800000, v17
	v_mul_f32_e32 v69, 0x45800000, v68
	v_add_f32_e32 v161, 1.0, v175
	v_add_f32_e32 v162, 1.0, v171
	v_rcp_f32_e32 v105, v149
	v_rcp_f32_e32 v149, v160
	v_add_f32_e32 v156, 1.0, v156
	v_add_f32_e32 v160, 1.0, v177
	v_pk_mul_f32 v[70:71], v[120:121], v[70:71]
	v_pk_mul_f32 v[76:77], v[122:123], v[76:77]
	v_rcp_f32_e32 v120, v91
	v_rcp_f32_e32 v121, v158
	v_rcp_f32_e32 v122, v154
	v_rcp_f32_e32 v123, v155
	v_cndmask_b32_e64 v44, v17, v44, s[0:1]
	v_cndmask_b32_e32 v68, v68, v69, vcc
	v_add_f32_e32 v163, 1.0, v176
	v_add_f32_e32 v164, 1.0, v172
	v_rcp_f32_e32 v150, v161
	v_rcp_f32_e32 v151, v162
	v_pk_mul_f32 v[78:79], v[126:127], v[78:79]
	v_rcp_f32_e32 v126, v156
	v_rcp_f32_e32 v127, v160
	v_pk_mul_f32 v[72:73], v[106:107], v[44:45] op_sel_hi:[1,0]
	v_pk_mul_f32 v[82:83], v[94:95], v[44:45] op_sel_hi:[1,0]
	v_pk_mul_f32 v[92:93], v[98:99], v[44:45] op_sel_hi:[1,0]
	v_pk_mul_f32 v[94:95], v[96:97], v[44:45] op_sel_hi:[1,0]
	v_pk_mul_f32 v[66:67], v[66:67], v[44:45] op_sel_hi:[1,0]
	v_pk_mul_f32 v[64:65], v[64:65], v[44:45] op_sel_hi:[1,0]
	v_pk_mul_f32 v[62:63], v[62:63], v[44:45] op_sel_hi:[1,0]
	v_mul_f32_e32 v17, v61, v44
	v_mul_f32_e32 v44, v60, v44
	v_mul_f32_e32 v91, v68, v49
	v_mov_b32_e32 v49, v68
	v_rcp_f32_e32 v152, v163
	v_rcp_f32_e32 v153, v164
	v_pk_mul_f32 v[58:59], v[68:69], v[58:59] op_sel_hi:[0,1]
	v_pk_mul_f32 v[18:19], v[68:69], v[18:19] op_sel_hi:[0,1]
	v_pk_mul_f32 v[56:57], v[68:69], v[56:57] op_sel_hi:[0,1]
	v_mul_f32_e32 v44, v3, v44
	v_pk_mul_f32 v[22:23], v[48:49], v[22:23]
	v_pk_mul_f32 v[80:81], v[136:137], v[142:143]
	v_pk_mul_f32 v[102:103], v[144:145], v[102:103]
	v_pk_mul_f32 v[116:117], v[146:147], v[116:117]
	v_pk_mul_f32 v[20:21], v[68:69], v[20:21] op_sel_hi:[0,1]
	v_pk_mul_f32 v[54:55], v[68:69], v[54:55] op_sel_hi:[0,1]
	v_pk_mul_f32 v[52:53], v[68:69], v[52:53] op_sel_hi:[0,1]
	v_pk_mul_f32 v[50:51], v[68:69], v[50:51] op_sel_hi:[0,1]
	v_pk_mul_f32 v[60:61], v[12:13], v[72:73]
	v_pk_mul_f32 v[68:69], v[14:15], v[82:83]
	v_pk_mul_f32 v[72:73], v[8:9], v[92:93]
	v_pk_mul_f32 v[62:63], v[0:1], v[62:63]
	v_pk_mul_f32 v[16:17], v[28:29], v[16:17]
	v_pk_mul_f32 v[58:59], v[30:31], v[58:59]
	v_pk_mul_f32 v[18:19], v[32:33], v[18:19]
	v_pk_mul_f32 v[56:57], v[34:35], v[56:57]
	v_pk_mul_f32 v[22:23], v[44:45], v[22:23]
	v_pk_mul_f32 v[74:75], v[132:133], v[130:131]
	v_pk_mul_f32 v[82:83], v[10:11], v[94:95]
	v_pk_mul_f32 v[66:67], v[4:5], v[66:67]
	v_pk_mul_f32 v[64:65], v[6:7], v[64:65]
	v_pk_mul_f32 v[20:21], v[36:37], v[20:21]
	v_pk_mul_f32 v[54:55], v[38:39], v[54:55]
	v_pk_mul_f32 v[52:53], v[40:41], v[52:53]
	v_pk_mul_f32 v[50:51], v[42:43], v[50:51]
	v_mul_f32_e32 v28, v2, v91
	v_pk_mul_f32 v[48:49], v[116:117], v[60:61]
	v_pk_mul_f32 v[60:61], v[102:103], v[68:69]
	v_pk_mul_f32 v[68:69], v[80:81], v[72:73]
	v_pk_mul_f32 v[62:63], v[70:71], v[62:63]
	v_mul_f32_e32 v70, v16, v17
	v_pk_mul_f32 v[16:17], v[84:85], v[58:59]
	v_pk_mul_f32 v[18:19], v[120:121], v[18:19]
	v_pk_mul_f32 v[56:57], v[122:123], v[56:57]
	v_pk_mul_f32 v[22:23], v[114:115], v[22:23]
	v_pk_mul_f32 v[72:73], v[74:75], v[82:83]
	v_pk_mul_f32 v[66:67], v[78:79], v[66:67]
	v_pk_mul_f32 v[64:65], v[76:77], v[64:65]
	v_pk_mul_f32 v[20:21], v[126:127], v[20:21]
	v_pk_mul_f32 v[54:55], v[134:135], v[54:55]
	v_pk_mul_f32 v[52:53], v[138:139], v[52:53]
	v_pk_mul_f32 v[50:51], v[140:141], v[50:51]
	v_mul_f32_e32 v58, v157, v28
	v_mul_f32_e32 v70, v159, v70
	v_pk_fma_f32 v[16:17], v[104:105], v[48:49], v[16:17]
	v_pk_fma_f32 v[18:19], v[148:149], v[60:61], v[18:19]
	v_pk_fma_f32 v[48:49], v[150:151], v[68:69], v[56:57]
	v_mov_b32_e32 v71, v22
	v_mov_b32_e32 v59, v23
	v_pk_fma_f32 v[20:21], v[152:153], v[72:73], v[20:21]
	v_pk_fma_f32 v[54:55], v[108:109], v[66:67], v[54:55]
	v_pk_fma_f32 v[52:53], v[110:111], v[64:65], v[52:53]
	v_pk_fma_f32 v[50:51], v[112:113], v[62:63], v[50:51]
	v_cvt_pk_bf16_f32 v16, v16, v17
	v_cvt_pk_bf16_f32 v17, v18, v19
	v_cvt_pk_bf16_f32 v18, v48, v49
	v_pk_add_f32 v[48:49], v[70:71], v[58:59]
	v_cvt_pk_bf16_f32 v19, v20, v21
	v_cvt_pk_bf16_f32 v20, v54, v55
	v_cvt_pk_bf16_f32 v21, v52, v53
	v_cvt_pk_bf16_f32 v22, v50, v51
	v_cvt_pk_bf16_f32 v23, v48, v49
	global_store_dwordx4 v[252:253], v[16:19], off offset:-16
	global_store_dwordx4 v[252:253], v[20:23], off
.Lmp1_loop:
	s_cmp_lg_u64 s[10:11], 0
	s_cbranch_scc1 .Lmp1_finalB
	v_add_co_u32_e32 v48, vcc, 0xf8000000, v26
	v_lshl_add_u64 v[50:51], v[26:27], 0, s[12:13]
	v_lshl_add_u64 v[52:53], v[26:27], 0, s[14:15]
	v_addc_co_u32_e32 v49, vcc, -1, v27, vcc
	global_load_dwordx4 v[20:23], v[26:27], off
	global_load_dwordx4 v[16:19], v[26:27], off offset:-16
	v_lshl_add_u64 v[54:55], v[26:27], 0, s[16:17]
	v_lshl_add_u64 v[56:57], v[26:27], 0, s[18:19]
	global_load_dwordx4 v[60:63], v[52:53], off offset:16
	global_load_dwordx4 v[64:67], v[50:51], off offset:16
	global_load_dwordx4 v[68:71], v[56:57], off offset:16
	global_load_dwordx4 v[72:75], v[54:55], off offset:16
	v_add_co_u32_e32 v50, vcc, 0xfc000000, v26
	v_lshl_add_u64 v[46:47], v[26:27], 0, s[20:21]
	s_nop 0
	v_addc_co_u32_e32 v51, vcc, -1, v27, vcc
	v_add_co_u32_e32 v52, vcc, 0xdfc00000, v26
	global_load_dwordx4 v[92:95], v[48:49], off offset:-16
	global_load_dwordx4 v[96:99], v[46:47], off offset:16
	v_addc_co_u32_e32 v53, vcc, -1, v27, vcc
	v_add_co_u32_e32 v48, vcc, s3, v26
	global_load_dwordx4 v[100:103], v[50:51], off offset:-16
	global_load_dwordx4 v[104:107], v[52:53], off offset:-16
	v_addc_co_u32_e32 v49, vcc, -1, v27, vcc
	v_add_co_u32_e32 v50, vcc, s23, v26
	v_add_u32_e32 v86, s8, v86
	s_nop 0
	v_addc_co_u32_e32 v51, vcc, -1, v27, vcc
	global_load_dwordx4 v[108:111], v[48:49], off offset:-16
	global_load_dwordx4 v[112:115], v[50:51], off offset:-16
	v_add_co_u32_e32 v252, vcc, 0xcbc00000, v26
	v_cmp_lt_i32_e64 s[0:1], s28, v86
	s_nop 0
	v_addc_co_u32_e32 v253, vcc, -1, v27, vcc
	s_or_b64 s[10:11], s[0:1], s[10:11]
	v_lshl_add_u64 v[26:27], v[26:27], 0, s[24:25]
	s_waitcnt vmcnt(25)
	v_lshlrev_b32_e32 v50, 16, v186
	s_waitcnt vmcnt(24)
	v_lshlrev_b32_e32 v58, 16, v180
	v_and_b32_e32 v59, 0xffff0000, v180
	s_waitcnt vmcnt(23)
	v_lshlrev_b32_e32 v83, 16, v191
	s_waitcnt vmcnt(22)
	v_lshlrev_b32_e32 v117, 16, v195
	v_and_b32_e32 v82, 0xffff0000, v191
	v_and_b32_e32 v116, 0xffff0000, v195
	s_waitcnt vmcnt(21)
	v_and_b32_e32 v191, 0xffff0000, v197
	s_waitcnt vmcnt(20)
	v_lshlrev_b32_e32 v180, 16, v223
	v_lshlrev_b32_e32 v85, 16, v199
	v_lshlrev_b32_e32 v118, 16, v194
	v_and_b32_e32 v119, 0xffff0000, v194
	v_lshlrev_b32_e32 v194, 16, v190
	v_and_b32_e32 v195, 0xffff0000, v190
	v_lshlrev_b32_e32 v76, 16, v221
	v_lshlrev_b32_e32 v128, 16, v192
	v_and_b32_e32 v129, 0xffff0000, v192
	v_lshlrev_b32_e32 v130, 16, v188
	v_and_b32_e32 v131, 0xffff0000, v188
	v_lshlrev_b32_e32 v78, 16, v220
	v_and_b32_e32 v79, 0xffff0000, v220
	v_mul_f32_e32 v137, 0xbfb8aa3b, v191
	s_waitcnt vmcnt(18)
	v_lshlrev_b32_e32 v142, 16, v231
	v_mul_f32_e32 v143, 0xbfb8aa3b, v180
	v_mul_f32_e32 v85, 0xbfb8aa3b, v85
	v_and_b32_e32 v144, 0xffff0000, v231
	v_pk_add_f32 v[190:191], v[118:119], v[194:195]
	v_mul_f32_e32 v145, 0xbfb8aa3b, v76
	v_pk_add_f32 v[194:195], v[128:129], v[130:131]
	v_mul_f32_e32 v130, 0xbfb8aa3b, v78
	v_mul_f32_e32 v131, 0xbfb8aa3b, v79
	v_and_b32_e32 v51, 0xffff0000, v186
	v_and_b32_e32 v81, 0xffff0000, v198
	v_and_b32_e32 v186, 0xffff0000, v223
	v_lshlrev_b32_e32 v124, 16, v189
	v_and_b32_e32 v125, 0xffff0000, v189
	v_and_b32_e32 v77, 0xffff0000, v221
	v_pk_add_f32 v[188:189], v[116:117], v[82:83]
	v_lshlrev_b32_e32 v221, 16, v228
	v_and_b32_e32 v223, 0xffff0000, v228
	v_lshlrev_b32_e32 v133, 16, v229
	v_and_b32_e32 v135, 0xffff0000, v229
	v_lshlrev_b32_e32 v139, 16, v230
	v_and_b32_e32 v141, 0xffff0000, v230
	v_lshlrev_b32_e32 v228, 16, v227
	v_and_b32_e32 v229, 0xffff0000, v227
	v_lshlrev_b32_e32 v230, 16, v226
	v_and_b32_e32 v231, 0xffff0000, v226
	v_lshlrev_b32_e32 v116, 16, v224
	v_and_b32_e32 v117, 0xffff0000, v224
	v_exp_f32_e32 v147, v137
	v_exp_f32_e32 v150, v143
	v_exp_f32_e32 v151, v85
	v_mul_f32_e32 v85, 0xbfb8aa3b, v142
	v_mul_f32_e32 v137, 0xbfb8aa3b, v144
	v_exp_f32_e32 v153, v145
	v_exp_f32_e32 v154, v130
	v_exp_f32_e32 v155, v131
	s_waitcnt vmcnt(17)
	v_lshlrev_b32_e32 v130, 16, v235
	v_and_b32_e32 v131, 0xffff0000, v235
	v_lshlrev_b32_e32 v142, 16, v234
	v_and_b32_e32 v143, 0xffff0000, v234
	v_lshlrev_b32_e32 v144, 16, v232
	v_and_b32_e32 v145, 0xffff0000, v232
	v_lshlrev_b32_e32 v52, 16, v185
	v_and_b32_e32 v53, 0xffff0000, v185
	v_mul_f32_e32 v81, 0xbfb8aa3b, v81
	v_lshlrev_b32_e32 v226, 16, v225
	v_and_b32_e32 v227, 0xffff0000, v225
	v_lshlrev_b32_e32 v234, 16, v233
	v_and_b32_e32 v235, 0xffff0000, v233
	v_pk_add_f32 v[228:229], v[228:229], v[130:131]
	s_waitcnt vmcnt(16)
	v_lshlrev_b32_e32 v130, 16, v243
	v_and_b32_e32 v131, 0xffff0000, v243
	v_pk_add_f32 v[230:231], v[230:231], v[142:143]
	v_lshlrev_b32_e32 v142, 16, v242
	v_and_b32_e32 v143, 0xffff0000, v242
	v_pk_add_f32 v[242:243], v[116:117], v[144:145]
	v_pk_mul_f32 v[126:127], v[52:53], v[52:53]
	v_mov_b32_e32 v140, v59
	v_exp_f32_e32 v149, v81
	v_mul_f32_e32 v81, 0xbfb8aa3b, v141
	v_pk_add_f32 v[226:227], v[226:227], v[234:235]
	v_lshlrev_b32_e32 v234, 16, v241
	v_and_b32_e32 v235, 0xffff0000, v241
	v_lshlrev_b32_e32 v116, 16, v240
	v_and_b32_e32 v117, 0xffff0000, v240
	s_waitcnt vmcnt(15)
	v_lshlrev_b32_e32 v240, 16, v244
	v_and_b32_e32 v241, 0xffff0000, v244
	v_mov_b32_e32 v141, v243
	v_lshlrev_b32_e32 v56, 16, v182
	v_and_b32_e32 v57, 0xffff0000, v182
	v_lshlrev_b32_e32 v182, 16, v181
	v_mov_b32_e32 v138, v58
	v_mov_b32_e32 v224, v126
	v_mul_f32_e32 v126, 0xbfb8aa3b, v133
	v_mul_f32_e32 v133, 0xbfb8aa3b, v135
	v_mul_f32_e32 v135, 0xbfb8aa3b, v139
	v_mov_b32_e32 v139, v242
	v_mul_f32_e32 v168, 0xbfb8aa3b, v240
	v_mul_f32_e32 v169, 0xbfb8aa3b, v241
	v_pk_mul_f32 v[240:241], v[140:141], v[140:141]
	v_lshlrev_b32_e32 v54, 16, v184
	v_and_b32_e32 v55, 0xffff0000, v184
	v_lshlrev_b32_e32 v184, 16, v183
	v_and_b32_e32 v185, 0xffff0000, v183
	v_and_b32_e32 v183, 0xffff0000, v181
	v_mov_b32_e32 v134, v182
	v_exp_f32_e32 v159, v135
	v_mov_b32_e32 v135, v226
	v_pk_fma_f32 v[240:241], v[138:139], v[138:139], v[240:241]
	v_mov_b32_e32 v136, v183
	v_exp_f32_e32 v162, v137
	v_mov_b32_e32 v137, v227
	v_pk_fma_f32 v[240:241], v[134:135], v[134:135], v[240:241]
	v_mov_b32_e32 v132, v56
	v_exp_f32_e32 v158, v133
	v_mov_b32_e32 v133, v230
	v_pk_fma_f32 v[240:241], v[136:137], v[136:137], v[240:241]
	v_mov_b32_e32 v84, v57
	v_exp_f32_e32 v161, v85
	v_mov_b32_e32 v85, v231
	v_pk_fma_f32 v[240:241], v[132:133], v[132:133], v[240:241]
	v_mov_b32_e32 v80, v184
	v_mul_f32_e32 v223, 0xbfb8aa3b, v223
	v_exp_f32_e32 v160, v81
	v_mov_b32_e32 v81, v228
	v_pk_fma_f32 v[84:85], v[84:85], v[84:85], v[240:241]
	v_lshlrev_b32_e32 v44, 16, v197
	v_lshlrev_b32_e32 v197, 16, v198
	v_and_b32_e32 v91, 0xffff0000, v199
	v_pk_mul_f32 v[120:121], v[50:51], v[50:51]
	v_lshlrev_b32_e32 v198, 16, v222
	v_and_b32_e32 v199, 0xffff0000, v222
	v_lshlrev_b32_e32 v122, 16, v193
	v_and_b32_e32 v123, 0xffff0000, v193
	v_mov_b32_e32 v222, v185
	v_exp_f32_e32 v157, v223
	v_mov_b32_e32 v223, v229
	v_pk_fma_f32 v[80:81], v[80:81], v[80:81], v[84:85]
	v_mov_b32_e32 v220, v54
	v_mul_f32_e32 v197, 0xbfb8aa3b, v197
	v_pk_add_f32 v[192:193], v[122:123], v[124:125]
	v_mov_b32_e32 v118, v120
	v_mul_f32_e32 v120, 0xbfb8aa3b, v221
	v_mov_b32_e32 v221, v194
	v_pk_fma_f32 v[222:223], v[222:223], v[222:223], v[80:81]
	v_lshlrev_b32_e32 v181, 16, v196
	v_and_b32_e32 v28, 0xffff0000, v196
	v_mov_b32_e32 v196, v55
	v_mul_f32_e32 v225, 0xbfb8aa3b, v186
	v_exp_f32_e32 v148, v197
	v_pk_mul_f32 v[128:129], v[192:193], v[192:193]
	v_mov_b32_e32 v197, v195
	v_pk_fma_f32 v[220:221], v[220:221], v[220:221], v[222:223]
	v_exp_f32_e32 v156, v225
	v_mov_b32_e32 v225, v128
	v_pk_fma_f32 v[196:197], v[196:197], v[196:197], v[220:221]
	v_lshlrev_b32_e32 v49, 16, v187
	v_and_b32_e32 v187, 0xffff0000, v187
	v_mul_f32_e32 v119, 0xbfb8aa3b, v199
	v_pk_mul_f32 v[124:125], v[190:191], v[190:191]
	v_mov_b32_e32 v128, v127
	v_pk_add_f32 v[196:197], v[224:225], v[196:197]
	v_mov_b32_e32 v48, v187
	v_exp_f32_e32 v152, v119
	v_mov_b32_e32 v119, v124
	v_pk_add_f32 v[196:197], v[128:129], v[196:197]
	v_pk_mul_f32 v[82:83], v[48:49], v[48:49]
	v_pk_mul_f32 v[122:123], v[188:189], v[188:189]
	v_mov_b32_e32 v124, v121
	v_pk_add_f32 v[196:197], v[118:119], v[196:197]
	v_mov_b32_e32 v232, v83
	v_mov_b32_e32 v233, v123
	v_pk_add_f32 v[196:197], v[124:125], v[196:197]
	v_mov_b32_e32 v83, v122
	v_pk_add_f32 v[196:197], v[232:233], v[196:197]
	v_mul_f32_e32 v181, 0xbfb8aa3b, v181
	v_pk_add_f32 v[196:197], v[82:83], v[196:197]
	ds_bpermute_b32 v221, v87, v197
	ds_bpermute_b32 v220, v87, v196
	v_mul_f32_e32 v44, 0xbfb8aa3b, v44
	v_mul_f32_e32 v48, 0xbfb8aa3b, v198
	v_exp_f32_e32 v181, v181
	v_exp_f32_e32 v44, v44
	s_waitcnt lgkmcnt(0)
	v_pk_add_f32 v[196:197], v[196:197], v[220:221]
	ds_bpermute_b32 v221, v88, v197
	ds_bpermute_b32 v220, v88, v196
	v_exp_f32_e32 v48, v48
	v_exp_f32_e32 v120, v120
	v_exp_f32_e32 v126, v126
	v_mul_f32_e32 v123, 0xbfb8aa3b, v130
	s_waitcnt lgkmcnt(0)
	v_pk_add_f32 v[196:197], v[196:197], v[220:221]
	ds_bpermute_b32 v221, v89, v197
	ds_bpermute_b32 v220, v89, v196
	v_mul_f32_e32 v127, 0xbfb8aa3b, v131
	s_waitcnt vmcnt(14)
	v_lshlrev_b32_e32 v167, 16, v248
	v_and_b32_e32 v248, 0xffff0000, v248
	v_lshlrev_b32_e32 v244, 16, v245
	s_waitcnt lgkmcnt(0)
	v_pk_add_f32 v[196:197], v[196:197], v[220:221]
	ds_bpermute_b32 v221, v90, v197
	ds_bpermute_b32 v220, v90, v196
	v_and_b32_e32 v245, 0xffff0000, v245
	v_lshlrev_b32_e32 v121, 16, v246
	v_and_b32_e32 v246, 0xffff0000, v246
	v_exp_f32_e32 v173, v123
	v_exp_f32_e32 v174, v127
	v_mul_f32_e32 v123, 0xbfb8aa3b, v167
	v_mul_f32_e32 v248, 0xbfb8aa3b, v248
	v_lshlrev_b32_e32 v122, 16, v247
	v_lshlrev_b32_e32 v170, 16, v249
	v_mul_f32_e32 v244, 0xbfb8aa3b, v244
	v_and_b32_e32 v249, 0xffff0000, v249
	v_mul_f32_e32 v245, 0xbfb8aa3b, v245
	v_lshlrev_b32_e32 v171, 16, v250
	v_and_b32_e32 v250, 0xffff0000, v250
	v_mul_f32_e32 v246, 0xbfb8aa3b, v246
	v_add_f32_e32 v127, 1.0, v150
	v_add_f32_e32 v140, 1.0, v151
	v_exp_f32_e32 v150, v123
	v_exp_f32_e32 v151, v248
	v_mul_f32_e32 v122, 0xbfb8aa3b, v122
	v_exp_f32_e32 v167, v169
	v_exp_f32_e32 v169, v244
	v_mul_f32_e32 v244, 0xbfb8aa3b, v170
	v_exp_f32_e32 v170, v245
	v_mul_f32_e32 v245, 0xbfb8aa3b, v249
	v_mul_f32_e32 v249, 0xbfb8aa3b, v171
	v_exp_f32_e32 v171, v246
	v_mul_f32_e32 v246, 0xbfb8aa3b, v250
	v_add_f32_e32 v181, 1.0, v181
	v_add_f32_e32 v44, 1.0, v44
	v_mul_f32_e32 v146, 0xbfb8aa3b, v77
	v_exp_f32_e32 v176, v122
	v_add_f32_e32 v122, 1.0, v149
	v_add_f32_e32 v48, 1.0, v48
	v_add_f32_e32 v141, 1.0, v152
	v_add_f32_e32 v149, 1.0, v155
	v_add_f32_e32 v138, 1.0, v156
	v_exp_f32_e32 v152, v244
	v_exp_f32_e32 v155, v246
	v_rcp_f32_e32 v244, v181
	v_add_f32_e32 v181, 1.0, v120
	v_rcp_f32_e32 v246, v44
	v_add_f32_e32 v44, 1.0, v126
	v_mul_f32_e32 v28, 0xbfb8aa3b, v28
	v_mul_f32_e32 v91, 0xbfb8aa3b, v91
	v_exp_f32_e32 v146, v146
	v_rcp_f32_e32 v120, v48
	v_rcp_f32_e32 v48, v138
	v_rcp_f32_e32 v134, v181
	v_rcp_f32_e32 v138, v44
	v_add_f32_e32 v181, 1.0, v173
	v_add_f32_e32 v44, 1.0, v174
	s_waitcnt lgkmcnt(0)
	v_pk_add_f32 v[196:197], v[196:197], v[220:221]
	v_exp_f32_e32 v28, v28
	v_exp_f32_e32 v91, v91
	v_rcp_f32_e32 v132, v181
	v_rcp_f32_e32 v133, v44
	v_add_f32_e32 v181, 1.0, v150
	v_add_f32_e32 v44, 1.0, v151
	v_pk_fma_f32 v[196:197], v[196:197], s[22:23], v[24:25] op_sel_hi:[1,0,1]
	v_and_b32_e32 v247, 0xffff0000, v247
	v_mul_f32_e32 v144, 0xbfb8aa3b, v142
	v_mul_f32_e32 v145, 0xbfb8aa3b, v143
	v_mul_f32_e32 v163, 0xbfb8aa3b, v234
	v_mul_f32_e32 v164, 0xbfb8aa3b, v235
	v_mul_f32_e32 v165, 0xbfb8aa3b, v116
	v_mul_f32_e32 v166, 0xbfb8aa3b, v117
	v_rcp_f32_e32 v84, v181
	v_rcp_f32_e32 v85, v44
	v_mul_f32_e32 v181, 0x4b800000, v197
	v_mul_f32_e32 v44, 0x4b800000, v196
	v_cmp_gt_f32_e32 vcc, s27, v196
	v_cmp_gt_f32_e64 s[0:1], s27, v197
	v_mul_f32_e32 v121, 0xbfb8aa3b, v121
	v_lshlrev_b32_e32 v172, 16, v251
	v_and_b32_e32 v251, 0xffff0000, v251
	v_mul_f32_e32 v247, 0xbfb8aa3b, v247
	v_exp_f32_e32 v144, v144
	v_exp_f32_e32 v145, v145
	v_exp_f32_e32 v163, v163
	v_exp_f32_e32 v164, v164
	v_exp_f32_e32 v165, v165
	v_exp_f32_e32 v166, v166
	v_exp_f32_e32 v168, v168
	v_cndmask_b32_e64 v181, v197, v181, s[0:1]
	v_cndmask_b32_e32 v44, v196, v44, vcc
	v_exp_f32_e32 v175, v121
	v_mul_f32_e32 v250, 0xbfb8aa3b, v172
	v_exp_f32_e32 v172, v247
	v_mul_f32_e32 v247, 0xbfb8aa3b, v251
	v_add_f32_e32 v251, 1.0, v147
	v_add_f32_e32 v121, 1.0, v148
	v_add_f32_e32 v147, 1.0, v153
	v_add_f32_e32 v146, 1.0, v146
	v_add_f32_e32 v148, 1.0, v154
	v_exp_f32_e32 v153, v245
	v_exp_f32_e32 v154, v249
	v_rsq_f32_e32 v181, v181
	v_rsq_f32_e32 v196, v44
	v_add_f32_e32 v28, 1.0, v28
	v_add_f32_e32 v91, 1.0, v91
	v_exp_f32_e32 v156, v250
	v_exp_f32_e32 v177, v247
	v_rcp_f32_e32 v248, v121
	v_rcp_f32_e32 v249, v122
	v_rcp_f32_e32 v121, v141
	v_rcp_f32_e32 v122, v147
	v_rcp_f32_e32 v123, v146
	v_rcp_f32_e32 v245, v28
	v_add_f32_e32 v139, 1.0, v157
	v_rcp_f32_e32 v247, v251
	v_add_f32_e32 v251, 1.0, v158
	v_add_f32_e32 v158, 1.0, v160
	v_rcp_f32_e32 v28, v127
	v_rcp_f32_e32 v250, v91
	v_add_f32_e32 v91, 1.0, v162
	v_rcp_f32_e32 v126, v148
	v_rcp_f32_e32 v127, v149
	v_add_f32_e32 v157, 1.0, v159
	v_add_f32_e32 v160, 1.0, v161
	v_rcp_f32_e32 v135, v139
	v_rcp_f32_e32 v139, v251
	v_rcp_f32_e32 v141, v158
	v_rcp_f32_e32 v251, v91
	v_add_f32_e32 v91, 1.0, v144
	v_add_f32_e32 v137, 1.0, v145
	v_add_f32_e32 v144, 1.0, v163
	v_add_f32_e32 v145, 1.0, v164
	v_add_f32_e32 v146, 1.0, v165
	v_add_f32_e32 v147, 1.0, v166
	v_add_f32_e32 v148, 1.0, v168
	v_add_f32_e32 v158, 1.0, v169
	v_rcp_f32_e32 v159, v140
	v_rcp_f32_e32 v140, v157
	v_rcp_f32_e32 v157, v160
	v_add_f32_e32 v149, 1.0, v167
	v_add_f32_e32 v160, 1.0, v170
	v_rcp_f32_e32 v136, v91
	v_rcp_f32_e32 v137, v137
	v_rcp_f32_e32 v144, v144
	v_rcp_f32_e32 v145, v145
	v_rcp_f32_e32 v146, v146
	v_rcp_f32_e32 v147, v147
	v_rcp_f32_e32 v240, v148
	v_rcp_f32_e32 v148, v158
	v_add_f32_e32 v91, 1.0, v152
	v_add_f32_e32 v158, 1.0, v153
	v_add_f32_e32 v154, 1.0, v154
	v_add_f32_e32 v155, 1.0, v155
	v_mul_f32_e32 v44, 0x45800000, v181
	v_mul_f32_e32 v197, 0x45800000, v196
	v_add_f32_e32 v161, 1.0, v175
	v_add_f32_e32 v162, 1.0, v171
	v_rcp_f32_e32 v241, v149
	v_rcp_f32_e32 v149, v160
	v_add_f32_e32 v156, 1.0, v156
	v_add_f32_e32 v160, 1.0, v177
	v_pk_mul_f32 v[198:199], v[120:121], v[198:199]
	v_pk_mul_f32 v[76:77], v[122:123], v[76:77]
	v_rcp_f32_e32 v120, v91
	v_rcp_f32_e32 v121, v158
	v_rcp_f32_e32 v122, v154
	v_rcp_f32_e32 v123, v155
	v_cndmask_b32_e64 v44, v181, v44, s[0:1]
	v_cndmask_b32_e32 v196, v196, v197, vcc
	v_add_f32_e32 v163, 1.0, v176
	v_add_f32_e32 v164, 1.0, v172
	v_rcp_f32_e32 v150, v161
	v_rcp_f32_e32 v151, v162
	v_pk_mul_f32 v[78:79], v[126:127], v[78:79]
	v_rcp_f32_e32 v126, v156
	v_rcp_f32_e32 v127, v160
	v_pk_mul_f32 v[220:221], v[242:243], v[44:45] op_sel_hi:[1,0]
	v_pk_mul_f32 v[82:83], v[226:227], v[44:45] op_sel_hi:[1,0]
	v_pk_mul_f32 v[224:225], v[230:231], v[44:45] op_sel_hi:[1,0]
	v_pk_mul_f32 v[226:227], v[228:229], v[44:45] op_sel_hi:[1,0]
	v_pk_mul_f32 v[194:195], v[194:195], v[44:45] op_sel_hi:[1,0]
	v_pk_mul_f32 v[192:193], v[192:193], v[44:45] op_sel_hi:[1,0]
	v_pk_mul_f32 v[190:191], v[190:191], v[44:45] op_sel_hi:[1,0]
	v_mul_f32_e32 v181, v189, v44
	v_mul_f32_e32 v44, v188, v44
	v_mul_f32_e32 v91, v196, v49
	v_mov_b32_e32 v49, v196
	v_rcp_f32_e32 v152, v163
	v_rcp_f32_e32 v153, v164
	v_pk_mul_f32 v[58:59], v[196:197], v[58:59] op_sel_hi:[0,1]
	v_pk_mul_f32 v[182:183], v[196:197], v[182:183] op_sel_hi:[0,1]
	v_pk_mul_f32 v[56:57], v[196:197], v[56:57] op_sel_hi:[0,1]
	v_mul_f32_e32 v44, v3, v44
	v_pk_mul_f32 v[186:187], v[48:49], v[186:187]
	v_pk_mul_f32 v[80:81], v[136:137], v[142:143]
	v_pk_mul_f32 v[234:235], v[144:145], v[234:235]
	v_pk_mul_f32 v[116:117], v[146:147], v[116:117]
	v_pk_mul_f32 v[184:185], v[196:197], v[184:185] op_sel_hi:[0,1]
	v_pk_mul_f32 v[54:55], v[196:197], v[54:55] op_sel_hi:[0,1]
	v_pk_mul_f32 v[52:53], v[196:197], v[52:53] op_sel_hi:[0,1]
	v_pk_mul_f32 v[50:51], v[196:197], v[50:51] op_sel_hi:[0,1]
	v_pk_mul_f32 v[188:189], v[12:13], v[220:221]
	v_pk_mul_f32 v[196:197], v[14:15], v[82:83]
	v_pk_mul_f32 v[220:221], v[8:9], v[224:225]
	v_pk_mul_f32 v[190:191], v[0:1], v[190:191]
	v_pk_mul_f32 v[180:181], v[28:29], v[180:181]
	v_pk_mul_f32 v[58:59], v[30:31], v[58:59]
	v_pk_mul_f32 v[182:183], v[32:33], v[182:183]
	v_pk_mul_f32 v[56:57], v[34:35], v[56:57]
	v_pk_mul_f32 v[186:187], v[44:45], v[186:187]
	v_pk_mul_f32 v[222:223], v[132:133], v[130:131]
	v_pk_mul_f32 v[82:83], v[10:11], v[226:227]
	v_pk_mul_f32 v[194:195], v[4:5], v[194:195]
	v_pk_mul_f32 v[192:193], v[6:7], v[192:193]
	v_pk_mul_f32 v[184:185], v[36:37], v[184:185]
	v_pk_mul_f32 v[54:55], v[38:39], v[54:55]
	v_pk_mul_f32 v[52:53], v[40:41], v[52:53]
	v_pk_mul_f32 v[50:51], v[42:43], v[50:51]
	v_mul_f32_e32 v28, v2, v91
	v_pk_mul_f32 v[48:49], v[116:117], v[188:189]
	v_pk_mul_f32 v[188:189], v[234:235], v[196:197]
	v_pk_mul_f32 v[196:197], v[80:81], v[220:221]
	v_pk_mul_f32 v[190:191], v[198:199], v[190:191]
	v_mul_f32_e32 v198, v180, v181
	v_pk_mul_f32 v[180:181], v[84:85], v[58:59]
	v_pk_mul_f32 v[182:183], v[120:121], v[182:183]
	v_pk_mul_f32 v[56:57], v[122:123], v[56:57]
	v_pk_mul_f32 v[186:187], v[250:251], v[186:187]
	v_pk_mul_f32 v[220:221], v[222:223], v[82:83]
	v_pk_mul_f32 v[194:195], v[78:79], v[194:195]
	v_pk_mul_f32 v[192:193], v[76:77], v[192:193]
	v_pk_mul_f32 v[184:185], v[126:127], v[184:185]
	v_pk_mul_f32 v[54:55], v[134:135], v[54:55]
	v_pk_mul_f32 v[52:53], v[138:139], v[52:53]
	v_pk_mul_f32 v[50:51], v[140:141], v[50:51]
	v_mul_f32_e32 v58, v157, v28
	v_mul_f32_e32 v198, v159, v198
	v_pk_fma_f32 v[180:181], v[240:241], v[48:49], v[180:181]
	v_pk_fma_f32 v[182:183], v[148:149], v[188:189], v[182:183]
	v_pk_fma_f32 v[48:49], v[150:151], v[196:197], v[56:57]
	v_mov_b32_e32 v199, v186
	v_mov_b32_e32 v59, v187
	v_pk_fma_f32 v[184:185], v[152:153], v[220:221], v[184:185]
	v_pk_fma_f32 v[54:55], v[244:245], v[194:195], v[54:55]
	v_pk_fma_f32 v[52:53], v[246:247], v[192:193], v[52:53]
	v_pk_fma_f32 v[50:51], v[248:249], v[190:191], v[50:51]
	v_cvt_pk_bf16_f32 v180, v180, v181
	v_cvt_pk_bf16_f32 v181, v182, v183
	v_cvt_pk_bf16_f32 v182, v48, v49
	v_pk_add_f32 v[48:49], v[198:199], v[58:59]
	v_cvt_pk_bf16_f32 v183, v184, v185
	v_cvt_pk_bf16_f32 v184, v54, v55
	v_cvt_pk_bf16_f32 v185, v52, v53
	v_cvt_pk_bf16_f32 v186, v50, v51
	v_cvt_pk_bf16_f32 v187, v48, v49
	global_store_dwordx4 v[254:255], v[180:183], off offset:-16
	global_store_dwordx4 v[254:255], v[184:187], off
	s_cmp_lg_u64 s[10:11], 0
	s_cbranch_scc1 .Lmp1_finalA
	v_add_co_u32_e32 v48, vcc, 0xf8000000, v26
	v_lshl_add_u64 v[50:51], v[26:27], 0, s[12:13]
	v_lshl_add_u64 v[52:53], v[26:27], 0, s[14:15]
	v_addc_co_u32_e32 v49, vcc, -1, v27, vcc
	global_load_dwordx4 v[184:187], v[26:27], off
	global_load_dwordx4 v[180:183], v[26:27], off offset:-16
	v_lshl_add_u64 v[54:55], v[26:27], 0, s[16:17]
	v_lshl_add_u64 v[56:57], v[26:27], 0, s[18:19]
	global_load_dwordx4 v[188:191], v[52:53], off offset:16
	global_load_dwordx4 v[192:195], v[50:51], off offset:16
	global_load_dwordx4 v[196:199], v[56:57], off offset:16
	global_load_dwordx4 v[220:223], v[54:55], off offset:16
	v_add_co_u32_e32 v50, vcc, 0xfc000000, v26
	v_lshl_add_u64 v[46:47], v[26:27], 0, s[20:21]
	s_nop 0
	v_addc_co_u32_e32 v51, vcc, -1, v27, vcc
	v_add_co_u32_e32 v52, vcc, 0xdfc00000, v26
	global_load_dwordx4 v[224:227], v[48:49], off offset:-16
	global_load_dwordx4 v[228:231], v[46:47], off offset:16
	v_addc_co_u32_e32 v53, vcc, -1, v27, vcc
	v_add_co_u32_e32 v48, vcc, s3, v26
	global_load_dwordx4 v[232:235], v[50:51], off offset:-16
	global_load_dwordx4 v[240:243], v[52:53], off offset:-16
	v_addc_co_u32_e32 v49, vcc, -1, v27, vcc
	v_add_co_u32_e32 v50, vcc, s23, v26
	v_add_u32_e32 v86, s8, v86
	s_nop 0
	v_addc_co_u32_e32 v51, vcc, -1, v27, vcc
	global_load_dwordx4 v[244:247], v[48:49], off offset:-16
	global_load_dwordx4 v[248:251], v[50:51], off offset:-16
	v_add_co_u32_e32 v254, vcc, 0xcbc00000, v26
	v_cmp_lt_i32_e64 s[0:1], s28, v86
	s_nop 0
	v_addc_co_u32_e32 v255, vcc, -1, v27, vcc
	s_or_b64 s[10:11], s[0:1], s[10:11]
	v_lshl_add_u64 v[26:27], v[26:27], 0, s[24:25]
	s_waitcnt vmcnt(25)
	v_lshlrev_b32_e32 v50, 16, v22
	s_waitcnt vmcnt(24)
	v_lshlrev_b32_e32 v58, 16, v16
	v_and_b32_e32 v59, 0xffff0000, v16
	s_waitcnt vmcnt(23)
	v_lshlrev_b32_e32 v83, 16, v63
	s_waitcnt vmcnt(22)
	v_lshlrev_b32_e32 v117, 16, v67
	v_and_b32_e32 v82, 0xffff0000, v63
	v_and_b32_e32 v116, 0xffff0000, v67
	s_waitcnt vmcnt(21)
	v_and_b32_e32 v63, 0xffff0000, v69
	s_waitcnt vmcnt(20)
	v_lshlrev_b32_e32 v16, 16, v75
	v_lshlrev_b32_e32 v85, 16, v71
	v_lshlrev_b32_e32 v118, 16, v66
	v_and_b32_e32 v119, 0xffff0000, v66
	v_lshlrev_b32_e32 v66, 16, v62
	v_and_b32_e32 v67, 0xffff0000, v62
	v_lshlrev_b32_e32 v76, 16, v73
	v_lshlrev_b32_e32 v128, 16, v64
	v_and_b32_e32 v129, 0xffff0000, v64
	v_lshlrev_b32_e32 v130, 16, v60
	v_and_b32_e32 v131, 0xffff0000, v60
	v_lshlrev_b32_e32 v78, 16, v72
	v_and_b32_e32 v79, 0xffff0000, v72
	v_mul_f32_e32 v137, 0xbfb8aa3b, v63
	s_waitcnt vmcnt(18)
	v_lshlrev_b32_e32 v142, 16, v99
	v_mul_f32_e32 v143, 0xbfb8aa3b, v16
	v_mul_f32_e32 v85, 0xbfb8aa3b, v85
	v_and_b32_e32 v144, 0xffff0000, v99
	v_pk_add_f32 v[62:63], v[118:119], v[66:67]
	v_mul_f32_e32 v145, 0xbfb8aa3b, v76
	v_pk_add_f32 v[66:67], v[128:129], v[130:131]
	v_mul_f32_e32 v130, 0xbfb8aa3b, v78
	v_mul_f32_e32 v131, 0xbfb8aa3b, v79
	v_and_b32_e32 v51, 0xffff0000, v22
	v_and_b32_e32 v81, 0xffff0000, v70
	v_and_b32_e32 v22, 0xffff0000, v75
	v_lshlrev_b32_e32 v124, 16, v61
	v_and_b32_e32 v125, 0xffff0000, v61
	v_and_b32_e32 v77, 0xffff0000, v73
	v_pk_add_f32 v[60:61], v[116:117], v[82:83]
	v_lshlrev_b32_e32 v73, 16, v96
	v_and_b32_e32 v75, 0xffff0000, v96
	v_lshlrev_b32_e32 v133, 16, v97
	v_and_b32_e32 v135, 0xffff0000, v97
	v_lshlrev_b32_e32 v139, 16, v98
	v_and_b32_e32 v141, 0xffff0000, v98
	v_lshlrev_b32_e32 v96, 16, v95
	v_and_b32_e32 v97, 0xffff0000, v95
	v_lshlrev_b32_e32 v98, 16, v94
	v_and_b32_e32 v99, 0xffff0000, v94
	v_lshlrev_b32_e32 v116, 16, v92
	v_and_b32_e32 v117, 0xffff0000, v92
	v_exp_f32_e32 v147, v137
	v_exp_f32_e32 v150, v143
	v_exp_f32_e32 v151, v85
	v_mul_f32_e32 v85, 0xbfb8aa3b, v142
	v_mul_f32_e32 v137, 0xbfb8aa3b, v144
	v_exp_f32_e32 v153, v145
	v_exp_f32_e32 v154, v130
	v_exp_f32_e32 v155, v131
	s_waitcnt vmcnt(17)
	v_lshlrev_b32_e32 v130, 16, v103
	v_and_b32_e32 v131, 0xffff0000, v103
	v_lshlrev_b32_e32 v142, 16, v102
	v_and_b32_e32 v143, 0xffff0000, v102
	v_lshlrev_b32_e32 v144, 16, v100
	v_and_b32_e32 v145, 0xffff0000, v100
	v_lshlrev_b32_e32 v52, 16, v21
	v_and_b32_e32 v53, 0xffff0000, v21
	v_mul_f32_e32 v81, 0xbfb8aa3b, v81
	v_lshlrev_b32_e32 v94, 16, v93
	v_and_b32_e32 v95, 0xffff0000, v93
	v_lshlrev_b32_e32 v102, 16, v101
	v_and_b32_e32 v103, 0xffff0000, v101
	v_pk_add_f32 v[96:97], v[96:97], v[130:131]
	s_waitcnt vmcnt(16)
	v_lshlrev_b32_e32 v130, 16, v107
	v_and_b32_e32 v131, 0xffff0000, v107
	v_pk_add_f32 v[98:99], v[98:99], v[142:143]
	v_lshlrev_b32_e32 v142, 16, v106
	v_and_b32_e32 v143, 0xffff0000, v106
	v_pk_add_f32 v[106:107], v[116:117], v[144:145]
	v_pk_mul_f32 v[126:127], v[52:53], v[52:53]
	v_mov_b32_e32 v140, v59
	v_exp_f32_e32 v149, v81
	v_mul_f32_e32 v81, 0xbfb8aa3b, v141
	v_pk_add_f32 v[94:95], v[94:95], v[102:103]
	v_lshlrev_b32_e32 v102, 16, v105
	v_and_b32_e32 v103, 0xffff0000, v105
	v_lshlrev_b32_e32 v116, 16, v104
	v_and_b32_e32 v117, 0xffff0000, v104
	s_waitcnt vmcnt(15)
	v_lshlrev_b32_e32 v104, 16, v108
	v_and_b32_e32 v105, 0xffff0000, v108
	v_mov_b32_e32 v141, v107
	v_lshlrev_b32_e32 v56, 16, v18
	v_and_b32_e32 v57, 0xffff0000, v18
	v_lshlrev_b32_e32 v18, 16, v17
	v_mov_b32_e32 v138, v58
	v_mov_b32_e32 v92, v126
	v_mul_f32_e32 v126, 0xbfb8aa3b, v133
	v_mul_f32_e32 v133, 0xbfb8aa3b, v135
	v_mul_f32_e32 v135, 0xbfb8aa3b, v139
	v_mov_b32_e32 v139, v106
	v_mul_f32_e32 v168, 0xbfb8aa3b, v104
	v_mul_f32_e32 v169, 0xbfb8aa3b, v105
	v_pk_mul_f32 v[104:105], v[140:141], v[140:141]
	v_lshlrev_b32_e32 v54, 16, v20
	v_and_b32_e32 v55, 0xffff0000, v20
	v_lshlrev_b32_e32 v20, 16, v19
	v_and_b32_e32 v21, 0xffff0000, v19
	v_and_b32_e32 v19, 0xffff0000, v17
	v_mov_b32_e32 v134, v18
	v_exp_f32_e32 v159, v135
	v_mov_b32_e32 v135, v94
	v_pk_fma_f32 v[104:105], v[138:139], v[138:139], v[104:105]
	v_mov_b32_e32 v136, v19
	v_exp_f32_e32 v162, v137
	v_mov_b32_e32 v137, v95
	v_pk_fma_f32 v[104:105], v[134:135], v[134:135], v[104:105]
	v_mov_b32_e32 v132, v56
	v_exp_f32_e32 v158, v133
	v_mov_b32_e32 v133, v98
	v_pk_fma_f32 v[104:105], v[136:137], v[136:137], v[104:105]
	v_mov_b32_e32 v84, v57
	v_exp_f32_e32 v161, v85
	v_mov_b32_e32 v85, v99
	v_pk_fma_f32 v[104:105], v[132:133], v[132:133], v[104:105]
	v_mov_b32_e32 v80, v20
	v_mul_f32_e32 v75, 0xbfb8aa3b, v75
	v_exp_f32_e32 v160, v81
	v_mov_b32_e32 v81, v96
	v_pk_fma_f32 v[84:85], v[84:85], v[84:85], v[104:105]
	v_lshlrev_b32_e32 v44, 16, v69
	v_lshlrev_b32_e32 v69, 16, v70
	v_and_b32_e32 v91, 0xffff0000, v71
	v_pk_mul_f32 v[120:121], v[50:51], v[50:51]
	v_lshlrev_b32_e32 v70, 16, v74
	v_and_b32_e32 v71, 0xffff0000, v74
	v_lshlrev_b32_e32 v122, 16, v65
	v_and_b32_e32 v123, 0xffff0000, v65
	v_mov_b32_e32 v74, v21
	v_exp_f32_e32 v157, v75
	v_mov_b32_e32 v75, v97
	v_pk_fma_f32 v[80:81], v[80:81], v[80:81], v[84:85]
	v_mov_b32_e32 v72, v54
	v_mul_f32_e32 v69, 0xbfb8aa3b, v69
	v_pk_add_f32 v[64:65], v[122:123], v[124:125]
	v_mov_b32_e32 v118, v120
	v_mul_f32_e32 v120, 0xbfb8aa3b, v73
	v_mov_b32_e32 v73, v66
	v_pk_fma_f32 v[74:75], v[74:75], v[74:75], v[80:81]
	v_lshlrev_b32_e32 v17, 16, v68
	v_and_b32_e32 v28, 0xffff0000, v68
	v_mov_b32_e32 v68, v55
	v_mul_f32_e32 v93, 0xbfb8aa3b, v22
	v_exp_f32_e32 v148, v69
	v_pk_mul_f32 v[128:129], v[64:65], v[64:65]
	v_mov_b32_e32 v69, v67
	v_pk_fma_f32 v[72:73], v[72:73], v[72:73], v[74:75]
	v_exp_f32_e32 v156, v93
	v_mov_b32_e32 v93, v128
	v_pk_fma_f32 v[68:69], v[68:69], v[68:69], v[72:73]
	v_lshlrev_b32_e32 v49, 16, v23
	v_and_b32_e32 v23, 0xffff0000, v23
	v_mul_f32_e32 v119, 0xbfb8aa3b, v71
	v_pk_mul_f32 v[124:125], v[62:63], v[62:63]
	v_mov_b32_e32 v128, v127
	v_pk_add_f32 v[68:69], v[92:93], v[68:69]
	v_mov_b32_e32 v48, v23
	v_exp_f32_e32 v152, v119
	v_mov_b32_e32 v119, v124
	v_pk_add_f32 v[68:69], v[128:129], v[68:69]
	v_pk_mul_f32 v[82:83], v[48:49], v[48:49]
	v_pk_mul_f32 v[122:123], v[60:61], v[60:61]
	v_mov_b32_e32 v124, v121
	v_pk_add_f32 v[68:69], v[118:119], v[68:69]
	v_mov_b32_e32 v100, v83
	v_mov_b32_e32 v101, v123
	v_pk_add_f32 v[68:69], v[124:125], v[68:69]
	v_mov_b32_e32 v83, v122
	v_pk_add_f32 v[68:69], v[100:101], v[68:69]
	v_mul_f32_e32 v17, 0xbfb8aa3b, v17
	v_pk_add_f32 v[68:69], v[82:83], v[68:69]
	ds_bpermute_b32 v73, v87, v69
	ds_bpermute_b32 v72, v87, v68
	v_mul_f32_e32 v44, 0xbfb8aa3b, v44
	v_mul_f32_e32 v48, 0xbfb8aa3b, v70
	v_exp_f32_e32 v17, v17
	v_exp_f32_e32 v44, v44
	s_waitcnt lgkmcnt(0)
	v_pk_add_f32 v[68:69], v[68:69], v[72:73]
	ds_bpermute_b32 v73, v88, v69
	ds_bpermute_b32 v72, v88, v68
	v_exp_f32_e32 v48, v48
	v_exp_f32_e32 v120, v120
	v_exp_f32_e32 v126, v126
	v_mul_f32_e32 v123, 0xbfb8aa3b, v130
	s_waitcnt lgkmcnt(0)
	v_pk_add_f32 v[68:69], v[68:69], v[72:73]
	ds_bpermute_b32 v73, v89, v69
	ds_bpermute_b32 v72, v89, v68
	v_mul_f32_e32 v127, 0xbfb8aa3b, v131
	s_waitcnt vmcnt(14)
	v_lshlrev_b32_e32 v167, 16, v112
	v_and_b32_e32 v112, 0xffff0000, v112
	v_lshlrev_b32_e32 v108, 16, v109
	s_waitcnt lgkmcnt(0)
	v_pk_add_f32 v[68:69], v[68:69], v[72:73]
	ds_bpermute_b32 v73, v90, v69
	ds_bpermute_b32 v72, v90, v68
	v_and_b32_e32 v109, 0xffff0000, v109
	v_lshlrev_b32_e32 v121, 16, v110
	v_and_b32_e32 v110, 0xffff0000, v110
	v_exp_f32_e32 v173, v123
	v_exp_f32_e32 v174, v127
	v_mul_f32_e32 v123, 0xbfb8aa3b, v167
	v_mul_f32_e32 v112, 0xbfb8aa3b, v112
	v_lshlrev_b32_e32 v122, 16, v111
	v_lshlrev_b32_e32 v170, 16, v113
	v_mul_f32_e32 v108, 0xbfb8aa3b, v108
	v_and_b32_e32 v113, 0xffff0000, v113
	v_mul_f32_e32 v109, 0xbfb8aa3b, v109
	v_lshlrev_b32_e32 v171, 16, v114
	v_and_b32_e32 v114, 0xffff0000, v114
	v_mul_f32_e32 v110, 0xbfb8aa3b, v110
	v_add_f32_e32 v127, 1.0, v150
	v_add_f32_e32 v140, 1.0, v151
	v_exp_f32_e32 v150, v123
	v_exp_f32_e32 v151, v112
	v_mul_f32_e32 v122, 0xbfb8aa3b, v122
	v_exp_f32_e32 v167, v169
	v_exp_f32_e32 v169, v108
	v_mul_f32_e32 v108, 0xbfb8aa3b, v170
	v_exp_f32_e32 v170, v109
	v_mul_f32_e32 v109, 0xbfb8aa3b, v113
	v_mul_f32_e32 v113, 0xbfb8aa3b, v171
	v_exp_f32_e32 v171, v110
	v_mul_f32_e32 v110, 0xbfb8aa3b, v114
	v_add_f32_e32 v17, 1.0, v17
	v_add_f32_e32 v44, 1.0, v44
	v_mul_f32_e32 v146, 0xbfb8aa3b, v77
	v_exp_f32_e32 v176, v122
	v_add_f32_e32 v122, 1.0, v149
	v_add_f32_e32 v48, 1.0, v48
	v_add_f32_e32 v141, 1.0, v152
	v_add_f32_e32 v149, 1.0, v155
	v_add_f32_e32 v138, 1.0, v156
	v_exp_f32_e32 v152, v108
	v_exp_f32_e32 v155, v110
	v_rcp_f32_e32 v108, v17
	v_add_f32_e32 v17, 1.0, v120
	v_rcp_f32_e32 v110, v44
	v_add_f32_e32 v44, 1.0, v126
	v_mul_f32_e32 v28, 0xbfb8aa3b, v28
	v_mul_f32_e32 v91, 0xbfb8aa3b, v91
	v_exp_f32_e32 v146, v146
	v_rcp_f32_e32 v120, v48
	v_rcp_f32_e32 v48, v138
	v_rcp_f32_e32 v134, v17
	v_rcp_f32_e32 v138, v44
	v_add_f32_e32 v17, 1.0, v173
	v_add_f32_e32 v44, 1.0, v174
	s_waitcnt lgkmcnt(0)
	v_pk_add_f32 v[68:69], v[68:69], v[72:73]
	v_exp_f32_e32 v28, v28
	v_exp_f32_e32 v91, v91
	v_rcp_f32_e32 v132, v17
	v_rcp_f32_e32 v133, v44
	v_add_f32_e32 v17, 1.0, v150
	v_add_f32_e32 v44, 1.0, v151
	v_pk_fma_f32 v[68:69], v[68:69], s[22:23], v[24:25] op_sel_hi:[1,0,1]
	v_and_b32_e32 v111, 0xffff0000, v111
	v_mul_f32_e32 v144, 0xbfb8aa3b, v142
	v_mul_f32_e32 v145, 0xbfb8aa3b, v143
	v_mul_f32_e32 v163, 0xbfb8aa3b, v102
	v_mul_f32_e32 v164, 0xbfb8aa3b, v103
	v_mul_f32_e32 v165, 0xbfb8aa3b, v116
	v_mul_f32_e32 v166, 0xbfb8aa3b, v117
	v_rcp_f32_e32 v84, v17
	v_rcp_f32_e32 v85, v44
	v_mul_f32_e32 v17, 0x4b800000, v69
	v_mul_f32_e32 v44, 0x4b800000, v68
	v_cmp_gt_f32_e32 vcc, s27, v68
	v_cmp_gt_f32_e64 s[0:1], s27, v69
	v_mul_f32_e32 v121, 0xbfb8aa3b, v121
	v_lshlrev_b32_e32 v172, 16, v115
	v_and_b32_e32 v115, 0xffff0000, v115
	v_mul_f32_e32 v111, 0xbfb8aa3b, v111
	v_exp_f32_e32 v144, v144
	v_exp_f32_e32 v145, v145
	v_exp_f32_e32 v163, v163
	v_exp_f32_e32 v164, v164
	v_exp_f32_e32 v165, v165
	v_exp_f32_e32 v166, v166
	v_exp_f32_e32 v168, v168
	v_cndmask_b32_e64 v17, v69, v17, s[0:1]
	v_cndmask_b32_e32 v44, v68, v44, vcc
	v_exp_f32_e32 v175, v121
	v_mul_f32_e32 v114, 0xbfb8aa3b, v172
	v_exp_f32_e32 v172, v111
	v_mul_f32_e32 v111, 0xbfb8aa3b, v115
	v_add_f32_e32 v115, 1.0, v147
	v_add_f32_e32 v121, 1.0, v148
	v_add_f32_e32 v147, 1.0, v153
	v_add_f32_e32 v146, 1.0, v146
	v_add_f32_e32 v148, 1.0, v154
	v_exp_f32_e32 v153, v109
	v_exp_f32_e32 v154, v113
	v_rsq_f32_e32 v17, v17
	v_rsq_f32_e32 v68, v44
	v_add_f32_e32 v28, 1.0, v28
	v_add_f32_e32 v91, 1.0, v91
	v_exp_f32_e32 v156, v114
	v_exp_f32_e32 v177, v111
	v_rcp_f32_e32 v112, v121
	v_rcp_f32_e32 v113, v122
	v_rcp_f32_e32 v121, v141
	v_rcp_f32_e32 v122, v147
	v_rcp_f32_e32 v123, v146
	v_rcp_f32_e32 v109, v28
	v_add_f32_e32 v139, 1.0, v157
	v_rcp_f32_e32 v111, v115
	v_add_f32_e32 v115, 1.0, v158
	v_add_f32_e32 v158, 1.0, v160
	v_rcp_f32_e32 v28, v127
	v_rcp_f32_e32 v114, v91
	v_add_f32_e32 v91, 1.0, v162
	v_rcp_f32_e32 v126, v148
	v_rcp_f32_e32 v127, v149
	v_add_f32_e32 v157, 1.0, v159
	v_add_f32_e32 v160, 1.0, v161
	v_rcp_f32_e32 v135, v139
	v_rcp_f32_e32 v139, v115
	v_rcp_f32_e32 v141, v158
	v_rcp_f32_e32 v115, v91
	v_add_f32_e32 v91, 1.0, v144
	v_add_f32_e32 v137, 1.0, v145
	v_add_f32_e32 v144, 1.0, v163
	v_add_f32_e32 v145, 1.0, v164
	v_add_f32_e32 v146, 1.0, v165
	v_add_f32_e32 v147, 1.0, v166
	v_add_f32_e32 v148, 1.0, v168
	v_add_f32_e32 v158, 1.0, v169
	v_rcp_f32_e32 v159, v140
	v_rcp_f32_e32 v140, v157
	v_rcp_f32_e32 v157, v160
	v_add_f32_e32 v149, 1.0, v167
	v_add_f32_e32 v160, 1.0, v170
	v_rcp_f32_e32 v136, v91
	v_rcp_f32_e32 v137, v137
	v_rcp_f32_e32 v144, v144
	v_rcp_f32_e32 v145, v145
	v_rcp_f32_e32 v146, v146
	v_rcp_f32_e32 v147, v147
	v_rcp_f32_e32 v104, v148
	v_rcp_f32_e32 v148, v158
	v_add_f32_e32 v91, 1.0, v152
	v_add_f32_e32 v158, 1.0, v153
	v_add_f32_e32 v154, 1.0, v154
	v_add_f32_e32 v155, 1.0, v155
	v_mul_f32_e32 v44, 0x45800000, v17
	v_mul_f32_e32 v69, 0x45800000, v68
	v_add_f32_e32 v161, 1.0, v175
	v_add_f32_e32 v162, 1.0, v171
	v_rcp_f32_e32 v105, v149
	v_rcp_f32_e32 v149, v160
	v_add_f32_e32 v156, 1.0, v156
	v_add_f32_e32 v160, 1.0, v177
	v_pk_mul_f32 v[70:71], v[120:121], v[70:71]
	v_pk_mul_f32 v[76:77], v[122:123], v[76:77]
	v_rcp_f32_e32 v120, v91
	v_rcp_f32_e32 v121, v158
	v_rcp_f32_e32 v122, v154
	v_rcp_f32_e32 v123, v155
	v_cndmask_b32_e64 v44, v17, v44, s[0:1]
	v_cndmask_b32_e32 v68, v68, v69, vcc
	v_add_f32_e32 v163, 1.0, v176
	v_add_f32_e32 v164, 1.0, v172
	v_rcp_f32_e32 v150, v161
	v_rcp_f32_e32 v151, v162
	v_pk_mul_f32 v[78:79], v[126:127], v[78:79]
	v_rcp_f32_e32 v126, v156
	v_rcp_f32_e32 v127, v160
	v_pk_mul_f32 v[72:73], v[106:107], v[44:45] op_sel_hi:[1,0]
	v_pk_mul_f32 v[82:83], v[94:95], v[44:45] op_sel_hi:[1,0]
	v_pk_mul_f32 v[92:93], v[98:99], v[44:45] op_sel_hi:[1,0]
	v_pk_mul_f32 v[94:95], v[96:97], v[44:45] op_sel_hi:[1,0]
	v_pk_mul_f32 v[66:67], v[66:67], v[44:45] op_sel_hi:[1,0]
	v_pk_mul_f32 v[64:65], v[64:65], v[44:45] op_sel_hi:[1,0]
	v_pk_mul_f32 v[62:63], v[62:63], v[44:45] op_sel_hi:[1,0]
	v_mul_f32_e32 v17, v61, v44
	v_mul_f32_e32 v44, v60, v44
	v_mul_f32_e32 v91, v68, v49
	v_mov_b32_e32 v49, v68
	v_rcp_f32_e32 v152, v163
	v_rcp_f32_e32 v153, v164
	v_pk_mul_f32 v[58:59], v[68:69], v[58:59] op_sel_hi:[0,1]
	v_pk_mul_f32 v[18:19], v[68:69], v[18:19] op_sel_hi:[0,1]
	v_pk_mul_f32 v[56:57], v[68:69], v[56:57] op_sel_hi:[0,1]
	v_mul_f32_e32 v44, v3, v44
	v_pk_mul_f32 v[22:23], v[48:49], v[22:23]
	v_pk_mul_f32 v[80:81], v[136:137], v[142:143]
	v_pk_mul_f32 v[102:103], v[144:145], v[102:103]
	v_pk_mul_f32 v[116:117], v[146:147], v[116:117]
	v_pk_mul_f32 v[20:21], v[68:69], v[20:21] op_sel_hi:[0,1]
	v_pk_mul_f32 v[54:55], v[68:69], v[54:55] op_sel_hi:[0,1]
	v_pk_mul_f32 v[52:53], v[68:69], v[52:53] op_sel_hi:[0,1]
	v_pk_mul_f32 v[50:51], v[68:69], v[50:51] op_sel_hi:[0,1]
	v_pk_mul_f32 v[60:61], v[12:13], v[72:73]
	v_pk_mul_f32 v[68:69], v[14:15], v[82:83]
	v_pk_mul_f32 v[72:73], v[8:9], v[92:93]
	v_pk_mul_f32 v[62:63], v[0:1], v[62:63]
	v_pk_mul_f32 v[16:17], v[28:29], v[16:17]
	v_pk_mul_f32 v[58:59], v[30:31], v[58:59]
	v_pk_mul_f32 v[18:19], v[32:33], v[18:19]
	v_pk_mul_f32 v[56:57], v[34:35], v[56:57]
	v_pk_mul_f32 v[22:23], v[44:45], v[22:23]
	v_pk_mul_f32 v[74:75], v[132:133], v[130:131]
	v_pk_mul_f32 v[82:83], v[10:11], v[94:95]
	v_pk_mul_f32 v[66:67], v[4:5], v[66:67]
	v_pk_mul_f32 v[64:65], v[6:7], v[64:65]
	v_pk_mul_f32 v[20:21], v[36:37], v[20:21]
	v_pk_mul_f32 v[54:55], v[38:39], v[54:55]
	v_pk_mul_f32 v[52:53], v[40:41], v[52:53]
	v_pk_mul_f32 v[50:51], v[42:43], v[50:51]
	v_mul_f32_e32 v28, v2, v91
	v_pk_mul_f32 v[48:49], v[116:117], v[60:61]
	v_pk_mul_f32 v[60:61], v[102:103], v[68:69]
	v_pk_mul_f32 v[68:69], v[80:81], v[72:73]
	v_pk_mul_f32 v[62:63], v[70:71], v[62:63]
	v_mul_f32_e32 v70, v16, v17
	v_pk_mul_f32 v[16:17], v[84:85], v[58:59]
	v_pk_mul_f32 v[18:19], v[120:121], v[18:19]
	v_pk_mul_f32 v[56:57], v[122:123], v[56:57]
	v_pk_mul_f32 v[22:23], v[114:115], v[22:23]
	v_pk_mul_f32 v[72:73], v[74:75], v[82:83]
	v_pk_mul_f32 v[66:67], v[78:79], v[66:67]
	v_pk_mul_f32 v[64:65], v[76:77], v[64:65]
	v_pk_mul_f32 v[20:21], v[126:127], v[20:21]
	v_pk_mul_f32 v[54:55], v[134:135], v[54:55]
	v_pk_mul_f32 v[52:53], v[138:139], v[52:53]
	v_pk_mul_f32 v[50:51], v[140:141], v[50:51]
	v_mul_f32_e32 v58, v157, v28
	v_mul_f32_e32 v70, v159, v70
	v_pk_fma_f32 v[16:17], v[104:105], v[48:49], v[16:17]
	v_pk_fma_f32 v[18:19], v[148:149], v[60:61], v[18:19]
	v_pk_fma_f32 v[48:49], v[150:151], v[68:69], v[56:57]
	v_mov_b32_e32 v71, v22
	v_mov_b32_e32 v59, v23
	v_pk_fma_f32 v[20:21], v[152:153], v[72:73], v[20:21]
	v_pk_fma_f32 v[54:55], v[108:109], v[66:67], v[54:55]
	v_pk_fma_f32 v[52:53], v[110:111], v[64:65], v[52:53]
	v_pk_fma_f32 v[50:51], v[112:113], v[62:63], v[50:51]
	v_cvt_pk_bf16_f32 v16, v16, v17
	v_cvt_pk_bf16_f32 v17, v18, v19
	v_cvt_pk_bf16_f32 v18, v48, v49
	v_pk_add_f32 v[48:49], v[70:71], v[58:59]
	v_cvt_pk_bf16_f32 v19, v20, v21
	v_cvt_pk_bf16_f32 v20, v54, v55
	v_cvt_pk_bf16_f32 v21, v52, v53
	v_cvt_pk_bf16_f32 v22, v50, v51
	v_cvt_pk_bf16_f32 v23, v48, v49
	global_store_dwordx4 v[252:253], v[16:19], off offset:-16
	global_store_dwordx4 v[252:253], v[20:23], off
	s_branch .Lmp1_loop

	.amdhsa_kernel _Z10hybrid_fwd5KArgs
		.amdhsa_group_segment_fixed_size 0
		.amdhsa_private_segment_fixed_size 0
		.amdhsa_kernarg_size 408
		.amdhsa_user_sgpr_count 2
		.amdhsa_user_sgpr_dispatch_ptr 0
		.amdhsa_user_sgpr_queue_ptr 0
		.amdhsa_user_sgpr_kernarg_segment_ptr 1
		.amdhsa_user_sgpr_dispatch_id 0
		.amdhsa_user_sgpr_kernarg_preload_length 0
		.amdhsa_user_sgpr_kernarg_preload_offset 0
		.amdhsa_user_sgpr_private_segment_size 0
		.amdhsa_uses_dynamic_stack 0
		.amdhsa_enable_private_segment 0
		.amdhsa_system_sgpr_workgroup_id_x 1
		.amdhsa_system_sgpr_workgroup_id_y 0
		.amdhsa_system_sgpr_workgroup_id_z 0
		.amdhsa_system_sgpr_workgroup_info 0
		.amdhsa_system_vgpr_workitem_id 2
		.amdhsa_next_free_vgpr 256
		.amdhsa_next_free_sgpr 98
		.amdhsa_accum_offset 256
		.amdhsa_reserve_vcc 1
		.amdhsa_float_round_mode_32 0
		.amdhsa_float_round_mode_16_64 0
		.amdhsa_float_denorm_mode_32 3
		.amdhsa_float_denorm_mode_16_64 3
		.amdhsa_dx10_clamp 1
		.amdhsa_ieee_mode 1
		.amdhsa_fp16_overflow 0
		.amdhsa_tg_split 0
		.amdhsa_exception_fp_ieee_invalid_op 0
		.amdhsa_exception_fp_denorm_src 0
		.amdhsa_exception_fp_ieee_div_zero 0
		.amdhsa_exception_fp_ieee_overflow 0
		.amdhsa_exception_fp_ieee_underflow 0
		.amdhsa_exception_fp_ieee_inexact 0
		.amdhsa_exception_int_div_zero 0
	.end_amdhsa_kernel

amdhsa.kernels:
  - .agpr_count:     0
    .args:
      - .offset:         0
        .size:           152
        .value_kind:     by_value
      - .offset:         152
        .size:           4
        .value_kind:     hidden_block_count_x
      - .offset:         156
        .size:           4
        .value_kind:     hidden_block_count_y
      - .offset:         160
        .size:           4
        .value_kind:     hidden_block_count_z
      - .offset:         164
        .size:           2
        .value_kind:     hidden_group_size_x
      - .offset:         166
        .size:           2
        .value_kind:     hidden_group_size_y
      - .offset:         168
        .size:           2
        .value_kind:     hidden_group_size_z
      - .offset:         170
        .size:           2
        .value_kind:     hidden_remainder_x
      - .offset:         172
        .size:           2
        .value_kind:     hidden_remainder_y
      - .offset:         174
        .size:           2
        .value_kind:     hidden_remainder_z
      - .offset:         192
        .size:           8
        .value_kind:     hidden_global_offset_x
      - .offset:         200
        .size:           8
        .value_kind:     hidden_global_offset_y
      - .offset:         208
        .size:           8
        .value_kind:     hidden_global_offset_z
      - .offset:         216
        .size:           2
        .value_kind:     hidden_grid_dims
      - .offset:         240
        .size:           8
        .value_kind:     hidden_multigrid_sync_arg
      - .offset:         272
        .size:           4
        .value_kind:     hidden_dynamic_lds_size
    .group_segment_fixed_size: 0
    .kernarg_segment_align: 8
    .kernarg_segment_size: 408
    .language:       OpenCL C
    .language_version:
      - 2
      - 0
    .max_flat_workgroup_size: 512
    .name:           _Z10hybrid_fwd5KArgs
    .private_segment_fixed_size: 0
    .sgpr_count:     104
    .sgpr_spill_count: 49
    .symbol:         _Z10hybrid_fwd5KArgs.kd
    .uniform_work_group_size: 1
    .uses_dynamic_stack: false
    .vgpr_count:     256
    .vgpr_spill_count: 0
    .wavefront_size: 64
